# combined: next A half-tile staged before epilogue stores, MIX ticket polls consumed after the unit, unit-start store waits removed, 64-bit accumulator clears
# speedup vs baseline: 1.0035x; 1.0035x over previous
; #define PG8_STAGE(bufoff, gbase, voff) do { _Pragma("unroll") for (int _i = 0; _i < 2; ++_i) \
;         __builtin_amdgcn_global_load_lds((const unsigned*)((const char*)(gbase) + (voff)[_i]), (PG8_LAS unsigned*)(lds + (bufoff) + ldsw + _i * 8192), 16, 0, 0); } while (0)
; #define PG8_LDA(dst, b, h) do { _Pragma("unroll") for (int m = 0; m < 4; ++m) _Pragma("unroll") for (int k = 0; k < 2; ++k) dst[m][k] = *(const PG8_LAS bf16x8*)(lds + PG8_SA(b, h) + aoff + m * 2048 + k * 1024); } while (0)
; #define PG8_LDB(dst, b, h) do { _Pragma("unroll") for (int n = 0; n < 2; ++n) _Pragma("unroll") for (int k = 0; k < 2; ++k) dst[n][k] = *(const PG8_LAS bf16x8*)(lds + PG8_SB(b, h) + boff + n * 2048 + k * 1024); } while (0)
; #define PG8_MMA(ai, bj, At, Bt) do { __builtin_amdgcn_s_setprio(1); _Pragma("unroll") for (int m = 0; m < 4; ++m) _Pragma("unroll") for (int n = 0; n < 2; ++n) _Pragma("unroll") for (int k = 0; k < 2; ++k) \
;         acc[ai][bj][m][n] = __builtin_amdgcn_mfma_f32_16x16x32_bf16(Bt[n][k], At[m][k], acc[ai][bj][m][n], 0, 0, 0); __builtin_amdgcn_s_setprio(0); } while (0)
; #define PG8_WAIT_V(n) asm volatile("s_waitcnt vmcnt(" #n ")" ::: "memory")
; #define PG8_WAIT_VN(n) asm volatile("s_waitcnt vmcnt(%0)" :: "n"(n) : "memory")
; #define PG8_WAIT_L(n) asm volatile("s_waitcnt lgkmcnt(" #n ")" ::: "memory")
; #define PG8_BAR __builtin_amdgcn_s_barrier()
; #define PG8_SCHED __builtin_amdgcn_sched_barrier(0)
; template <class Epi, class Sched, bool ALIGN_EPI = false, bool SP2 = false>
; __device__ __forceinline__ void gemm_phase(PG8_LAS unsigned char* lds, const Gemm g, const Sched& S, const Epi& E, const int wave_id) {
;     ...
;             PG8_WAIT_VN(8 + Epi::NS); if (strict) PG8_WAIT_V(8); PG8_WAIT_L(0); PG8_BAR; PG8_MMA(1, 0, At, B0); PG8_MMA(1, 1, At, B1); PG8_BAR; PG8_SCHED;
;             PG8_LDB(B0, 1, 0); PG8_LDB(B1, 1, 1); PG8_SCHED; PG8_LDA(At, 1, 0); PG8_STAGE(PG8_SA(0, 1), a2 + hstep, voffA);
;             PG8_WAIT_V(8); PG8_WAIT_L(0); PG8_BAR; PG8_MMA(0, 0, At, B0); PG8_MMA(0, 1, At, B1); PG8_BAR; PG8_SCHED;
.LBB0_157:
	s_waitcnt lgkmcnt(0)
	s_barrier
	s_setprio 1
	s_waitcnt lgkmcnt(0)
	v_mfma_f32_16x16x32_bf16 v[62:65], v[146:149], v[186:189], v[62:65]
	v_mfma_f32_16x16x32_bf16 v[58:61], v[154:157], v[186:189], v[58:61]
	v_mfma_f32_16x16x32_bf16 v[54:57], v[146:149], v[178:181], v[54:57]
	v_mfma_f32_16x16x32_bf16 v[50:53], v[154:157], v[178:181], v[50:53]
	v_mfma_f32_16x16x32_bf16 v[30:33], v[146:149], v[170:173], v[30:33]
	v_mfma_f32_16x16x32_bf16 v[26:29], v[154:157], v[170:173], v[26:29]
	v_mfma_f32_16x16x32_bf16 v[22:25], v[146:149], v[162:165], v[22:25]
	v_mfma_f32_16x16x32_bf16 v[18:21], v[154:157], v[162:165], v[18:21]
	v_mfma_f32_16x16x32_bf16 v[62:65], v[150:153], v[190:193], v[62:65]
	v_mfma_f32_16x16x32_bf16 v[58:61], v[158:161], v[190:193], v[58:61]
	v_mfma_f32_16x16x32_bf16 v[54:57], v[150:153], v[182:185], v[54:57]
	v_mfma_f32_16x16x32_bf16 v[50:53], v[158:161], v[182:185], v[50:53]
	v_mfma_f32_16x16x32_bf16 v[30:33], v[150:153], v[174:177], v[30:33]
	v_mfma_f32_16x16x32_bf16 v[26:29], v[158:161], v[174:177], v[26:29]
	v_mfma_f32_16x16x32_bf16 v[22:25], v[150:153], v[166:169], v[22:25]
	v_mfma_f32_16x16x32_bf16 v[18:21], v[158:161], v[166:169], v[18:21]
	s_setprio 0
	s_setprio 1
	v_mfma_f32_16x16x32_bf16 v[46:49], v[130:133], v[186:189], v[46:49]
	v_mfma_f32_16x16x32_bf16 v[42:45], v[138:141], v[186:189], v[42:45]
	v_mfma_f32_16x16x32_bf16 v[38:41], v[130:133], v[178:181], v[38:41]
	v_mfma_f32_16x16x32_bf16 v[34:37], v[138:141], v[178:181], v[34:37]
	v_mfma_f32_16x16x32_bf16 v[14:17], v[130:133], v[170:173], v[14:17]
	v_mfma_f32_16x16x32_bf16 v[10:13], v[138:141], v[170:173], v[10:13]
	v_mfma_f32_16x16x32_bf16 v[6:9], v[130:133], v[162:165], v[6:9]
	v_mfma_f32_16x16x32_bf16 v[2:5], v[138:141], v[162:165], v[2:5]
	v_mfma_f32_16x16x32_bf16 v[46:49], v[134:137], v[190:193], v[46:49]
	v_mfma_f32_16x16x32_bf16 v[42:45], v[142:145], v[190:193], v[42:45]
	v_mfma_f32_16x16x32_bf16 v[38:41], v[134:137], v[182:185], v[38:41]
	v_mfma_f32_16x16x32_bf16 v[34:37], v[142:145], v[182:185], v[34:37]
	v_mfma_f32_16x16x32_bf16 v[14:17], v[134:137], v[174:177], v[14:17]
	v_mfma_f32_16x16x32_bf16 v[10:13], v[142:145], v[174:177], v[10:13]
	v_mfma_f32_16x16x32_bf16 v[6:9], v[134:137], v[166:169], v[6:9]
	v_mfma_f32_16x16x32_bf16 v[2:5], v[142:145], v[166:169], v[2:5]
	s_setprio 0
	s_barrier
	s_add_i32 s28, 0, 0x18000
	s_add_i32 s29, 0, 0x1c000
	v_add_u32_e32 v142, s28, v246
	v_add_u32_e32 v158, s29, v246
	ds_read_b128 v[130:133], v142
	ds_read_b128 v[134:137], v142 offset:1024
	ds_read_b128 v[138:141], v142 offset:2048
	ds_read_b128 v[142:145], v142 offset:3072
	ds_read_b128 v[146:149], v158
	ds_read_b128 v[150:153], v158 offset:1024
	ds_read_b128 v[154:157], v158 offset:2048
	ds_read_b128 v[158:161], v158 offset:3072
	s_add_u32 s26, s26, 0x40000
	s_addc_u32 s27, s27, 0
	s_mov_b32 m0, s52
	v_lshl_add_u64 v[194:195], s[26:27], 0, v[210:211]
	ds_read_b128 v[162:165], v249 offset:32768
	ds_read_b128 v[166:169], v249 offset:33792
	ds_read_b128 v[170:173], v249 offset:34816
	ds_read_b128 v[174:177], v249 offset:35840
	ds_read_b128 v[178:181], v249 offset:36864
	ds_read_b128 v[182:185], v249 offset:37888
	ds_read_b128 v[186:189], v249 offset:38912
	ds_read_b128 v[190:193], v249 offset:39936
	global_load_lds_dwordx4 v[194:195], off
	v_lshl_add_u64 v[194:195], s[26:27], 0, v[214:215]
	s_mov_b32 m0, s54
	s_nop 0
	global_load_lds_dwordx4 v[194:195], off
	s_waitcnt vmcnt(18)
	s_cmp_eq_u32 s100, 0
	s_cbranch_scc1 .Lthird_wait_relaxed_6
	s_waitcnt vmcnt(8)
.Lthird_wait_relaxed_6:
	s_waitcnt lgkmcnt(0)
	s_barrier
	s_setprio 1
	s_waitcnt lgkmcnt(0)
	v_mfma_f32_16x16x32_bf16 v[126:129], v[130:133], v[162:165], v[126:129]
	v_mfma_f32_16x16x32_bf16 v[122:125], v[138:141], v[162:165], v[122:125]
	v_mfma_f32_16x16x32_bf16 v[118:121], v[130:133], v[170:173], v[118:121]
	v_mfma_f32_16x16x32_bf16 v[114:117], v[138:141], v[170:173], v[114:117]
	v_mfma_f32_16x16x32_bf16 v[94:97], v[130:133], v[178:181], v[94:97]
	v_mfma_f32_16x16x32_bf16 v[90:93], v[138:141], v[178:181], v[90:93]
	v_mfma_f32_16x16x32_bf16 v[86:89], v[130:133], v[186:189], v[86:89]
	v_mfma_f32_16x16x32_bf16 v[82:85], v[138:141], v[186:189], v[82:85]
	v_mfma_f32_16x16x32_bf16 v[126:129], v[134:137], v[166:169], v[126:129]
	v_mfma_f32_16x16x32_bf16 v[122:125], v[142:145], v[166:169], v[122:125]
	v_mfma_f32_16x16x32_bf16 v[118:121], v[134:137], v[174:177], v[118:121]
	v_mfma_f32_16x16x32_bf16 v[114:117], v[142:145], v[174:177], v[114:117]
	v_mfma_f32_16x16x32_bf16 v[94:97], v[134:137], v[182:185], v[94:97]
	v_mfma_f32_16x16x32_bf16 v[90:93], v[142:145], v[182:185], v[90:93]
	v_mfma_f32_16x16x32_bf16 v[86:89], v[134:137], v[190:193], v[86:89]
	v_mfma_f32_16x16x32_bf16 v[82:85], v[142:145], v[190:193], v[82:85]
	s_setprio 0
	s_setprio 1
	v_mfma_f32_16x16x32_bf16 v[110:113], v[146:149], v[162:165], v[110:113]
	v_mfma_f32_16x16x32_bf16 v[106:109], v[154:157], v[162:165], v[106:109]
	v_mfma_f32_16x16x32_bf16 v[102:105], v[146:149], v[170:173], v[102:105]
	v_mfma_f32_16x16x32_bf16 v[98:101], v[154:157], v[170:173], v[98:101]
	v_mfma_f32_16x16x32_bf16 v[78:81], v[146:149], v[178:181], v[78:81]
	v_mfma_f32_16x16x32_bf16 v[74:77], v[154:157], v[178:181], v[74:77]
	v_mfma_f32_16x16x32_bf16 v[70:73], v[146:149], v[186:189], v[70:73]
	v_mfma_f32_16x16x32_bf16 v[66:69], v[154:157], v[186:189], v[66:69]
	v_mfma_f32_16x16x32_bf16 v[110:113], v[150:153], v[166:169], v[110:113]
	v_mfma_f32_16x16x32_bf16 v[106:109], v[158:161], v[166:169], v[106:109]
	v_mfma_f32_16x16x32_bf16 v[102:105], v[150:153], v[174:177], v[102:105]
	v_mfma_f32_16x16x32_bf16 v[98:101], v[158:161], v[174:177], v[98:101]
	v_mfma_f32_16x16x32_bf16 v[78:81], v[150:153], v[182:185], v[78:81]
	v_mfma_f32_16x16x32_bf16 v[74:77], v[158:161], v[182:185], v[74:77]
	v_mfma_f32_16x16x32_bf16 v[70:73], v[150:153], v[190:193], v[70:73]
	v_mfma_f32_16x16x32_bf16 v[66:69], v[158:161], v[190:193], v[66:69]
	s_setprio 0
	s_barrier
; #define PG8_STAGE(bufoff, gbase, voff) do { _Pragma("unroll") for (int _i = 0; _i < 2; ++_i) \
;         __builtin_amdgcn_global_load_lds((const unsigned*)((const char*)(gbase) + (voff)[_i]), (PG8_LAS unsigned*)(lds + (bufoff) + ldsw + _i * 8192), 16, 0, 0); } while (0)
; #define PG8_LDA(dst, b, h) do { _Pragma("unroll") for (int m = 0; m < 4; ++m) _Pragma("unroll") for (int k = 0; k < 2; ++k) dst[m][k] = *(const PG8_LAS bf16x8*)(lds + PG8_SA(b, h) + aoff + m * 2048 + k * 1024); } while (0)
; #define PG8_LDB(dst, b, h) do { _Pragma("unroll") for (int n = 0; n < 2; ++n) _Pragma("unroll") for (int k = 0; k < 2; ++k) dst[n][k] = *(const PG8_LAS bf16x8*)(lds + PG8_SB(b, h) + boff + n * 2048 + k * 1024); } while (0)
; #define PG8_WAIT_V(n) asm volatile("s_waitcnt vmcnt(" #n ")" ::: "memory")
; #define PG8_WAIT_VN(n) asm volatile("s_waitcnt vmcnt(%0)" :: "n"(n) : "memory")
; template <class Epi, class Sched, bool ALIGN_EPI = false, bool SP2 = false>
; __device__ __forceinline__ void gemm_phase(PG8_LAS unsigned char* lds, const Gemm g, const Sched& S, const Epi& E, const int wave_id) {
;     ...
;             int tz_ = __builtin_amdgcn_readfirstlane(t | (ui > 0 ? 0 : 1)); asm volatile("" : "+s"(tz_));
;             const bool strict = !(Epi::NS > 0 && tz_ == 0);
;             PG8_LDB(B0, 0, 0); PG8_LDB(B1, 0, 1); PG8_SCHED; PG8_LDA(At, 0, 0); PG8_STAGE(PG8_SA(1, 1), a1 + hstep, voffA);
;             PG8_WAIT_VN(8 + Epi::NS); if (strict) PG8_WAIT_V(8); PG8_WAIT_L(0); PG8_BAR; PG8_MMA(0, 0, At, B0); PG8_MMA(0, 1, At, B1); PG8_BAR; PG8_SCHED;
;             PG8_LDA(At, 0, 1); PG8_STAGE(PG8_SB(0, 0), b2, voffB); PG8_STAGE(PG8_SB(0, 1), b2 + hstep, voffB); PG8_STAGE(PG8_SA(0, 0), a2, voffA);
;             PG8_WAIT_VN(8 + Epi::NS); if (strict) PG8_WAIT_V(8); PG8_WAIT_L(0); PG8_BAR; PG8_MMA(1, 0, At, B0); PG8_MMA(1, 1, At, B1); PG8_BAR; PG8_SCHED;
;             PG8_LDB(B0, 1, 0); PG8_LDB(B1, 1, 1); PG8_SCHED; PG8_LDA(At, 1, 0); PG8_STAGE(PG8_SA(0, 1), a2 + hstep, voffA);
;             PG8_WAIT_V(8); PG8_WAIT_L(0); PG8_BAR; PG8_MMA(0, 0, At, B0); PG8_MMA(0, 1, At, B1); PG8_BAR; PG8_SCHED;
;             PG8_LDA(At, 1, 1); PG8_STAGE(PG8_SB(1, 0), b3, voffB); PG8_STAGE(PG8_SB(1, 1), b3 + hstep, voffB); PG8_STAGE(PG8_SA(1, 0), a3, voffA);
;             PG8_WAIT_V(8); PG8_WAIT_L(0); PG8_BAR; PG8_MMA(1, 0, At, B0); PG8_MMA(1, 1, At, B1); PG8_BAR; PG8_SCHED;
	s_add_i32 s26, s28, s40
	v_lshl_add_u64 v[194:195], v[232:233], 0, s[64:65]
	s_mov_b32 m0, s26
	ds_read_b128 v[162:165], v249 offset:49152
	ds_read_b128 v[166:169], v249 offset:50176
	ds_read_b128 v[170:173], v249 offset:51200
	ds_read_b128 v[174:177], v249 offset:52224
	ds_read_b128 v[178:181], v249 offset:53248
	ds_read_b128 v[182:185], v249 offset:54272
	ds_read_b128 v[186:189], v249 offset:55296
	ds_read_b128 v[190:193], v249 offset:56320
	global_load_lds_dwordx4 v[194:195], off
	s_add_i32 m0, s26, 0x2000
	s_add_u32 s24, s24, 0x40080
	v_lshl_add_u64 v[194:195], v[230:231], 0, s[64:65]
	s_addc_u32 s25, s25, 0
	s_add_i32 s26, s29, s40
	global_load_lds_dwordx4 v[194:195], off
	v_lshl_add_u64 v[194:195], s[24:25], 0, v[212:213]
	s_mov_b32 m0, s26
	s_nop 0
	global_load_lds_dwordx4 v[194:195], off
	v_lshl_add_u64 v[194:195], s[24:25], 0, v[216:217]
	s_add_i32 m0, s26, 0x2000
	s_nop 0
	global_load_lds_dwordx4 v[194:195], off
	v_lshl_add_u64 v[194:195], v[226:227], 0, s[64:65]
	s_mov_b32 m0, s57
	s_nop 0
	global_load_lds_dwordx4 v[194:195], off
	v_lshl_add_u64 v[194:195], v[228:229], 0, s[64:65]
	s_mov_b32 m0, s62
	s_nop 0
	global_load_lds_dwordx4 v[194:195], off
	s_waitcnt vmcnt(8)
	s_waitcnt lgkmcnt(0)
	s_barrier
	s_setprio 1
	s_waitcnt lgkmcnt(0)
	v_mfma_f32_16x16x32_bf16 v[62:65], v[130:133], v[162:165], v[62:65]
	v_mfma_f32_16x16x32_bf16 v[58:61], v[138:141], v[162:165], v[58:61]
	v_mfma_f32_16x16x32_bf16 v[54:57], v[130:133], v[170:173], v[54:57]
	v_mfma_f32_16x16x32_bf16 v[50:53], v[138:141], v[170:173], v[50:53]
	v_mfma_f32_16x16x32_bf16 v[30:33], v[130:133], v[178:181], v[30:33]
	v_mfma_f32_16x16x32_bf16 v[26:29], v[138:141], v[178:181], v[26:29]
	v_mfma_f32_16x16x32_bf16 v[22:25], v[130:133], v[186:189], v[22:25]
	v_mfma_f32_16x16x32_bf16 v[18:21], v[138:141], v[186:189], v[18:21]
	v_mfma_f32_16x16x32_bf16 v[62:65], v[134:137], v[166:169], v[62:65]
	v_mfma_f32_16x16x32_bf16 v[58:61], v[142:145], v[166:169], v[58:61]
	v_mfma_f32_16x16x32_bf16 v[54:57], v[134:137], v[174:177], v[54:57]
	v_mfma_f32_16x16x32_bf16 v[50:53], v[142:145], v[174:177], v[50:53]
	v_mfma_f32_16x16x32_bf16 v[30:33], v[134:137], v[182:185], v[30:33]
	v_mfma_f32_16x16x32_bf16 v[26:29], v[142:145], v[182:185], v[26:29]
	v_mfma_f32_16x16x32_bf16 v[22:25], v[134:137], v[190:193], v[22:25]
	v_mfma_f32_16x16x32_bf16 v[18:21], v[142:145], v[190:193], v[18:21]
	s_setprio 0
	s_setprio 1
	v_mfma_f32_16x16x32_bf16 v[46:49], v[146:149], v[162:165], v[46:49]
	v_mfma_f32_16x16x32_bf16 v[42:45], v[154:157], v[162:165], v[42:45]
	v_mfma_f32_16x16x32_bf16 v[38:41], v[146:149], v[170:173], v[38:41]
	v_mfma_f32_16x16x32_bf16 v[34:37], v[154:157], v[170:173], v[34:37]
	v_mfma_f32_16x16x32_bf16 v[14:17], v[146:149], v[178:181], v[14:17]
	v_mfma_f32_16x16x32_bf16 v[10:13], v[154:157], v[178:181], v[10:13]
	v_mfma_f32_16x16x32_bf16 v[6:9], v[146:149], v[186:189], v[6:9]
	v_mfma_f32_16x16x32_bf16 v[2:5], v[154:157], v[186:189], v[2:5]
	v_mfma_f32_16x16x32_bf16 v[46:49], v[150:153], v[166:169], v[46:49]
	v_mfma_f32_16x16x32_bf16 v[42:45], v[158:161], v[166:169], v[42:45]
	v_mfma_f32_16x16x32_bf16 v[38:41], v[150:153], v[174:177], v[38:41]
	v_mfma_f32_16x16x32_bf16 v[34:37], v[158:161], v[174:177], v[34:37]
	v_mfma_f32_16x16x32_bf16 v[14:17], v[150:153], v[182:185], v[14:17]
	v_mfma_f32_16x16x32_bf16 v[10:13], v[158:161], v[182:185], v[10:13]
	v_mfma_f32_16x16x32_bf16 v[6:9], v[150:153], v[190:193], v[6:9]
	v_mfma_f32_16x16x32_bf16 v[2:5], v[158:161], v[190:193], v[2:5]
	s_setprio 0
	s_barrier
	s_add_i32 s76, s76, 2
	s_add_u32 s22, s22, 0x100
	s_addc_u32 s23, s23, 0
	s_cmp_gt_u32 s76, 13
	s_cbranch_scc1 .LBB0_162
.LBB0_158:
	v_add_u32_e32 v130, s76, v250
	v_add_u32_e32 v130, 2, v130
	s_nop 0
	v_readfirstlane_b32 s24, v130
	s_nop 0
	s_mov_b32 s100, s24
	ds_read_b128 v[146:149], v247
	ds_read_b128 v[150:153], v247 offset:1024
	ds_read_b128 v[154:157], v247 offset:2048
	ds_read_b128 v[158:161], v247 offset:3072
	ds_read_b128 v[130:133], v248
	ds_read_b128 v[134:137], v248 offset:1024
	ds_read_b128 v[138:141], v248 offset:2048
	ds_read_b128 v[142:145], v248 offset:3072
	v_lshl_add_u64 v[194:195], v[224:225], 0, s[22:23]
	s_add_i32 m0, s41, 0xc000
	ds_read_b128 v[186:189], v249
	ds_read_b128 v[190:193], v249 offset:1024
	ds_read_b128 v[178:181], v249 offset:2048
	ds_read_b128 v[182:185], v249 offset:3072
	ds_read_b128 v[170:173], v249 offset:4096
	ds_read_b128 v[174:177], v249 offset:5120
	ds_read_b128 v[162:165], v249 offset:6144
	ds_read_b128 v[166:169], v249 offset:7168
	global_load_lds_dwordx4 v[194:195], off
	v_lshl_add_u64 v[194:195], v[222:223], 0, s[22:23]
	s_add_i32 m0, s41, 0xe000
	s_cmp_lg_u32 s24, 0
	global_load_lds_dwordx4 v[194:195], off
	s_waitcnt vmcnt(16)
	s_cselect_b64 s[28:29], -1, 0
	s_cmp_eq_u32 s24, 0
	s_cbranch_scc1 .LBB0_160
	s_waitcnt vmcnt(8)

; __device__ __forceinline__ unsigned cvt_pk_bf16(float lo, float hi) { unsigned r; asm volatile("v_cvt_pk_bf16_f32 %0, %1, %2" : "=v"(r) : "v"(lo), "v"(hi)); return r; }
; #define PG8_STAGE(bufoff, gbase, voff) do { _Pragma("unroll") for (int _i = 0; _i < 2; ++_i) \
;         __builtin_amdgcn_global_load_lds((const unsigned*)((const char*)(gbase) + (voff)[_i]), (PG8_LAS unsigned*)(lds + (bufoff) + ldsw + _i * 8192), 16, 0, 0); } while (0)
; #define PG8_LDA(dst, b, h) do { _Pragma("unroll") for (int m = 0; m < 4; ++m) _Pragma("unroll") for (int k = 0; k < 2; ++k) dst[m][k] = *(const PG8_LAS bf16x8*)(lds + PG8_SA(b, h) + aoff + m * 2048 + k * 1024); } while (0)
; #define PG8_SCHED __builtin_amdgcn_sched_barrier(0)
; #define GAS __attribute__((address_space(1)))
; __device__ __forceinline__ float siluf_(float x) { return x * sigmoidf_(x); }
; template <class Epi, class Sched, bool ALIGN_EPI = false, bool SP2 = false>
; __device__ __forceinline__ void gemm_phase(PG8_LAS unsigned char* lds, const Gemm g, const Sched& S, const Epi& E, const int wave_id) {
;     ...
;             PG8_LDB(B0, 0, 0); PG8_LDB(B1, 0, 1); PG8_SCHED; PG8_LDA(At, 0, 0); PG8_STAGE(PG8_SA(1, 1), a1 + hstep, voffA);
;     __device__ __forceinline__ bool operator()(AccT& acc, const Unit& u, int wr, int wc, int fr, int fq) const {
;         asm volatile("" : "+s"(wr), "+s"(wc), "+v"(fr), "+v"(fq));
;         const int row0 = u.pm * 256 + wr * 64 + fr + 16 * (fq & 1), col0 = u.pn * 128 + wc * 16 + 4 * (fq & 2);
; #pragma unroll
;         for (int ai = 0; ai < 2; ++ai)
; #pragma unroll
;             for (int mp = 0; mp < 2; ++mp) { bf16* rowp = act + (size_t)(row0 + ai * 128 + mp * 32) * DFF + col0;
; #pragma unroll
;                 for (int bj = 0; bj < 2; ++bj) { unsigned pk[2][2];
; #pragma unroll
;                     for (int k = 0; k < 2; ++k) { const f32x4 g = acc[ai][bj][2 * mp + k][0], up = acc[ai][bj][2 * mp + k][1];
;                         pk[k][0] = pg8::cvt_pk_bf16(siluf_(g[0]) * up[0], siluf_(g[1]) * up[1]); pk[k][1] = pg8::cvt_pk_bf16(siluf_(g[2]) * up[2], siluf_(g[3]) * up[3]); }
;                     const auto sx = __builtin_amdgcn_permlane16_swap(pk[0][0], pk[1][0], false, false), sy = __builtin_amdgcn_permlane16_swap(pk[0][1], pk[1][1], false, false);
;                     *(GAS v4u*)(rowp + bj * 64) = (v4u){sx[0], sy[0], sx[1], sy[1]}; } }
.LBB0_164:
	s_add_u32 s100, s68, 0x40080
	s_addc_u32 s101, s13, 0
	v_lshl_add_u64 v[194:195], s[100:101], 0, v[220:221]
	s_add_i32 m0, s41, 0xc000
	s_nop 0
	global_load_lds_dwordx4 v[194:195], off
	v_lshl_add_u64 v[194:195], s[100:101], 0, v[218:219]
	s_add_i32 m0, s41, 0xe000
	s_nop 0
	global_load_lds_dwordx4 v[194:195], off
	v_mul_f32_e32 v137, 0xbfb8aa3b, v126
	v_exp_f32_e32 v137, v137
	s_mov_b32 s11, s39
	v_mov_b32_e32 v130, v1
	s_mov_b32 s13, s56
	v_add_f32_e32 v137, 1.0, v137
	v_rcp_f32_e32 v137, v137
	v_mov_b32_e32 v131, v245
	s_lshl_b32 s19, s19, 7
	v_mul_f32_e32 v126, v126, v137
	v_mul_f32_e32 v122, v122, v126
	v_mul_f32_e32 v126, 0xbfb8aa3b, v127
	v_exp_f32_e32 v126, v126
	s_lshl_b32 s13, s13, 4
	s_lshl_b32 s18, s18, 8
	s_lshl_b32 s11, s11, 6
	v_add_f32_e32 v126, 1.0, v126
	v_rcp_f32_e32 v126, v126
	v_lshlrev_b32_e32 v132, 4, v131
	s_add_i32 s13, s13, s19
	v_lshlrev_b32_e32 v131, 2, v131
	v_mul_f32_e32 v126, v127, v126
	v_mul_f32_e32 v123, v123, v126
	v_cvt_pk_bf16_f32 v122, v122, v123
	v_mul_f32_e32 v123, 0xbfb8aa3b, v128
	v_exp_f32_e32 v123, v123
	v_and_b32_e32 v133, 16, v132
	v_and_or_b32 v132, v131, 8, s13
	s_add_i32 s11, s11, s18
	v_add_f32_e32 v123, 1.0, v123
	v_rcp_f32_e32 v123, v123
	v_add3_u32 v136, s11, v130, v133
	v_ashrrev_i32_e32 v133, 31, v132
	v_mov_b64_e32 v[130:131], s[6:7]
	v_mul_f32_e32 v123, v128, v123
	v_mul_f32_e32 v123, v124, v123
	v_mul_f32_e32 v124, 0xbfb8aa3b, v129
	v_exp_f32_e32 v124, v124
	s_movk_i32 s11, 0x1600
	v_mad_i64_i32 v[134:135], s[18:19], v136, s11, v[130:131]
	v_add_f32_e32 v124, 1.0, v124
	v_rcp_f32_e32 v124, v124
	v_lshlrev_b64 v[132:133], 1, v[132:133]
	v_lshl_add_u64 v[134:135], v[134:135], 0, v[132:133]
	s_andn2_b64 vcc, exec, s[4:5]
	v_mul_f32_e32 v124, v129, v124
	v_mul_f32_e32 v124, v125, v124
	v_cvt_pk_bf16_f32 v123, v123, v124
	v_mul_f32_e32 v124, 0xbfb8aa3b, v118
	v_exp_f32_e32 v124, v124
	s_nop 0
	v_add_f32_e32 v124, 1.0, v124
	v_rcp_f32_e32 v124, v124
	s_nop 0
	v_mul_f32_e32 v118, v118, v124
	v_mul_f32_e32 v114, v114, v118
	v_mul_f32_e32 v118, 0xbfb8aa3b, v119
	v_exp_f32_e32 v118, v118
	s_nop 0
	v_add_f32_e32 v118, 1.0, v118
	v_rcp_f32_e32 v118, v118
	s_nop 0
	v_mul_f32_e32 v118, v119, v118
	v_mul_f32_e32 v115, v115, v118
	v_cvt_pk_bf16_f32 v124, v114, v115
	v_mul_f32_e32 v114, 0xbfb8aa3b, v120
	v_exp_f32_e32 v114, v114
	v_mul_f32_e32 v115, 0xbfb8aa3b, v121
	v_exp_f32_e32 v115, v115
	v_permlane16_swap_b32_e32 v122, v124
	v_add_f32_e32 v114, 1.0, v114
	v_rcp_f32_e32 v114, v114
	v_add_f32_e32 v115, 1.0, v115
	v_rcp_f32_e32 v115, v115
	v_mul_f32_e32 v114, v120, v114
	v_mul_f32_e32 v114, v116, v114
	v_mul_f32_e32 v115, v121, v115
	v_mul_f32_e32 v115, v117, v115
	v_cvt_pk_bf16_f32 v125, v114, v115
	v_mul_f32_e32 v114, 0xbfb8aa3b, v110
	v_exp_f32_e32 v114, v114
	v_permlane16_swap_b32_e32 v123, v125
	global_store_dwordx4 v[134:135], v[122:125], off
	v_add_f32_e32 v114, 1.0, v114
	v_rcp_f32_e32 v114, v114
	s_nop 0
	v_mul_f32_e32 v110, v110, v114
	v_mul_f32_e32 v106, v106, v110
	v_mul_f32_e32 v110, 0xbfb8aa3b, v111
	v_exp_f32_e32 v110, v110
	s_nop 0
	v_add_f32_e32 v110, 1.0, v110
	v_rcp_f32_e32 v110, v110
	s_nop 0
	v_mul_f32_e32 v110, v111, v110
	v_mul_f32_e32 v107, v107, v110
	v_cvt_pk_bf16_f32 v106, v106, v107
	v_mul_f32_e32 v107, 0xbfb8aa3b, v112
	v_exp_f32_e32 v107, v107
	s_nop 0
	v_add_f32_e32 v107, 1.0, v107
	v_rcp_f32_e32 v107, v107
	s_nop 0
	v_mul_f32_e32 v107, v112, v107
	v_mul_f32_e32 v107, v108, v107
	v_mul_f32_e32 v108, 0xbfb8aa3b, v113
	v_exp_f32_e32 v108, v108
	s_nop 0
	v_add_f32_e32 v108, 1.0, v108
	v_rcp_f32_e32 v108, v108
	s_nop 0
	v_mul_f32_e32 v108, v113, v108
	v_mul_f32_e32 v108, v109, v108
	v_cvt_pk_bf16_f32 v107, v107, v108
	v_mul_f32_e32 v108, 0xbfb8aa3b, v102
	v_exp_f32_e32 v108, v108
	s_nop 0
	v_add_f32_e32 v108, 1.0, v108
	v_rcp_f32_e32 v108, v108
	s_nop 0
	v_mul_f32_e32 v102, v102, v108
	v_mul_f32_e32 v98, v98, v102
	v_mul_f32_e32 v102, 0xbfb8aa3b, v103
	v_exp_f32_e32 v102, v102
	s_nop 0
	v_add_f32_e32 v102, 1.0, v102
	v_rcp_f32_e32 v102, v102
	s_nop 0
	v_mul_f32_e32 v102, v103, v102
	v_mul_f32_e32 v99, v99, v102
	v_cvt_pk_bf16_f32 v108, v98, v99
	v_mul_f32_e32 v98, 0xbfb8aa3b, v104
	v_exp_f32_e32 v98, v98
	v_mul_f32_e32 v99, 0xbfb8aa3b, v105
	v_exp_f32_e32 v99, v99
	v_permlane16_swap_b32_e32 v106, v108
	v_add_f32_e32 v98, 1.0, v98
	v_rcp_f32_e32 v98, v98
	v_add_f32_e32 v99, 1.0, v99
	v_rcp_f32_e32 v99, v99
	v_mul_f32_e32 v98, v104, v98
	v_mul_f32_e32 v98, v100, v98
	v_mul_f32_e32 v100, 0xbfb8aa3b, v94
	v_exp_f32_e32 v100, v100
	v_mul_f32_e32 v99, v105, v99
	v_mul_f32_e32 v99, v101, v99
	v_cvt_pk_bf16_f32 v109, v98, v99
	v_add_f32_e32 v100, 1.0, v100
	v_rcp_f32_e32 v100, v100
	v_permlane16_swap_b32_e32 v107, v109
	global_store_dwordx4 v[134:135], v[106:109], off offset:128
	v_mul_f32_e32 v94, v94, v100
	v_mul_f32_e32 v90, v90, v94
	v_mul_f32_e32 v94, 0xbfb8aa3b, v95
	v_exp_f32_e32 v94, v94
	v_add_u32_e32 v98, 32, v136
	v_mad_i64_i32 v[98:99], s[18:19], v98, s11, v[130:131]
	v_add_f32_e32 v94, 1.0, v94
	v_rcp_f32_e32 v94, v94
	v_lshl_add_u64 v[98:99], v[98:99], 0, v[132:133]
	v_mul_f32_e32 v94, v95, v94
	v_mul_f32_e32 v91, v91, v94
	v_cvt_pk_bf16_f32 v90, v90, v91
	v_mul_f32_e32 v91, 0xbfb8aa3b, v96
	v_exp_f32_e32 v91, v91
	s_nop 0
	v_add_f32_e32 v91, 1.0, v91
	v_rcp_f32_e32 v91, v91
	s_nop 0
	v_mul_f32_e32 v91, v96, v91
	v_mul_f32_e32 v91, v92, v91
	v_mul_f32_e32 v92, 0xbfb8aa3b, v97
	v_exp_f32_e32 v92, v92
	s_nop 0
	v_add_f32_e32 v92, 1.0, v92
	v_rcp_f32_e32 v92, v92
	s_nop 0
	v_mul_f32_e32 v92, v97, v92
	v_mul_f32_e32 v92, v93, v92
	v_cvt_pk_bf16_f32 v91, v91, v92
	v_mul_f32_e32 v92, 0xbfb8aa3b, v86
	v_exp_f32_e32 v92, v92
	s_nop 0
	v_add_f32_e32 v92, 1.0, v92
; __device__ __forceinline__ unsigned cvt_pk_bf16(float lo, float hi) { unsigned r; asm volatile("v_cvt_pk_bf16_f32 %0, %1, %2" : "=v"(r) : "v"(lo), "v"(hi)); return r; }
; #define GAS __attribute__((address_space(1)))
; __device__ __forceinline__ float siluf_(float x) { return x * sigmoidf_(x); }
;     __device__ __forceinline__ bool operator()(AccT& acc, const Unit& u, int wr, int wc, int fr, int fq) const {
;     ...
;                 for (int bj = 0; bj < 2; ++bj) { unsigned pk[2][2];
; #pragma unroll
;                     for (int k = 0; k < 2; ++k) { const f32x4 g = acc[ai][bj][2 * mp + k][0], up = acc[ai][bj][2 * mp + k][1];
;                         pk[k][0] = pg8::cvt_pk_bf16(siluf_(g[0]) * up[0], siluf_(g[1]) * up[1]); pk[k][1] = pg8::cvt_pk_bf16(siluf_(g[2]) * up[2], siluf_(g[3]) * up[3]); }
;                     const auto sx = __builtin_amdgcn_permlane16_swap(pk[0][0], pk[1][0], false, false), sy = __builtin_amdgcn_permlane16_swap(pk[0][1], pk[1][1], false, false);
;                     *(GAS v4u*)(rowp + bj * 64) = (v4u){sx[0], sy[0], sx[1], sy[1]}; } }
	v_rcp_f32_e32 v92, v92
	s_nop 0
	v_mul_f32_e32 v86, v86, v92
	v_mul_f32_e32 v82, v82, v86
	v_mul_f32_e32 v86, 0xbfb8aa3b, v87
	v_exp_f32_e32 v86, v86
	s_nop 0
	v_add_f32_e32 v86, 1.0, v86
	v_rcp_f32_e32 v86, v86
	s_nop 0
	v_mul_f32_e32 v86, v87, v86
	v_mul_f32_e32 v83, v83, v86
	v_cvt_pk_bf16_f32 v92, v82, v83
	v_mul_f32_e32 v82, 0xbfb8aa3b, v88
	v_exp_f32_e32 v82, v82
	v_mul_f32_e32 v83, 0xbfb8aa3b, v89
	v_exp_f32_e32 v83, v83
	v_permlane16_swap_b32_e32 v90, v92
	v_add_f32_e32 v82, 1.0, v82
	v_rcp_f32_e32 v82, v82
	v_add_f32_e32 v83, 1.0, v83
	v_rcp_f32_e32 v83, v83
	v_mul_f32_e32 v82, v88, v82
	v_mul_f32_e32 v82, v84, v82
	v_mul_f32_e32 v83, v89, v83
	v_mul_f32_e32 v83, v85, v83
	v_cvt_pk_bf16_f32 v93, v82, v83
	v_mul_f32_e32 v82, 0xbfb8aa3b, v78
	v_exp_f32_e32 v82, v82
	v_permlane16_swap_b32_e32 v91, v93
	global_store_dwordx4 v[98:99], v[90:93], off
	v_add_f32_e32 v82, 1.0, v82
	v_rcp_f32_e32 v82, v82
	s_nop 0
	v_mul_f32_e32 v78, v78, v82
	v_mul_f32_e32 v74, v74, v78
	v_mul_f32_e32 v78, 0xbfb8aa3b, v79
	v_exp_f32_e32 v78, v78
	s_nop 0
	v_add_f32_e32 v78, 1.0, v78
	v_rcp_f32_e32 v78, v78
	s_nop 0
	v_mul_f32_e32 v78, v79, v78
	v_mul_f32_e32 v75, v75, v78
	v_cvt_pk_bf16_f32 v74, v74, v75
	v_mul_f32_e32 v75, 0xbfb8aa3b, v80
	v_exp_f32_e32 v75, v75
	s_nop 0
	v_add_f32_e32 v75, 1.0, v75
	v_rcp_f32_e32 v75, v75
	s_nop 0
	v_mul_f32_e32 v75, v80, v75
	v_mul_f32_e32 v75, v76, v75
	v_mul_f32_e32 v76, 0xbfb8aa3b, v81
	v_exp_f32_e32 v76, v76
	s_nop 0
	v_add_f32_e32 v76, 1.0, v76
	v_rcp_f32_e32 v76, v76
	s_nop 0
	v_mul_f32_e32 v76, v81, v76
	v_mul_f32_e32 v76, v77, v76
	v_cvt_pk_bf16_f32 v75, v75, v76
	v_mul_f32_e32 v76, 0xbfb8aa3b, v70
	v_exp_f32_e32 v76, v76
	s_nop 0
	v_add_f32_e32 v76, 1.0, v76
	v_rcp_f32_e32 v76, v76
	s_nop 0
	v_mul_f32_e32 v70, v70, v76
	v_mul_f32_e32 v66, v66, v70
	v_mul_f32_e32 v70, 0xbfb8aa3b, v71
	v_exp_f32_e32 v70, v70
	s_nop 0
	v_add_f32_e32 v70, 1.0, v70
	v_rcp_f32_e32 v70, v70
	s_nop 0
	v_mul_f32_e32 v70, v71, v70
	v_mul_f32_e32 v67, v67, v70
	v_cvt_pk_bf16_f32 v76, v66, v67
	v_mul_f32_e32 v66, 0xbfb8aa3b, v72
	v_exp_f32_e32 v66, v66
	v_mul_f32_e32 v67, 0xbfb8aa3b, v73
	v_exp_f32_e32 v67, v67
	v_permlane16_swap_b32_e32 v74, v76
	v_add_f32_e32 v66, 1.0, v66
	v_rcp_f32_e32 v66, v66
	v_add_f32_e32 v67, 1.0, v67
	v_rcp_f32_e32 v67, v67
	v_mul_f32_e32 v66, v72, v66
	v_mul_f32_e32 v66, v68, v66
	v_mul_f32_e32 v68, 0xbfb8aa3b, v62
	v_exp_f32_e32 v68, v68
	v_mul_f32_e32 v67, v73, v67
	v_mul_f32_e32 v67, v69, v67
	v_cvt_pk_bf16_f32 v77, v66, v67
	v_add_f32_e32 v68, 1.0, v68
	v_rcp_f32_e32 v68, v68
	v_permlane16_swap_b32_e32 v75, v77
	global_store_dwordx4 v[98:99], v[74:77], off offset:128
	v_mul_f32_e32 v62, v62, v68
	v_mul_f32_e32 v58, v58, v62
	v_mul_f32_e32 v62, 0xbfb8aa3b, v63
	v_exp_f32_e32 v62, v62
	v_add_u32_e32 v66, 0x80, v136
	v_mad_i64_i32 v[66:67], s[18:19], v66, s11, v[130:131]
	v_add_f32_e32 v62, 1.0, v62
	v_rcp_f32_e32 v62, v62
	v_lshl_add_u64 v[66:67], v[66:67], 0, v[132:133]
	v_mul_f32_e32 v62, v63, v62
	v_mul_f32_e32 v59, v59, v62
	v_cvt_pk_bf16_f32 v58, v58, v59
	v_mul_f32_e32 v59, 0xbfb8aa3b, v64
	v_exp_f32_e32 v59, v59
	s_nop 0
	v_add_f32_e32 v59, 1.0, v59
	v_rcp_f32_e32 v59, v59
	s_nop 0
	v_mul_f32_e32 v59, v64, v59
	v_mul_f32_e32 v59, v60, v59
	v_mul_f32_e32 v60, 0xbfb8aa3b, v65
	v_exp_f32_e32 v60, v60
	s_nop 0
	v_add_f32_e32 v60, 1.0, v60
	v_rcp_f32_e32 v60, v60
	s_nop 0
	v_mul_f32_e32 v60, v65, v60
	v_mul_f32_e32 v60, v61, v60
	v_cvt_pk_bf16_f32 v59, v59, v60
	v_mul_f32_e32 v60, 0xbfb8aa3b, v54
	v_exp_f32_e32 v60, v60
	s_nop 0
	v_add_f32_e32 v60, 1.0, v60
	v_rcp_f32_e32 v60, v60
	s_nop 0
	v_mul_f32_e32 v54, v54, v60
	v_mul_f32_e32 v50, v50, v54
	v_mul_f32_e32 v54, 0xbfb8aa3b, v55
	v_exp_f32_e32 v54, v54
	s_nop 0
	v_add_f32_e32 v54, 1.0, v54
	v_rcp_f32_e32 v54, v54
	s_nop 0
	v_mul_f32_e32 v54, v55, v54
	v_mul_f32_e32 v51, v51, v54
	v_cvt_pk_bf16_f32 v60, v50, v51
	v_mul_f32_e32 v50, 0xbfb8aa3b, v56
	v_exp_f32_e32 v50, v50
	v_mul_f32_e32 v51, 0xbfb8aa3b, v57
	v_exp_f32_e32 v51, v51
	v_permlane16_swap_b32_e32 v58, v60
	v_add_f32_e32 v50, 1.0, v50
	v_rcp_f32_e32 v50, v50
	v_add_f32_e32 v51, 1.0, v51
	v_rcp_f32_e32 v51, v51
	v_mul_f32_e32 v50, v56, v50
	v_mul_f32_e32 v50, v52, v50
	v_mul_f32_e32 v51, v57, v51
	v_mul_f32_e32 v51, v53, v51
	v_cvt_pk_bf16_f32 v61, v50, v51
	v_mul_f32_e32 v50, 0xbfb8aa3b, v46
	v_exp_f32_e32 v50, v50
	v_permlane16_swap_b32_e32 v59, v61
	global_store_dwordx4 v[66:67], v[58:61], off
	v_add_f32_e32 v50, 1.0, v50
	v_rcp_f32_e32 v50, v50
	s_nop 0
	v_mul_f32_e32 v46, v46, v50
	v_mul_f32_e32 v42, v42, v46
	v_mul_f32_e32 v46, 0xbfb8aa3b, v47
	v_exp_f32_e32 v46, v46
	s_nop 0
	v_add_f32_e32 v46, 1.0, v46
	v_rcp_f32_e32 v46, v46
	s_nop 0
	v_mul_f32_e32 v46, v47, v46
	v_mul_f32_e32 v43, v43, v46
	v_cvt_pk_bf16_f32 v42, v42, v43
	v_mul_f32_e32 v43, 0xbfb8aa3b, v48
	v_exp_f32_e32 v43, v43
	s_nop 0
	v_add_f32_e32 v43, 1.0, v43
; __device__ __forceinline__ unsigned cvt_pk_bf16(float lo, float hi) { unsigned r; asm volatile("v_cvt_pk_bf16_f32 %0, %1, %2" : "=v"(r) : "v"(lo), "v"(hi)); return r; }
; #define PG8_BAR __builtin_amdgcn_s_barrier()
; #define GAS __attribute__((address_space(1)))
; __device__ __forceinline__ float siluf_(float x) { return x * sigmoidf_(x); }
; template <class Epi, class Sched, bool ALIGN_EPI = false, bool SP2 = false>
; __device__ __forceinline__ void gemm_phase(PG8_LAS unsigned char* lds, const Gemm g, const Sched& S, const Epi& E, const int wave_id) {
;     ...
;         if (!has_next) break;
;         if (!keep_acc) {
; #pragma unroll
;         for (int a = 0; a < 2; ++a)
; #pragma unroll
;             for (int b = 0; b < 2; ++b)
; #pragma unroll
;                 for (int m = 0; m < 4; ++m)
; #pragma unroll
;                     for (int n = 0; n < 2; ++n) acc[a][b][m][n] = (f32x4){0.f, 0.f, 0.f, 0.f};
;         }
;         cur = nxt; cA = nA; cB = nB; ++ui;
;         if constexpr (ALIGN_EPI) { if (wr == 1) PG8_BAR; }
;     __device__ __forceinline__ bool operator()(AccT& acc, const Unit& u, int wr, int wc, int fr, int fq) const {
;     ...
;                 for (int bj = 0; bj < 2; ++bj) { unsigned pk[2][2];
; #pragma unroll
;                     for (int k = 0; k < 2; ++k) { const f32x4 g = acc[ai][bj][2 * mp + k][0], up = acc[ai][bj][2 * mp + k][1];
;                         pk[k][0] = pg8::cvt_pk_bf16(siluf_(g[0]) * up[0], siluf_(g[1]) * up[1]); pk[k][1] = pg8::cvt_pk_bf16(siluf_(g[2]) * up[2], siluf_(g[3]) * up[3]); }
;                     const auto sx = __builtin_amdgcn_permlane16_swap(pk[0][0], pk[1][0], false, false), sy = __builtin_amdgcn_permlane16_swap(pk[0][1], pk[1][1], false, false);
;                     *(GAS v4u*)(rowp + bj * 64) = (v4u){sx[0], sy[0], sx[1], sy[1]}; } }
	v_rcp_f32_e32 v43, v43
	s_nop 0
	v_mul_f32_e32 v43, v48, v43
	v_mul_f32_e32 v43, v44, v43
	v_mul_f32_e32 v44, 0xbfb8aa3b, v49
	v_exp_f32_e32 v44, v44
	s_nop 0
	v_add_f32_e32 v44, 1.0, v44
	v_rcp_f32_e32 v44, v44
	s_nop 0
	v_mul_f32_e32 v44, v49, v44
	v_mul_f32_e32 v44, v45, v44
	v_cvt_pk_bf16_f32 v43, v43, v44
	v_mul_f32_e32 v44, 0xbfb8aa3b, v38
	v_exp_f32_e32 v44, v44
	s_nop 0
	v_add_f32_e32 v44, 1.0, v44
	v_rcp_f32_e32 v44, v44
	s_nop 0
	v_mul_f32_e32 v38, v38, v44
	v_mul_f32_e32 v34, v34, v38
	v_mul_f32_e32 v38, 0xbfb8aa3b, v39
	v_exp_f32_e32 v38, v38
	s_nop 0
	v_add_f32_e32 v38, 1.0, v38
	v_rcp_f32_e32 v38, v38
	s_nop 0
	v_mul_f32_e32 v38, v39, v38
	v_mul_f32_e32 v35, v35, v38
	v_cvt_pk_bf16_f32 v44, v34, v35
	v_mul_f32_e32 v34, 0xbfb8aa3b, v40
	v_exp_f32_e32 v34, v34
	v_mul_f32_e32 v35, 0xbfb8aa3b, v41
	v_exp_f32_e32 v35, v35
	v_permlane16_swap_b32_e32 v42, v44
	v_add_f32_e32 v34, 1.0, v34
	v_rcp_f32_e32 v34, v34
	v_add_f32_e32 v35, 1.0, v35
	v_rcp_f32_e32 v35, v35
	v_mul_f32_e32 v34, v40, v34
	v_mul_f32_e32 v34, v36, v34
	v_mul_f32_e32 v36, 0xbfb8aa3b, v30
	v_exp_f32_e32 v36, v36
	v_mul_f32_e32 v35, v41, v35
	v_mul_f32_e32 v35, v37, v35
	v_cvt_pk_bf16_f32 v45, v34, v35
	v_add_f32_e32 v36, 1.0, v36
	v_rcp_f32_e32 v36, v36
	v_permlane16_swap_b32_e32 v43, v45
	global_store_dwordx4 v[66:67], v[42:45], off offset:128
	v_mul_f32_e32 v30, v30, v36
	v_mul_f32_e32 v26, v26, v30
	v_mul_f32_e32 v30, 0xbfb8aa3b, v31
	v_exp_f32_e32 v30, v30
	v_add_u32_e32 v34, 0xa0, v136
	v_mad_i64_i32 v[34:35], s[18:19], v34, s11, v[130:131]
	v_add_f32_e32 v30, 1.0, v30
	v_rcp_f32_e32 v30, v30
	v_lshl_add_u64 v[34:35], v[34:35], 0, v[132:133]
	s_mov_b64 s[18:19], -1
	v_mul_f32_e32 v30, v31, v30
	v_mul_f32_e32 v27, v27, v30
	v_cvt_pk_bf16_f32 v26, v26, v27
	v_mul_f32_e32 v27, 0xbfb8aa3b, v32
	v_exp_f32_e32 v27, v27
	s_nop 0
	v_add_f32_e32 v27, 1.0, v27
	v_rcp_f32_e32 v27, v27
	s_nop 0
	v_mul_f32_e32 v27, v32, v27
	v_mul_f32_e32 v27, v28, v27
	v_mul_f32_e32 v28, 0xbfb8aa3b, v33
	v_exp_f32_e32 v28, v28
	s_nop 0
	v_add_f32_e32 v28, 1.0, v28
	v_rcp_f32_e32 v28, v28
	s_nop 0
	v_mul_f32_e32 v28, v33, v28
	v_mul_f32_e32 v28, v29, v28
	v_cvt_pk_bf16_f32 v27, v27, v28
	v_mul_f32_e32 v28, 0xbfb8aa3b, v22
	v_exp_f32_e32 v28, v28
	s_nop 0
	v_add_f32_e32 v28, 1.0, v28
	v_rcp_f32_e32 v28, v28
	s_nop 0
	v_mul_f32_e32 v22, v22, v28
	v_mul_f32_e32 v18, v18, v22
	v_mul_f32_e32 v22, 0xbfb8aa3b, v23
	v_exp_f32_e32 v22, v22
	s_nop 0
	v_add_f32_e32 v22, 1.0, v22
	v_rcp_f32_e32 v22, v22
	s_nop 0
	v_mul_f32_e32 v22, v23, v22
	v_mul_f32_e32 v19, v19, v22
	v_cvt_pk_bf16_f32 v28, v18, v19
	v_mul_f32_e32 v18, 0xbfb8aa3b, v24
	v_exp_f32_e32 v18, v18
	v_mul_f32_e32 v19, 0xbfb8aa3b, v25
	v_exp_f32_e32 v19, v19
	v_permlane16_swap_b32_e32 v26, v28
	v_add_f32_e32 v18, 1.0, v18
	v_rcp_f32_e32 v18, v18
	v_add_f32_e32 v19, 1.0, v19
	v_rcp_f32_e32 v19, v19
	v_mul_f32_e32 v18, v24, v18
	v_mul_f32_e32 v18, v20, v18
	v_mul_f32_e32 v19, v25, v19
	v_mul_f32_e32 v19, v21, v19
	v_cvt_pk_bf16_f32 v29, v18, v19
	v_mul_f32_e32 v18, 0xbfb8aa3b, v14
	v_exp_f32_e32 v18, v18
	v_permlane16_swap_b32_e32 v27, v29
	global_store_dwordx4 v[34:35], v[26:29], off
	v_add_f32_e32 v18, 1.0, v18
	v_rcp_f32_e32 v18, v18
	s_nop 0
	v_mul_f32_e32 v14, v14, v18
	v_mul_f32_e32 v10, v10, v14
	v_mul_f32_e32 v14, 0xbfb8aa3b, v15
	v_exp_f32_e32 v14, v14
	s_nop 0
	v_add_f32_e32 v14, 1.0, v14
	v_rcp_f32_e32 v14, v14
	s_nop 0
	v_mul_f32_e32 v14, v15, v14
	v_mul_f32_e32 v11, v11, v14
	v_cvt_pk_bf16_f32 v10, v10, v11
	v_mul_f32_e32 v11, 0xbfb8aa3b, v16
	v_exp_f32_e32 v11, v11
	s_nop 0
	v_add_f32_e32 v11, 1.0, v11
	v_rcp_f32_e32 v11, v11
	s_nop 0
	v_mul_f32_e32 v11, v16, v11
	v_mul_f32_e32 v11, v12, v11
	v_mul_f32_e32 v12, 0xbfb8aa3b, v17
	v_exp_f32_e32 v12, v12
	s_nop 0
	v_add_f32_e32 v12, 1.0, v12
	v_rcp_f32_e32 v12, v12
	s_nop 0
	v_mul_f32_e32 v12, v17, v12
	v_mul_f32_e32 v12, v13, v12
	v_cvt_pk_bf16_f32 v11, v11, v12
	v_mul_f32_e32 v12, 0xbfb8aa3b, v6
	v_exp_f32_e32 v12, v12
	s_nop 0
	v_add_f32_e32 v12, 1.0, v12
	v_rcp_f32_e32 v12, v12
	s_nop 0
	v_mul_f32_e32 v6, v6, v12
	v_mul_f32_e32 v2, v2, v6
	v_mul_f32_e32 v6, 0xbfb8aa3b, v7
	v_exp_f32_e32 v6, v6
	s_nop 0
	v_add_f32_e32 v6, 1.0, v6
	v_rcp_f32_e32 v6, v6
	s_nop 0
	v_mul_f32_e32 v6, v7, v6
	v_mul_f32_e32 v3, v3, v6
	v_cvt_pk_bf16_f32 v12, v2, v3
	v_mul_f32_e32 v2, 0xbfb8aa3b, v8
	v_mul_f32_e32 v3, 0xbfb8aa3b, v9
	v_exp_f32_e32 v2, v2
	v_exp_f32_e32 v3, v3
	v_permlane16_swap_b32_e32 v10, v12
	v_add_f32_e32 v2, 1.0, v2
	v_add_f32_e32 v3, 1.0, v3
	v_rcp_f32_e32 v2, v2
	v_rcp_f32_e32 v3, v3
	v_mul_f32_e32 v2, v8, v2
	v_mul_f32_e32 v3, v9, v3
	v_mul_f32_e32 v2, v4, v2
	v_mul_f32_e32 v3, v5, v3
	v_cvt_pk_bf16_f32 v13, v2, v3
	s_nop 0
	v_permlane16_swap_b32_e32 v11, v13
	global_store_dwordx4 v[34:35], v[10:13], off offset:128
	s_cbranch_vccnz .LBB0_149
	s_andn2_b64 vcc, exec, s[2:3]
	s_cbranch_vccnz .LBB0_148
	s_barrier
	s_branch .LBB0_148

; #define PG8_STAGE(bufoff, gbase, voff) do { _Pragma("unroll") for (int _i = 0; _i < 2; ++_i) \
;         __builtin_amdgcn_global_load_lds((const unsigned*)((const char*)(gbase) + (voff)[_i]), (PG8_LAS unsigned*)(lds + (bufoff) + ldsw + _i * 8192), 16, 0, 0); } while (0)
; #define PG8_LDA(dst, b, h) do { _Pragma("unroll") for (int m = 0; m < 4; ++m) _Pragma("unroll") for (int k = 0; k < 2; ++k) dst[m][k] = *(const PG8_LAS bf16x8*)(lds + PG8_SA(b, h) + aoff + m * 2048 + k * 1024); } while (0)
; #define PG8_LDB(dst, b, h) do { _Pragma("unroll") for (int n = 0; n < 2; ++n) _Pragma("unroll") for (int k = 0; k < 2; ++k) dst[n][k] = *(const PG8_LAS bf16x8*)(lds + PG8_SB(b, h) + boff + n * 2048 + k * 1024); } while (0)
; #define PG8_MMA(ai, bj, At, Bt) do { __builtin_amdgcn_s_setprio(1); _Pragma("unroll") for (int m = 0; m < 4; ++m) _Pragma("unroll") for (int n = 0; n < 2; ++n) _Pragma("unroll") for (int k = 0; k < 2; ++k) \
;         acc[ai][bj][m][n] = __builtin_amdgcn_mfma_f32_16x16x32_bf16(Bt[n][k], At[m][k], acc[ai][bj][m][n], 0, 0, 0); __builtin_amdgcn_s_setprio(0); } while (0)
; #define PG8_WAIT_V(n) asm volatile("s_waitcnt vmcnt(" #n ")" ::: "memory")
; #define PG8_WAIT_VN(n) asm volatile("s_waitcnt vmcnt(%0)" :: "n"(n) : "memory")
; #define PG8_WAIT_L(n) asm volatile("s_waitcnt lgkmcnt(" #n ")" ::: "memory")
; #define PG8_BAR __builtin_amdgcn_s_barrier()
; #define PG8_SCHED __builtin_amdgcn_sched_barrier(0)
; template <class Epi, class Sched, bool ALIGN_EPI = false, bool SP2 = false>
; __device__ __forceinline__ void gemm_phase(PG8_LAS unsigned char* lds, const Gemm g, const Sched& S, const Epi& E, const int wave_id) {
;     ...
;             PG8_WAIT_VN(8 + Epi::NS); if (strict) PG8_WAIT_V(8); PG8_WAIT_L(0); PG8_BAR; PG8_MMA(1, 0, At, B0); PG8_MMA(1, 1, At, B1); PG8_BAR; PG8_SCHED;
;             PG8_LDB(B0, 1, 0); PG8_LDB(B1, 1, 1); PG8_SCHED; PG8_LDA(At, 1, 0); PG8_STAGE(PG8_SA(0, 1), a2 + hstep, voffA);
;             PG8_WAIT_V(8); PG8_WAIT_L(0); PG8_BAR; PG8_MMA(0, 0, At, B0); PG8_MMA(0, 1, At, B1); PG8_BAR; PG8_SCHED;
.LBB0_235:
	s_waitcnt lgkmcnt(0)
	s_barrier
	s_setprio 1
	s_waitcnt lgkmcnt(0)
	v_mfma_f32_16x16x32_bf16 v[62:65], v[146:149], v[186:189], v[62:65]
	v_mfma_f32_16x16x32_bf16 v[58:61], v[154:157], v[186:189], v[58:61]
	v_mfma_f32_16x16x32_bf16 v[46:49], v[146:149], v[178:181], v[46:49]
	v_mfma_f32_16x16x32_bf16 v[42:45], v[154:157], v[178:181], v[42:45]
	v_mfma_f32_16x16x32_bf16 v[30:33], v[146:149], v[170:173], v[30:33]
	v_mfma_f32_16x16x32_bf16 v[26:29], v[154:157], v[170:173], v[26:29]
	v_mfma_f32_16x16x32_bf16 v[14:17], v[146:149], v[162:165], v[14:17]
	v_mfma_f32_16x16x32_bf16 v[10:13], v[154:157], v[162:165], v[10:13]
	v_mfma_f32_16x16x32_bf16 v[62:65], v[150:153], v[190:193], v[62:65]
	v_mfma_f32_16x16x32_bf16 v[58:61], v[158:161], v[190:193], v[58:61]
	v_mfma_f32_16x16x32_bf16 v[46:49], v[150:153], v[182:185], v[46:49]
	v_mfma_f32_16x16x32_bf16 v[42:45], v[158:161], v[182:185], v[42:45]
	v_mfma_f32_16x16x32_bf16 v[30:33], v[150:153], v[174:177], v[30:33]
	v_mfma_f32_16x16x32_bf16 v[26:29], v[158:161], v[174:177], v[26:29]
	v_mfma_f32_16x16x32_bf16 v[14:17], v[150:153], v[166:169], v[14:17]
	v_mfma_f32_16x16x32_bf16 v[10:13], v[158:161], v[166:169], v[10:13]
	s_setprio 0
	s_setprio 1
	v_mfma_f32_16x16x32_bf16 v[54:57], v[130:133], v[186:189], v[54:57]
	v_mfma_f32_16x16x32_bf16 v[50:53], v[138:141], v[186:189], v[50:53]
	v_mfma_f32_16x16x32_bf16 v[38:41], v[130:133], v[178:181], v[38:41]
	v_mfma_f32_16x16x32_bf16 v[34:37], v[138:141], v[178:181], v[34:37]
	v_mfma_f32_16x16x32_bf16 v[22:25], v[130:133], v[170:173], v[22:25]
	v_mfma_f32_16x16x32_bf16 v[18:21], v[138:141], v[170:173], v[18:21]
	v_mfma_f32_16x16x32_bf16 v[6:9], v[130:133], v[162:165], v[6:9]
	v_mfma_f32_16x16x32_bf16 v[2:5], v[138:141], v[162:165], v[2:5]
	v_mfma_f32_16x16x32_bf16 v[54:57], v[134:137], v[190:193], v[54:57]
	v_mfma_f32_16x16x32_bf16 v[50:53], v[142:145], v[190:193], v[50:53]
	v_mfma_f32_16x16x32_bf16 v[38:41], v[134:137], v[182:185], v[38:41]
	v_mfma_f32_16x16x32_bf16 v[34:37], v[142:145], v[182:185], v[34:37]
	v_mfma_f32_16x16x32_bf16 v[22:25], v[134:137], v[174:177], v[22:25]
	v_mfma_f32_16x16x32_bf16 v[18:21], v[142:145], v[174:177], v[18:21]
	v_mfma_f32_16x16x32_bf16 v[6:9], v[134:137], v[166:169], v[6:9]
	v_mfma_f32_16x16x32_bf16 v[2:5], v[142:145], v[166:169], v[2:5]
	s_setprio 0
	s_barrier
	s_add_i32 s20, 0, 0x18000
	s_add_i32 s21, 0, 0x1c000
	v_add_u32_e32 v142, s20, v246
	v_add_u32_e32 v158, s21, v246
	ds_read_b128 v[130:133], v142
	ds_read_b128 v[134:137], v142 offset:1024
	ds_read_b128 v[138:141], v142 offset:2048
	ds_read_b128 v[142:145], v142 offset:3072
	ds_read_b128 v[146:149], v158
	ds_read_b128 v[150:153], v158 offset:1024
	ds_read_b128 v[154:157], v158 offset:2048
	ds_read_b128 v[158:161], v158 offset:3072
	s_add_u32 s18, s18, 0xb0000
	s_addc_u32 s19, s19, 0
	s_mov_b32 m0, s39
	v_lshl_add_u64 v[194:195], s[18:19], 0, v[210:211]
	ds_read_b128 v[162:165], v247 offset:32768
	ds_read_b128 v[166:169], v247 offset:33792
	ds_read_b128 v[170:173], v247 offset:34816
	ds_read_b128 v[174:177], v247 offset:35840
	ds_read_b128 v[178:181], v247 offset:36864
	ds_read_b128 v[182:185], v247 offset:37888
	ds_read_b128 v[186:189], v247 offset:38912
	ds_read_b128 v[190:193], v247 offset:39936
	global_load_lds_dwordx4 v[194:195], off
	v_lshl_add_u64 v[194:195], s[18:19], 0, v[214:215]
	s_mov_b32 m0, s40
	s_nop 0
	global_load_lds_dwordx4 v[194:195], off
	s_waitcnt vmcnt(26)
	s_cmp_eq_u32 s100, 0
	s_cbranch_scc1 .Lthird_wait_relaxed_5
	s_waitcnt vmcnt(8)
.Lthird_wait_relaxed_5:
	s_waitcnt lgkmcnt(0)
	s_barrier
	s_setprio 1
	s_waitcnt lgkmcnt(0)
	v_mfma_f32_16x16x32_bf16 v[126:129], v[130:133], v[162:165], v[126:129]
	v_mfma_f32_16x16x32_bf16 v[122:125], v[138:141], v[162:165], v[122:125]
	v_mfma_f32_16x16x32_bf16 v[110:113], v[130:133], v[170:173], v[110:113]
	v_mfma_f32_16x16x32_bf16 v[106:109], v[138:141], v[170:173], v[106:109]
	v_mfma_f32_16x16x32_bf16 v[94:97], v[130:133], v[178:181], v[94:97]
	v_mfma_f32_16x16x32_bf16 v[90:93], v[138:141], v[178:181], v[90:93]
	v_mfma_f32_16x16x32_bf16 v[78:81], v[130:133], v[186:189], v[78:81]
	v_mfma_f32_16x16x32_bf16 v[74:77], v[138:141], v[186:189], v[74:77]
	v_mfma_f32_16x16x32_bf16 v[126:129], v[134:137], v[166:169], v[126:129]
	v_mfma_f32_16x16x32_bf16 v[122:125], v[142:145], v[166:169], v[122:125]
	v_mfma_f32_16x16x32_bf16 v[110:113], v[134:137], v[174:177], v[110:113]
	v_mfma_f32_16x16x32_bf16 v[106:109], v[142:145], v[174:177], v[106:109]
	v_mfma_f32_16x16x32_bf16 v[94:97], v[134:137], v[182:185], v[94:97]
	v_mfma_f32_16x16x32_bf16 v[90:93], v[142:145], v[182:185], v[90:93]
	v_mfma_f32_16x16x32_bf16 v[78:81], v[134:137], v[190:193], v[78:81]
	v_mfma_f32_16x16x32_bf16 v[74:77], v[142:145], v[190:193], v[74:77]
	s_setprio 0
	s_setprio 1
	v_mfma_f32_16x16x32_bf16 v[118:121], v[146:149], v[162:165], v[118:121]
	v_mfma_f32_16x16x32_bf16 v[114:117], v[154:157], v[162:165], v[114:117]
	v_mfma_f32_16x16x32_bf16 v[102:105], v[146:149], v[170:173], v[102:105]
	v_mfma_f32_16x16x32_bf16 v[98:101], v[154:157], v[170:173], v[98:101]
	v_mfma_f32_16x16x32_bf16 v[86:89], v[146:149], v[178:181], v[86:89]
	v_mfma_f32_16x16x32_bf16 v[82:85], v[154:157], v[178:181], v[82:85]
	v_mfma_f32_16x16x32_bf16 v[70:73], v[146:149], v[186:189], v[70:73]
	v_mfma_f32_16x16x32_bf16 v[66:69], v[154:157], v[186:189], v[66:69]
	v_mfma_f32_16x16x32_bf16 v[118:121], v[150:153], v[166:169], v[118:121]
	v_mfma_f32_16x16x32_bf16 v[114:117], v[158:161], v[166:169], v[114:117]
	v_mfma_f32_16x16x32_bf16 v[102:105], v[150:153], v[174:177], v[102:105]
	v_mfma_f32_16x16x32_bf16 v[98:101], v[158:161], v[174:177], v[98:101]
	v_mfma_f32_16x16x32_bf16 v[86:89], v[150:153], v[182:185], v[86:89]
	v_mfma_f32_16x16x32_bf16 v[82:85], v[158:161], v[182:185], v[82:85]
	v_mfma_f32_16x16x32_bf16 v[70:73], v[150:153], v[190:193], v[70:73]
	v_mfma_f32_16x16x32_bf16 v[66:69], v[158:161], v[190:193], v[66:69]
	s_setprio 0
	s_barrier
; #define PG8_STAGE(bufoff, gbase, voff) do { _Pragma("unroll") for (int _i = 0; _i < 2; ++_i) \
;         __builtin_amdgcn_global_load_lds((const unsigned*)((const char*)(gbase) + (voff)[_i]), (PG8_LAS unsigned*)(lds + (bufoff) + ldsw + _i * 8192), 16, 0, 0); } while (0)
; #define PG8_LDA(dst, b, h) do { _Pragma("unroll") for (int m = 0; m < 4; ++m) _Pragma("unroll") for (int k = 0; k < 2; ++k) dst[m][k] = *(const PG8_LAS bf16x8*)(lds + PG8_SA(b, h) + aoff + m * 2048 + k * 1024); } while (0)
; #define PG8_LDB(dst, b, h) do { _Pragma("unroll") for (int n = 0; n < 2; ++n) _Pragma("unroll") for (int k = 0; k < 2; ++k) dst[n][k] = *(const PG8_LAS bf16x8*)(lds + PG8_SB(b, h) + boff + n * 2048 + k * 1024); } while (0)
; #define PG8_WAIT_V(n) asm volatile("s_waitcnt vmcnt(" #n ")" ::: "memory")
; #define PG8_WAIT_VN(n) asm volatile("s_waitcnt vmcnt(%0)" :: "n"(n) : "memory")
; template <class Epi, class Sched, bool ALIGN_EPI = false, bool SP2 = false>
; __device__ __forceinline__ void gemm_phase(PG8_LAS unsigned char* lds, const Gemm g, const Sched& S, const Epi& E, const int wave_id) {
;     ...
;             int tz_ = __builtin_amdgcn_readfirstlane(t | (ui > 0 ? 0 : 1)); asm volatile("" : "+s"(tz_));
;             const bool strict = !(Epi::NS > 0 && tz_ == 0);
;             PG8_LDB(B0, 0, 0); PG8_LDB(B1, 0, 1); PG8_SCHED; PG8_LDA(At, 0, 0); PG8_STAGE(PG8_SA(1, 1), a1 + hstep, voffA);
;             PG8_WAIT_VN(8 + Epi::NS); if (strict) PG8_WAIT_V(8); PG8_WAIT_L(0); PG8_BAR; PG8_MMA(0, 0, At, B0); PG8_MMA(0, 1, At, B1); PG8_BAR; PG8_SCHED;
;             PG8_LDA(At, 0, 1); PG8_STAGE(PG8_SB(0, 0), b2, voffB); PG8_STAGE(PG8_SB(0, 1), b2 + hstep, voffB); PG8_STAGE(PG8_SA(0, 0), a2, voffA);
;             PG8_WAIT_VN(8 + Epi::NS); if (strict) PG8_WAIT_V(8); PG8_WAIT_L(0); PG8_BAR; PG8_MMA(1, 0, At, B0); PG8_MMA(1, 1, At, B1); PG8_BAR; PG8_SCHED;
;             PG8_LDB(B0, 1, 0); PG8_LDB(B1, 1, 1); PG8_SCHED; PG8_LDA(At, 1, 0); PG8_STAGE(PG8_SA(0, 1), a2 + hstep, voffA);
;             PG8_WAIT_V(8); PG8_WAIT_L(0); PG8_BAR; PG8_MMA(0, 0, At, B0); PG8_MMA(0, 1, At, B1); PG8_BAR; PG8_SCHED;
;             PG8_LDA(At, 1, 1); PG8_STAGE(PG8_SB(1, 0), b3, voffB); PG8_STAGE(PG8_SB(1, 1), b3 + hstep, voffB); PG8_STAGE(PG8_SA(1, 0), a3, voffA);
;             PG8_WAIT_V(8); PG8_WAIT_L(0); PG8_BAR; PG8_MMA(1, 0, At, B0); PG8_MMA(1, 1, At, B1); PG8_BAR; PG8_SCHED;
	s_add_i32 s18, s20, s30
	v_lshl_add_u64 v[194:195], v[232:233], 0, s[64:65]
	s_mov_b32 m0, s18
	ds_read_b128 v[162:165], v247 offset:49152
	ds_read_b128 v[166:169], v247 offset:50176
	ds_read_b128 v[170:173], v247 offset:51200
	ds_read_b128 v[174:177], v247 offset:52224
	ds_read_b128 v[178:181], v247 offset:53248
	ds_read_b128 v[182:185], v247 offset:54272
	ds_read_b128 v[186:189], v247 offset:55296
	ds_read_b128 v[190:193], v247 offset:56320
	global_load_lds_dwordx4 v[194:195], off
	s_add_i32 m0, s18, 0x2000
	s_add_u32 s16, s16, 0xb0080
	v_lshl_add_u64 v[194:195], v[230:231], 0, s[64:65]
	s_addc_u32 s17, s17, 0
	s_add_i32 s18, s21, s30
	global_load_lds_dwordx4 v[194:195], off
	v_lshl_add_u64 v[194:195], s[16:17], 0, v[212:213]
	s_mov_b32 m0, s18
	s_nop 0
	global_load_lds_dwordx4 v[194:195], off
	v_lshl_add_u64 v[194:195], s[16:17], 0, v[216:217]
	s_add_i32 m0, s18, 0x2000
	s_nop 0
	global_load_lds_dwordx4 v[194:195], off
	v_lshl_add_u64 v[194:195], v[226:227], 0, s[64:65]
	s_mov_b32 m0, s42
	s_nop 0
	global_load_lds_dwordx4 v[194:195], off
	v_lshl_add_u64 v[194:195], v[228:229], 0, s[64:65]
	s_mov_b32 m0, s43
	s_nop 0
	global_load_lds_dwordx4 v[194:195], off
	s_waitcnt vmcnt(8)
	s_waitcnt lgkmcnt(0)
	s_barrier
	s_setprio 1
	s_waitcnt lgkmcnt(0)
	v_mfma_f32_16x16x32_bf16 v[62:65], v[130:133], v[162:165], v[62:65]
	v_mfma_f32_16x16x32_bf16 v[58:61], v[138:141], v[162:165], v[58:61]
	v_mfma_f32_16x16x32_bf16 v[46:49], v[130:133], v[170:173], v[46:49]
	v_mfma_f32_16x16x32_bf16 v[42:45], v[138:141], v[170:173], v[42:45]
	v_mfma_f32_16x16x32_bf16 v[30:33], v[130:133], v[178:181], v[30:33]
	v_mfma_f32_16x16x32_bf16 v[26:29], v[138:141], v[178:181], v[26:29]
	v_mfma_f32_16x16x32_bf16 v[14:17], v[130:133], v[186:189], v[14:17]
	v_mfma_f32_16x16x32_bf16 v[10:13], v[138:141], v[186:189], v[10:13]
	v_mfma_f32_16x16x32_bf16 v[62:65], v[134:137], v[166:169], v[62:65]
	v_mfma_f32_16x16x32_bf16 v[58:61], v[142:145], v[166:169], v[58:61]
	v_mfma_f32_16x16x32_bf16 v[46:49], v[134:137], v[174:177], v[46:49]
	v_mfma_f32_16x16x32_bf16 v[42:45], v[142:145], v[174:177], v[42:45]
	v_mfma_f32_16x16x32_bf16 v[30:33], v[134:137], v[182:185], v[30:33]
	v_mfma_f32_16x16x32_bf16 v[26:29], v[142:145], v[182:185], v[26:29]
	v_mfma_f32_16x16x32_bf16 v[14:17], v[134:137], v[190:193], v[14:17]
	v_mfma_f32_16x16x32_bf16 v[10:13], v[142:145], v[190:193], v[10:13]
	s_setprio 0
	s_setprio 1
	v_mfma_f32_16x16x32_bf16 v[54:57], v[146:149], v[162:165], v[54:57]
	v_mfma_f32_16x16x32_bf16 v[50:53], v[154:157], v[162:165], v[50:53]
	v_mfma_f32_16x16x32_bf16 v[38:41], v[146:149], v[170:173], v[38:41]
	v_mfma_f32_16x16x32_bf16 v[34:37], v[154:157], v[170:173], v[34:37]
	v_mfma_f32_16x16x32_bf16 v[22:25], v[146:149], v[178:181], v[22:25]
	v_mfma_f32_16x16x32_bf16 v[18:21], v[154:157], v[178:181], v[18:21]
	v_mfma_f32_16x16x32_bf16 v[6:9], v[146:149], v[186:189], v[6:9]
	v_mfma_f32_16x16x32_bf16 v[2:5], v[154:157], v[186:189], v[2:5]
	v_mfma_f32_16x16x32_bf16 v[54:57], v[150:153], v[166:169], v[54:57]
	v_mfma_f32_16x16x32_bf16 v[50:53], v[158:161], v[166:169], v[50:53]
	v_mfma_f32_16x16x32_bf16 v[38:41], v[150:153], v[174:177], v[38:41]
	v_mfma_f32_16x16x32_bf16 v[34:37], v[158:161], v[174:177], v[34:37]
	v_mfma_f32_16x16x32_bf16 v[22:25], v[150:153], v[182:185], v[22:25]
	v_mfma_f32_16x16x32_bf16 v[18:21], v[158:161], v[182:185], v[18:21]
	v_mfma_f32_16x16x32_bf16 v[6:9], v[150:153], v[190:193], v[6:9]
	v_mfma_f32_16x16x32_bf16 v[2:5], v[158:161], v[190:193], v[2:5]
	s_setprio 0
	s_barrier
	s_add_i32 s63, s63, 2
	s_add_u32 s14, s14, 0x100
	s_addc_u32 s15, s15, 0
	s_cmp_gt_u32 s63, 41
	s_cbranch_scc1 .LBB0_240
.LBB0_236:
	v_add_u32_e32 v130, s63, v248
	v_add_u32_e32 v130, 2, v130
	s_nop 0
	v_readfirstlane_b32 s16, v130
	s_nop 0
	s_mov_b32 s100, s16
	v_add_u32_e32 v130, 0, v246
	v_add_u32_e32 v131, 0x10000, v130
	v_add_u32_e32 v142, 0x14000, v130
	ds_read_b128 v[146:149], v131
	ds_read_b128 v[150:153], v131 offset:1024
	ds_read_b128 v[154:157], v131 offset:2048
	ds_read_b128 v[158:161], v131 offset:3072
	ds_read_b128 v[130:133], v142
	ds_read_b128 v[134:137], v142 offset:1024
	ds_read_b128 v[138:141], v142 offset:2048
	ds_read_b128 v[142:145], v142 offset:3072
	v_lshl_add_u64 v[194:195], v[224:225], 0, s[14:15]
	s_add_i32 m0, s31, 0xc000
	ds_read_b128 v[186:189], v247
	ds_read_b128 v[190:193], v247 offset:1024
	ds_read_b128 v[178:181], v247 offset:2048
	ds_read_b128 v[182:185], v247 offset:3072
	ds_read_b128 v[170:173], v247 offset:4096
	ds_read_b128 v[174:177], v247 offset:5120
	ds_read_b128 v[162:165], v247 offset:6144
	ds_read_b128 v[166:169], v247 offset:7168
	global_load_lds_dwordx4 v[194:195], off
	v_lshl_add_u64 v[194:195], v[222:223], 0, s[14:15]
	s_add_i32 m0, s31, 0xe000
	s_cmp_lg_u32 s16, 0
	global_load_lds_dwordx4 v[194:195], off
	s_waitcnt vmcnt(24)
	s_cselect_b64 s[20:21], -1, 0
	s_cmp_eq_u32 s16, 0
	s_cbranch_scc1 .LBB0_238
	s_waitcnt vmcnt(8)

; #define PG8_STAGE(bufoff, gbase, voff) do { _Pragma("unroll") for (int _i = 0; _i < 2; ++_i) \
;         __builtin_amdgcn_global_load_lds((const unsigned*)((const char*)(gbase) + (voff)[_i]), (PG8_LAS unsigned*)(lds + (bufoff) + ldsw + _i * 8192), 16, 0, 0); } while (0)
; #define PG8_LDA(dst, b, h) do { _Pragma("unroll") for (int m = 0; m < 4; ++m) _Pragma("unroll") for (int k = 0; k < 2; ++k) dst[m][k] = *(const PG8_LAS bf16x8*)(lds + PG8_SA(b, h) + aoff + m * 2048 + k * 1024); } while (0)
; #define PG8_LDB(dst, b, h) do { _Pragma("unroll") for (int n = 0; n < 2; ++n) _Pragma("unroll") for (int k = 0; k < 2; ++k) dst[n][k] = *(const PG8_LAS bf16x8*)(lds + PG8_SB(b, h) + boff + n * 2048 + k * 1024); } while (0)
; #define PG8_SCHED __builtin_amdgcn_sched_barrier(0)
; #define GAS __attribute__((address_space(1)))
; __device__ __forceinline__ v4u tr4(int a, v4u x) { return (v4u){bperm(a, x.x), bperm(a, x.y), bperm(a, x.z), bperm(a, x.w)}; }
; template <class Epi, class Sched, bool ALIGN_EPI = false, bool SP2 = false>
; __device__ __forceinline__ void gemm_phase(PG8_LAS unsigned char* lds, const Gemm g, const Sched& S, const Epi& E, const int wave_id) {
;     ...
;             PG8_LDB(B0, 0, 0); PG8_LDB(B1, 0, 1); PG8_SCHED; PG8_LDA(At, 0, 0); PG8_STAGE(PG8_SA(1, 1), a1 + hstep, voffA);
;     __device__ __forceinline__ bool operator()(AccT& acc, const Unit& u, int wr, int wc, int fr, int fq) const {
;         asm volatile("" : "+s"(wr), "+s"(wc), "+v"(fr), "+v"(fq));
;         const LaneT t = lane_t(fr, fq);
;         const bf16* src = (const bf16*)(ws + WS_HB); bf16* dst = (bf16*)(ws + WS_YB);
;         const int row0 = u.pm * 256 + wr * 64 + t.tfr, col0 = u.pn * 256 + wc * 32 + 8 * t.tfq;
; #pragma unroll
;         for (int ai = 0; ai < 2; ++ai)
; #pragma unroll
;             for (int m = 0; m < 4; ++m) { const size_t off = (size_t)(row0 + ai * 128 + m * 16) * D + col0;
; #pragma unroll
;                 for (int bj = 0; bj < 2; ++bj) { const v4u r = tr4(t.push, *(const GAS v4u*)(src + off + bj * 128));
;                     const f32x4 y0 = (f32x4){bflo(r.x), bfhi(r.x), bflo(r.y), bfhi(r.y)} * ca + acc[ai][bj][m][0] * cb, y1 = (f32x4){bflo(r.z), bfhi(r.z), bflo(r.w), bfhi(r.w)} * ca + acc[ai][bj][m][1] * cb;
;                     *(GAS v4u*)(dst + off + bj * 128) = tr4(t.pull, pack8(y0, y1)); } }
.LBB0_242:
	s_add_u32 s100, s6, 0xb0080
	s_addc_u32 s101, s7, 0
	v_lshl_add_u64 v[194:195], s[100:101], 0, v[220:221]
	s_add_i32 m0, s31, 0xc000
	s_nop 0
	global_load_lds_dwordx4 v[194:195], off
	v_lshl_add_u64 v[194:195], s[100:101], 0, v[218:219]
	s_add_i32 m0, s31, 0xe000
	s_nop 0
	global_load_lds_dwordx4 v[194:195], off
	s_mov_b32 s12, s41
	v_mov_b32_e32 v130, v1
	s_mov_b32 s13, s29
	v_mov_b32_e32 v131, v245
	s_lshl_b32 s14, s54, 8
	v_lshl_add_u32 v132, v130, 4, v131
	s_lshl_b32 s13, s13, 6
	v_ashrrev_i32_e32 v134, 2, v132
	v_and_b32_e32 v135, 3, v131
	v_lshlrev_b32_e32 v131, 4, v131
	s_add_i32 s13, s13, s14
	v_lshl_add_u32 v133, v130, 2, v131
	v_add_u32_e32 v130, s13, v134
	s_lshl_b32 s13, s56, 8
	s_lshl_b32 s12, s12, 5
	s_add_i32 s12, s12, s13
	v_and_b32_e32 v132, -4, v132
	v_lshl_or_b32 v134, v135, 3, s12
	v_ashrrev_i32_e32 v131, 31, v130
	v_lshl_add_u32 v132, v135, 6, v132
	v_ashrrev_i32_e32 v135, 31, v134
	v_lshlrev_b64 v[130:131], 10, v[130:131]
	v_lshl_add_u64 v[130:131], v[130:131], 0, v[134:135]
	v_readlane_b32 s14, v253, 11
	v_lshlrev_b64 v[130:131], 1, v[130:131]
	v_readlane_b32 s15, v253, 12
	v_lshl_add_u64 v[140:141], s[60:61], 0, v[130:131]
	s_mov_b64 s[12:13], 0x8000
	v_lshl_add_u64 v[138:139], s[14:15], 0, v[130:131]
	v_mov_b64_e32 v[130:131], v[138:139]
	global_load_dwordx4 v[146:149], v[130:131], off
	s_and_b64 vcc, exec, s[4:5]
	global_load_dwordx4 v[150:153], v[130:131], off offset:256
	s_mov_b64 s[12:13], 0x8000
	v_lshl_add_u64 v[130:131], v[138:139], 0, s[12:13]
	global_load_dwordx4 v[154:157], v[130:131], off
	global_load_dwordx4 v[158:161], v[130:131], off offset:256
	s_mov_b64 s[12:13], 0x10000
	v_lshl_add_u64 v[130:131], v[138:139], 0, s[12:13]
	global_load_dwordx4 v[162:165], v[130:131], off
	global_load_dwordx4 v[166:169], v[130:131], off offset:256
	s_mov_b64 s[12:13], 0x18000
	v_lshl_add_u64 v[130:131], v[138:139], 0, s[12:13]
	global_load_dwordx4 v[170:173], v[130:131], off
	global_load_dwordx4 v[174:177], v[130:131], off offset:256
	s_mov_b64 s[12:13], 0x40000
	v_lshl_add_u64 v[130:131], v[138:139], 0, s[12:13]
	global_load_dwordx4 v[178:181], v[130:131], off
	global_load_dwordx4 v[182:185], v[130:131], off offset:256
	s_mov_b64 s[12:13], 0x48000
	v_lshl_add_u64 v[130:131], v[138:139], 0, s[12:13]
	global_load_dwordx4 v[186:189], v[130:131], off
	global_load_dwordx4 v[190:193], v[130:131], off offset:256
	s_waitcnt vmcnt(11)
	ds_bpermute_b32 v143, v133, v147
	ds_bpermute_b32 v142, v133, v146
	ds_bpermute_b32 v145, v133, v149
	ds_bpermute_b32 v144, v133, v148
	v_mov_b64_e32 v[134:135], v[140:141]
	s_waitcnt lgkmcnt(3)
	v_lshlrev_b32_e32 v136, 16, v143
	v_and_b32_e32 v137, 0xffff0000, v143
	s_waitcnt lgkmcnt(2)
	v_and_b32_e32 v143, 0xffff0000, v142
	v_lshlrev_b32_e32 v142, 16, v142
	v_pk_mul_f32 v[136:137], v[136:137], s[96:97] op_sel_hi:[1,0]
	v_pk_fma_f32 v[128:129], v[128:129], 0.5, v[136:137] op_sel_hi:[1,0,1]
	v_pk_mul_f32 v[142:143], v[142:143], s[96:97] op_sel_hi:[1,0]
	v_pk_fma_f32 v[126:127], v[126:127], 0.5, v[142:143] op_sel_hi:[1,0,1]
	s_waitcnt lgkmcnt(1)
	v_lshlrev_b32_e32 v136, 16, v145
	v_and_b32_e32 v137, 0xffff0000, v145
	s_waitcnt lgkmcnt(0)
	v_and_b32_e32 v145, 0xffff0000, v144
	v_lshlrev_b32_e32 v144, 16, v144
	v_pk_mul_f32 v[136:137], v[136:137], s[96:97] op_sel_hi:[1,0]
	v_pk_fma_f32 v[124:125], v[124:125], 0.5, v[136:137] op_sel_hi:[1,0,1]
	v_pk_mul_f32 v[144:145], v[144:145], s[96:97] op_sel_hi:[1,0]
	v_pk_fma_f32 v[122:123], v[122:123], 0.5, v[144:145] op_sel_hi:[1,0,1]
	v_cvt_pk_bf16_f32 v126, v126, v127
	v_cvt_pk_bf16_f32 v127, v128, v129
	v_cvt_pk_bf16_f32 v128, v122, v123
	v_cvt_pk_bf16_f32 v125, v124, v125
	s_nop 1
	ds_bpermute_b32 v122, v132, v126
	ds_bpermute_b32 v123, v132, v127
	ds_bpermute_b32 v124, v132, v128
	ds_bpermute_b32 v125, v132, v125
	s_waitcnt lgkmcnt(0)
	global_store_dwordx4 v[134:135], v[122:125], off
	s_mov_b64 s[12:13], 0x50000
	v_lshl_add_u64 v[130:131], v[138:139], 0, s[12:13]
	global_load_dwordx4 v[126:129], v[130:131], off
	s_waitcnt vmcnt(12)
	ds_bpermute_b32 v143, v133, v151
	ds_bpermute_b32 v142, v133, v150
	ds_bpermute_b32 v145, v133, v153
	ds_bpermute_b32 v144, v133, v152
	s_waitcnt lgkmcnt(3)
	v_lshlrev_b32_e32 v136, 16, v143
	v_and_b32_e32 v137, 0xffff0000, v143
	s_waitcnt lgkmcnt(2)
	v_and_b32_e32 v143, 0xffff0000, v142
	v_lshlrev_b32_e32 v142, 16, v142
	v_pk_mul_f32 v[136:137], v[136:137], s[96:97] op_sel_hi:[1,0]
	v_pk_fma_f32 v[120:121], v[120:121], 0.5, v[136:137] op_sel_hi:[1,0,1]
	v_pk_mul_f32 v[142:143], v[142:143], s[96:97] op_sel_hi:[1,0]
	v_pk_fma_f32 v[118:119], v[118:119], 0.5, v[142:143] op_sel_hi:[1,0,1]
	s_waitcnt lgkmcnt(1)
	v_lshlrev_b32_e32 v136, 16, v145
	v_and_b32_e32 v137, 0xffff0000, v145
	s_waitcnt lgkmcnt(0)
	v_and_b32_e32 v145, 0xffff0000, v144
	v_lshlrev_b32_e32 v144, 16, v144
	v_pk_mul_f32 v[136:137], v[136:137], s[96:97] op_sel_hi:[1,0]
	v_pk_fma_f32 v[116:117], v[116:117], 0.5, v[136:137] op_sel_hi:[1,0,1]
	v_pk_mul_f32 v[144:145], v[144:145], s[96:97] op_sel_hi:[1,0]
	v_pk_fma_f32 v[114:115], v[114:115], 0.5, v[144:145] op_sel_hi:[1,0,1]
	v_cvt_pk_bf16_f32 v118, v118, v119
	v_cvt_pk_bf16_f32 v119, v120, v121
	v_cvt_pk_bf16_f32 v120, v114, v115
	v_cvt_pk_bf16_f32 v117, v116, v117
	s_nop 1
	ds_bpermute_b32 v114, v132, v118
	ds_bpermute_b32 v115, v132, v119
	ds_bpermute_b32 v116, v132, v120
	ds_bpermute_b32 v117, v132, v117
	s_waitcnt lgkmcnt(0)
	global_store_dwordx4 v[134:135], v[114:117], off offset:256
	global_load_dwordx4 v[118:121], v[130:131], off offset:256
	s_waitcnt vmcnt(13)
	ds_bpermute_b32 v143, v133, v155
	ds_bpermute_b32 v142, v133, v154
	ds_bpermute_b32 v145, v133, v157
	ds_bpermute_b32 v144, v133, v156
	s_mov_b64 s[12:13], 0x8000
	v_lshl_add_u64 v[134:135], v[140:141], 0, s[12:13]
	s_waitcnt lgkmcnt(3)
; #define GAS __attribute__((address_space(1)))
; __device__ __forceinline__ v4u tr4(int a, v4u x) { return (v4u){bperm(a, x.x), bperm(a, x.y), bperm(a, x.z), bperm(a, x.w)}; }
; __device__ __forceinline__ v4u pack8(const f32x4& a, const f32x4& b) { return (v4u){pg8::cvt_pk_bf16(a[0], a[1]), pg8::cvt_pk_bf16(a[2], a[3]), pg8::cvt_pk_bf16(b[0], b[1]), pg8::cvt_pk_bf16(b[2], b[3])}; }
;     __device__ __forceinline__ bool operator()(AccT& acc, const Unit& u, int wr, int wc, int fr, int fq) const {
;     ...
;             for (int m = 0; m < 4; ++m) { const size_t off = (size_t)(row0 + ai * 128 + m * 16) * D + col0;
; #pragma unroll
;                 for (int bj = 0; bj < 2; ++bj) { const v4u r = tr4(t.push, *(const GAS v4u*)(src + off + bj * 128));
;                     const f32x4 y0 = (f32x4){bflo(r.x), bfhi(r.x), bflo(r.y), bfhi(r.y)} * ca + acc[ai][bj][m][0] * cb, y1 = (f32x4){bflo(r.z), bfhi(r.z), bflo(r.w), bfhi(r.w)} * ca + acc[ai][bj][m][1] * cb;
;                     *(GAS v4u*)(dst + off + bj * 128) = tr4(t.pull, pack8(y0, y1)); } }
	v_lshlrev_b32_e32 v136, 16, v143
	v_and_b32_e32 v137, 0xffff0000, v143
	s_waitcnt lgkmcnt(2)
	v_and_b32_e32 v143, 0xffff0000, v142
	v_lshlrev_b32_e32 v142, 16, v142
	v_pk_mul_f32 v[136:137], v[136:137], s[96:97] op_sel_hi:[1,0]
	v_pk_fma_f32 v[112:113], v[112:113], 0.5, v[136:137] op_sel_hi:[1,0,1]
	v_pk_mul_f32 v[142:143], v[142:143], s[96:97] op_sel_hi:[1,0]
	v_pk_fma_f32 v[110:111], v[110:111], 0.5, v[142:143] op_sel_hi:[1,0,1]
	s_waitcnt lgkmcnt(1)
	v_lshlrev_b32_e32 v136, 16, v145
	v_and_b32_e32 v137, 0xffff0000, v145
	s_waitcnt lgkmcnt(0)
	v_and_b32_e32 v145, 0xffff0000, v144
	v_lshlrev_b32_e32 v144, 16, v144
	v_pk_mul_f32 v[136:137], v[136:137], s[96:97] op_sel_hi:[1,0]
	v_pk_fma_f32 v[108:109], v[108:109], 0.5, v[136:137] op_sel_hi:[1,0,1]
	v_pk_mul_f32 v[144:145], v[144:145], s[96:97] op_sel_hi:[1,0]
	v_pk_fma_f32 v[106:107], v[106:107], 0.5, v[144:145] op_sel_hi:[1,0,1]
	v_cvt_pk_bf16_f32 v110, v110, v111
	v_cvt_pk_bf16_f32 v111, v112, v113
	v_cvt_pk_bf16_f32 v112, v106, v107
	v_cvt_pk_bf16_f32 v109, v108, v109
	s_nop 1
	ds_bpermute_b32 v106, v132, v110
	ds_bpermute_b32 v107, v132, v111
	ds_bpermute_b32 v108, v132, v112
	ds_bpermute_b32 v109, v132, v109
	s_waitcnt lgkmcnt(0)
	global_store_dwordx4 v[134:135], v[106:109], off
	s_mov_b64 s[12:13], 0x58000
	v_lshl_add_u64 v[130:131], v[138:139], 0, s[12:13]
	global_load_dwordx4 v[110:113], v[130:131], off
	s_waitcnt vmcnt(14)
	ds_bpermute_b32 v143, v133, v159
	ds_bpermute_b32 v142, v133, v158
	ds_bpermute_b32 v145, v133, v161
	ds_bpermute_b32 v144, v133, v160
	s_waitcnt lgkmcnt(3)
	v_lshlrev_b32_e32 v136, 16, v143
	v_and_b32_e32 v137, 0xffff0000, v143
	s_waitcnt lgkmcnt(2)
	v_and_b32_e32 v143, 0xffff0000, v142
	v_lshlrev_b32_e32 v142, 16, v142
	v_pk_mul_f32 v[136:137], v[136:137], s[96:97] op_sel_hi:[1,0]
	v_pk_fma_f32 v[104:105], v[104:105], 0.5, v[136:137] op_sel_hi:[1,0,1]
	v_pk_mul_f32 v[142:143], v[142:143], s[96:97] op_sel_hi:[1,0]
	v_pk_fma_f32 v[102:103], v[102:103], 0.5, v[142:143] op_sel_hi:[1,0,1]
	s_waitcnt lgkmcnt(1)
	v_lshlrev_b32_e32 v136, 16, v145
	v_and_b32_e32 v137, 0xffff0000, v145
	s_waitcnt lgkmcnt(0)
	v_and_b32_e32 v145, 0xffff0000, v144
	v_lshlrev_b32_e32 v144, 16, v144
	v_pk_mul_f32 v[136:137], v[136:137], s[96:97] op_sel_hi:[1,0]
	v_pk_fma_f32 v[100:101], v[100:101], 0.5, v[136:137] op_sel_hi:[1,0,1]
	v_pk_mul_f32 v[144:145], v[144:145], s[96:97] op_sel_hi:[1,0]
	v_pk_fma_f32 v[98:99], v[98:99], 0.5, v[144:145] op_sel_hi:[1,0,1]
	v_cvt_pk_bf16_f32 v102, v102, v103
	v_cvt_pk_bf16_f32 v103, v104, v105
	v_cvt_pk_bf16_f32 v104, v98, v99
	v_cvt_pk_bf16_f32 v101, v100, v101
	s_nop 1
	ds_bpermute_b32 v98, v132, v102
	ds_bpermute_b32 v99, v132, v103
	ds_bpermute_b32 v100, v132, v104
	ds_bpermute_b32 v101, v132, v101
	s_waitcnt lgkmcnt(0)
	global_store_dwordx4 v[134:135], v[98:101], off offset:256
	global_load_dwordx4 v[102:105], v[130:131], off offset:256
	s_waitcnt vmcnt(15)
	ds_bpermute_b32 v143, v133, v163
	ds_bpermute_b32 v142, v133, v162
	ds_bpermute_b32 v145, v133, v165
	ds_bpermute_b32 v144, v133, v164
	s_mov_b64 s[12:13], 0x10000
	v_lshl_add_u64 v[134:135], v[140:141], 0, s[12:13]
	s_waitcnt lgkmcnt(3)
	v_lshlrev_b32_e32 v136, 16, v143
	v_and_b32_e32 v137, 0xffff0000, v143
	s_waitcnt lgkmcnt(2)
	v_and_b32_e32 v143, 0xffff0000, v142
	v_lshlrev_b32_e32 v142, 16, v142
	v_pk_mul_f32 v[136:137], v[136:137], s[96:97] op_sel_hi:[1,0]
	v_pk_fma_f32 v[96:97], v[96:97], 0.5, v[136:137] op_sel_hi:[1,0,1]
	v_pk_mul_f32 v[142:143], v[142:143], s[96:97] op_sel_hi:[1,0]
	v_pk_fma_f32 v[94:95], v[94:95], 0.5, v[142:143] op_sel_hi:[1,0,1]
	s_waitcnt lgkmcnt(1)
	v_lshlrev_b32_e32 v136, 16, v145
	v_and_b32_e32 v137, 0xffff0000, v145
	s_waitcnt lgkmcnt(0)
	v_and_b32_e32 v145, 0xffff0000, v144
	v_lshlrev_b32_e32 v144, 16, v144
	v_pk_mul_f32 v[136:137], v[136:137], s[96:97] op_sel_hi:[1,0]
	v_pk_fma_f32 v[92:93], v[92:93], 0.5, v[136:137] op_sel_hi:[1,0,1]
	v_pk_mul_f32 v[144:145], v[144:145], s[96:97] op_sel_hi:[1,0]
	v_pk_fma_f32 v[90:91], v[90:91], 0.5, v[144:145] op_sel_hi:[1,0,1]
	v_cvt_pk_bf16_f32 v94, v94, v95
	v_cvt_pk_bf16_f32 v95, v96, v97
	v_cvt_pk_bf16_f32 v96, v90, v91
	v_cvt_pk_bf16_f32 v93, v92, v93
	s_nop 1
	ds_bpermute_b32 v90, v132, v94
	ds_bpermute_b32 v91, v132, v95
	ds_bpermute_b32 v92, v132, v96
	ds_bpermute_b32 v93, v132, v93
	s_waitcnt lgkmcnt(0)
	global_store_dwordx4 v[134:135], v[90:93], off
	s_waitcnt vmcnt(15)
	ds_bpermute_b32 v143, v133, v167
	ds_bpermute_b32 v142, v133, v166
	ds_bpermute_b32 v145, v133, v169
	ds_bpermute_b32 v144, v133, v168
	s_waitcnt lgkmcnt(3)
	v_lshlrev_b32_e32 v136, 16, v143
	v_and_b32_e32 v137, 0xffff0000, v143
	s_waitcnt lgkmcnt(2)
	v_and_b32_e32 v143, 0xffff0000, v142
	v_lshlrev_b32_e32 v142, 16, v142
	v_pk_mul_f32 v[136:137], v[136:137], s[96:97] op_sel_hi:[1,0]
	v_pk_fma_f32 v[88:89], v[88:89], 0.5, v[136:137] op_sel_hi:[1,0,1]
	v_pk_mul_f32 v[142:143], v[142:143], s[96:97] op_sel_hi:[1,0]
	v_pk_fma_f32 v[86:87], v[86:87], 0.5, v[142:143] op_sel_hi:[1,0,1]
	s_waitcnt lgkmcnt(1)
	v_lshlrev_b32_e32 v136, 16, v145
	v_and_b32_e32 v137, 0xffff0000, v145
	s_waitcnt lgkmcnt(0)
	v_and_b32_e32 v145, 0xffff0000, v144
	v_lshlrev_b32_e32 v144, 16, v144
	v_pk_mul_f32 v[136:137], v[136:137], s[96:97] op_sel_hi:[1,0]
	v_pk_fma_f32 v[84:85], v[84:85], 0.5, v[136:137] op_sel_hi:[1,0,1]
	v_pk_mul_f32 v[144:145], v[144:145], s[96:97] op_sel_hi:[1,0]
	v_pk_fma_f32 v[82:83], v[82:83], 0.5, v[144:145] op_sel_hi:[1,0,1]
	v_cvt_pk_bf16_f32 v86, v86, v87
	v_cvt_pk_bf16_f32 v87, v88, v89
	v_cvt_pk_bf16_f32 v88, v82, v83
	v_cvt_pk_bf16_f32 v85, v84, v85
	s_nop 1
	ds_bpermute_b32 v82, v132, v86
	ds_bpermute_b32 v83, v132, v87
	ds_bpermute_b32 v84, v132, v88
	ds_bpermute_b32 v85, v132, v85
	s_waitcnt lgkmcnt(0)
; #define GAS __attribute__((address_space(1)))
; __device__ __forceinline__ v4u tr4(int a, v4u x) { return (v4u){bperm(a, x.x), bperm(a, x.y), bperm(a, x.z), bperm(a, x.w)}; }
; __device__ __forceinline__ v4u pack8(const f32x4& a, const f32x4& b) { return (v4u){pg8::cvt_pk_bf16(a[0], a[1]), pg8::cvt_pk_bf16(a[2], a[3]), pg8::cvt_pk_bf16(b[0], b[1]), pg8::cvt_pk_bf16(b[2], b[3])}; }
;     __device__ __forceinline__ bool operator()(AccT& acc, const Unit& u, int wr, int wc, int fr, int fq) const {
;     ...
;             for (int m = 0; m < 4; ++m) { const size_t off = (size_t)(row0 + ai * 128 + m * 16) * D + col0;
; #pragma unroll
;                 for (int bj = 0; bj < 2; ++bj) { const v4u r = tr4(t.push, *(const GAS v4u*)(src + off + bj * 128));
;                     const f32x4 y0 = (f32x4){bflo(r.x), bfhi(r.x), bflo(r.y), bfhi(r.y)} * ca + acc[ai][bj][m][0] * cb, y1 = (f32x4){bflo(r.z), bfhi(r.z), bflo(r.w), bfhi(r.w)} * ca + acc[ai][bj][m][1] * cb;
;                     *(GAS v4u*)(dst + off + bj * 128) = tr4(t.pull, pack8(y0, y1)); } }
	global_store_dwordx4 v[134:135], v[82:85], off offset:256
	s_waitcnt vmcnt(15)
	ds_bpermute_b32 v143, v133, v171
	ds_bpermute_b32 v142, v133, v170
	ds_bpermute_b32 v145, v133, v173
	ds_bpermute_b32 v144, v133, v172
	s_mov_b64 s[12:13], 0x18000
	v_lshl_add_u64 v[134:135], v[140:141], 0, s[12:13]
	s_waitcnt lgkmcnt(3)
	v_lshlrev_b32_e32 v136, 16, v143
	v_and_b32_e32 v137, 0xffff0000, v143
	s_waitcnt lgkmcnt(2)
	v_and_b32_e32 v143, 0xffff0000, v142
	v_lshlrev_b32_e32 v142, 16, v142
	v_pk_mul_f32 v[136:137], v[136:137], s[96:97] op_sel_hi:[1,0]
	v_pk_fma_f32 v[80:81], v[80:81], 0.5, v[136:137] op_sel_hi:[1,0,1]
	v_pk_mul_f32 v[142:143], v[142:143], s[96:97] op_sel_hi:[1,0]
	v_pk_fma_f32 v[78:79], v[78:79], 0.5, v[142:143] op_sel_hi:[1,0,1]
	s_waitcnt lgkmcnt(1)
	v_lshlrev_b32_e32 v136, 16, v145
	v_and_b32_e32 v137, 0xffff0000, v145
	s_waitcnt lgkmcnt(0)
	v_and_b32_e32 v145, 0xffff0000, v144
	v_lshlrev_b32_e32 v144, 16, v144
	v_pk_mul_f32 v[136:137], v[136:137], s[96:97] op_sel_hi:[1,0]
	v_pk_fma_f32 v[76:77], v[76:77], 0.5, v[136:137] op_sel_hi:[1,0,1]
	v_pk_mul_f32 v[144:145], v[144:145], s[96:97] op_sel_hi:[1,0]
	v_pk_fma_f32 v[74:75], v[74:75], 0.5, v[144:145] op_sel_hi:[1,0,1]
	v_cvt_pk_bf16_f32 v78, v78, v79
	v_cvt_pk_bf16_f32 v79, v80, v81
	v_cvt_pk_bf16_f32 v80, v74, v75
	v_cvt_pk_bf16_f32 v77, v76, v77
	s_nop 1
	ds_bpermute_b32 v74, v132, v78
	ds_bpermute_b32 v75, v132, v79
	ds_bpermute_b32 v76, v132, v80
	ds_bpermute_b32 v77, v132, v77
	s_waitcnt lgkmcnt(0)
	global_store_dwordx4 v[134:135], v[74:77], off
	s_waitcnt vmcnt(15)
	ds_bpermute_b32 v143, v133, v175
	ds_bpermute_b32 v142, v133, v174
	ds_bpermute_b32 v145, v133, v177
	ds_bpermute_b32 v144, v133, v176
	s_waitcnt lgkmcnt(3)
	v_lshlrev_b32_e32 v136, 16, v143
	v_and_b32_e32 v137, 0xffff0000, v143
	s_waitcnt lgkmcnt(2)
	v_and_b32_e32 v143, 0xffff0000, v142
	v_lshlrev_b32_e32 v142, 16, v142
	v_pk_mul_f32 v[136:137], v[136:137], s[96:97] op_sel_hi:[1,0]
	v_pk_fma_f32 v[72:73], v[72:73], 0.5, v[136:137] op_sel_hi:[1,0,1]
	v_pk_mul_f32 v[142:143], v[142:143], s[96:97] op_sel_hi:[1,0]
	v_pk_fma_f32 v[70:71], v[70:71], 0.5, v[142:143] op_sel_hi:[1,0,1]
	s_waitcnt lgkmcnt(1)
	v_lshlrev_b32_e32 v136, 16, v145
	v_and_b32_e32 v137, 0xffff0000, v145
	s_waitcnt lgkmcnt(0)
	v_and_b32_e32 v145, 0xffff0000, v144
	v_lshlrev_b32_e32 v144, 16, v144
	v_pk_mul_f32 v[136:137], v[136:137], s[96:97] op_sel_hi:[1,0]
	v_pk_fma_f32 v[68:69], v[68:69], 0.5, v[136:137] op_sel_hi:[1,0,1]
	v_pk_mul_f32 v[144:145], v[144:145], s[96:97] op_sel_hi:[1,0]
	v_pk_fma_f32 v[66:67], v[66:67], 0.5, v[144:145] op_sel_hi:[1,0,1]
	v_cvt_pk_bf16_f32 v70, v70, v71
	v_cvt_pk_bf16_f32 v71, v72, v73
	v_cvt_pk_bf16_f32 v72, v66, v67
	v_cvt_pk_bf16_f32 v69, v68, v69
	s_nop 1
	ds_bpermute_b32 v66, v132, v70
	ds_bpermute_b32 v67, v132, v71
	ds_bpermute_b32 v68, v132, v72
	ds_bpermute_b32 v69, v132, v69
	s_waitcnt lgkmcnt(0)
	global_store_dwordx4 v[134:135], v[66:69], off offset:256
	s_waitcnt vmcnt(15)
	ds_bpermute_b32 v143, v133, v179
	ds_bpermute_b32 v142, v133, v178
	ds_bpermute_b32 v145, v133, v181
	ds_bpermute_b32 v144, v133, v180
	s_mov_b64 s[12:13], 0x40000
	v_lshl_add_u64 v[134:135], v[140:141], 0, s[12:13]
	s_waitcnt lgkmcnt(3)
	v_lshlrev_b32_e32 v136, 16, v143
	v_and_b32_e32 v137, 0xffff0000, v143
	s_waitcnt lgkmcnt(2)
	v_and_b32_e32 v143, 0xffff0000, v142
	v_lshlrev_b32_e32 v142, 16, v142
	v_pk_mul_f32 v[136:137], v[136:137], s[96:97] op_sel_hi:[1,0]
	v_pk_fma_f32 v[64:65], v[64:65], 0.5, v[136:137] op_sel_hi:[1,0,1]
	v_pk_mul_f32 v[142:143], v[142:143], s[96:97] op_sel_hi:[1,0]
	v_pk_fma_f32 v[62:63], v[62:63], 0.5, v[142:143] op_sel_hi:[1,0,1]
	s_waitcnt lgkmcnt(1)
	v_lshlrev_b32_e32 v136, 16, v145
	v_and_b32_e32 v137, 0xffff0000, v145
	s_waitcnt lgkmcnt(0)
	v_and_b32_e32 v145, 0xffff0000, v144
	v_lshlrev_b32_e32 v144, 16, v144
	v_pk_mul_f32 v[136:137], v[136:137], s[96:97] op_sel_hi:[1,0]
	v_pk_fma_f32 v[60:61], v[60:61], 0.5, v[136:137] op_sel_hi:[1,0,1]
	v_pk_mul_f32 v[144:145], v[144:145], s[96:97] op_sel_hi:[1,0]
	v_pk_fma_f32 v[58:59], v[58:59], 0.5, v[144:145] op_sel_hi:[1,0,1]
	v_cvt_pk_bf16_f32 v62, v62, v63
	v_cvt_pk_bf16_f32 v63, v64, v65
	v_cvt_pk_bf16_f32 v64, v58, v59
	v_cvt_pk_bf16_f32 v61, v60, v61
	s_nop 1
	ds_bpermute_b32 v58, v132, v62
	ds_bpermute_b32 v59, v132, v63
	ds_bpermute_b32 v60, v132, v64
	ds_bpermute_b32 v61, v132, v61
	s_waitcnt lgkmcnt(0)
	global_store_dwordx4 v[134:135], v[58:61], off
	s_waitcnt vmcnt(15)
	ds_bpermute_b32 v143, v133, v183
	ds_bpermute_b32 v142, v133, v182
	ds_bpermute_b32 v145, v133, v185
	ds_bpermute_b32 v144, v133, v184
	s_waitcnt lgkmcnt(3)
	v_lshlrev_b32_e32 v136, 16, v143
	v_and_b32_e32 v137, 0xffff0000, v143
	s_waitcnt lgkmcnt(2)
	v_and_b32_e32 v143, 0xffff0000, v142
	v_lshlrev_b32_e32 v142, 16, v142
	v_pk_mul_f32 v[136:137], v[136:137], s[96:97] op_sel_hi:[1,0]
	v_pk_fma_f32 v[56:57], v[56:57], 0.5, v[136:137] op_sel_hi:[1,0,1]
	v_pk_mul_f32 v[142:143], v[142:143], s[96:97] op_sel_hi:[1,0]
	v_pk_fma_f32 v[54:55], v[54:55], 0.5, v[142:143] op_sel_hi:[1,0,1]
	s_waitcnt lgkmcnt(1)
	v_lshlrev_b32_e32 v136, 16, v145
	v_and_b32_e32 v137, 0xffff0000, v145
	s_waitcnt lgkmcnt(0)
	v_and_b32_e32 v145, 0xffff0000, v144
	v_lshlrev_b32_e32 v144, 16, v144
	v_pk_mul_f32 v[136:137], v[136:137], s[96:97] op_sel_hi:[1,0]
	v_pk_fma_f32 v[52:53], v[52:53], 0.5, v[136:137] op_sel_hi:[1,0,1]
	v_pk_mul_f32 v[144:145], v[144:145], s[96:97] op_sel_hi:[1,0]
	v_pk_fma_f32 v[50:51], v[50:51], 0.5, v[144:145] op_sel_hi:[1,0,1]
	v_cvt_pk_bf16_f32 v54, v54, v55
	v_cvt_pk_bf16_f32 v55, v56, v57
	v_cvt_pk_bf16_f32 v56, v50, v51
	v_cvt_pk_bf16_f32 v53, v52, v53
	s_nop 1
	ds_bpermute_b32 v50, v132, v54
	ds_bpermute_b32 v51, v132, v55
	ds_bpermute_b32 v52, v132, v56
	ds_bpermute_b32 v53, v132, v53
	s_waitcnt lgkmcnt(0)
; #define GAS __attribute__((address_space(1)))
; __device__ __forceinline__ v4u tr4(int a, v4u x) { return (v4u){bperm(a, x.x), bperm(a, x.y), bperm(a, x.z), bperm(a, x.w)}; }
; __device__ __forceinline__ v4u pack8(const f32x4& a, const f32x4& b) { return (v4u){pg8::cvt_pk_bf16(a[0], a[1]), pg8::cvt_pk_bf16(a[2], a[3]), pg8::cvt_pk_bf16(b[0], b[1]), pg8::cvt_pk_bf16(b[2], b[3])}; }
;     __device__ __forceinline__ bool operator()(AccT& acc, const Unit& u, int wr, int wc, int fr, int fq) const {
;     ...
;             for (int m = 0; m < 4; ++m) { const size_t off = (size_t)(row0 + ai * 128 + m * 16) * D + col0;
; #pragma unroll
;                 for (int bj = 0; bj < 2; ++bj) { const v4u r = tr4(t.push, *(const GAS v4u*)(src + off + bj * 128));
;                     const f32x4 y0 = (f32x4){bflo(r.x), bfhi(r.x), bflo(r.y), bfhi(r.y)} * ca + acc[ai][bj][m][0] * cb, y1 = (f32x4){bflo(r.z), bfhi(r.z), bflo(r.w), bfhi(r.w)} * ca + acc[ai][bj][m][1] * cb;
;                     *(GAS v4u*)(dst + off + bj * 128) = tr4(t.pull, pack8(y0, y1)); } }
	global_store_dwordx4 v[134:135], v[50:53], off offset:256
	s_waitcnt vmcnt(15)
	ds_bpermute_b32 v143, v133, v187
	ds_bpermute_b32 v142, v133, v186
	ds_bpermute_b32 v145, v133, v189
	ds_bpermute_b32 v144, v133, v188
	s_mov_b64 s[12:13], 0x48000
	v_lshl_add_u64 v[134:135], v[140:141], 0, s[12:13]
	s_waitcnt lgkmcnt(3)
	v_lshlrev_b32_e32 v136, 16, v143
	v_and_b32_e32 v137, 0xffff0000, v143
	s_waitcnt lgkmcnt(2)
	v_and_b32_e32 v143, 0xffff0000, v142
	v_lshlrev_b32_e32 v142, 16, v142
	v_pk_mul_f32 v[136:137], v[136:137], s[96:97] op_sel_hi:[1,0]
	v_pk_fma_f32 v[48:49], v[48:49], 0.5, v[136:137] op_sel_hi:[1,0,1]
	v_pk_mul_f32 v[142:143], v[142:143], s[96:97] op_sel_hi:[1,0]
	v_pk_fma_f32 v[46:47], v[46:47], 0.5, v[142:143] op_sel_hi:[1,0,1]
	s_waitcnt lgkmcnt(1)
	v_lshlrev_b32_e32 v136, 16, v145
	v_and_b32_e32 v137, 0xffff0000, v145
	s_waitcnt lgkmcnt(0)
	v_and_b32_e32 v145, 0xffff0000, v144
	v_lshlrev_b32_e32 v144, 16, v144
	v_pk_mul_f32 v[136:137], v[136:137], s[96:97] op_sel_hi:[1,0]
	v_pk_fma_f32 v[44:45], v[44:45], 0.5, v[136:137] op_sel_hi:[1,0,1]
	v_pk_mul_f32 v[144:145], v[144:145], s[96:97] op_sel_hi:[1,0]
	v_pk_fma_f32 v[42:43], v[42:43], 0.5, v[144:145] op_sel_hi:[1,0,1]
	v_cvt_pk_bf16_f32 v46, v46, v47
	v_cvt_pk_bf16_f32 v47, v48, v49
	v_cvt_pk_bf16_f32 v48, v42, v43
	v_cvt_pk_bf16_f32 v45, v44, v45
	s_nop 1
	ds_bpermute_b32 v42, v132, v46
	ds_bpermute_b32 v43, v132, v47
	ds_bpermute_b32 v44, v132, v48
	ds_bpermute_b32 v45, v132, v45
	s_waitcnt lgkmcnt(0)
	global_store_dwordx4 v[134:135], v[42:45], off
	s_waitcnt vmcnt(15)
	ds_bpermute_b32 v143, v133, v191
	ds_bpermute_b32 v142, v133, v190
	ds_bpermute_b32 v145, v133, v193
	ds_bpermute_b32 v144, v133, v192
	s_waitcnt lgkmcnt(3)
	v_lshlrev_b32_e32 v136, 16, v143
	v_and_b32_e32 v137, 0xffff0000, v143
	s_waitcnt lgkmcnt(2)
	v_and_b32_e32 v143, 0xffff0000, v142
	v_lshlrev_b32_e32 v142, 16, v142
	v_pk_mul_f32 v[136:137], v[136:137], s[96:97] op_sel_hi:[1,0]
	v_pk_fma_f32 v[40:41], v[40:41], 0.5, v[136:137] op_sel_hi:[1,0,1]
	v_pk_mul_f32 v[142:143], v[142:143], s[96:97] op_sel_hi:[1,0]
	v_pk_fma_f32 v[38:39], v[38:39], 0.5, v[142:143] op_sel_hi:[1,0,1]
	s_waitcnt lgkmcnt(1)
	v_lshlrev_b32_e32 v136, 16, v145
	v_and_b32_e32 v137, 0xffff0000, v145
	s_waitcnt lgkmcnt(0)
	v_and_b32_e32 v145, 0xffff0000, v144
	v_lshlrev_b32_e32 v144, 16, v144
	v_pk_mul_f32 v[136:137], v[136:137], s[96:97] op_sel_hi:[1,0]
	v_pk_fma_f32 v[36:37], v[36:37], 0.5, v[136:137] op_sel_hi:[1,0,1]
	v_pk_mul_f32 v[144:145], v[144:145], s[96:97] op_sel_hi:[1,0]
	v_pk_fma_f32 v[34:35], v[34:35], 0.5, v[144:145] op_sel_hi:[1,0,1]
	v_cvt_pk_bf16_f32 v38, v38, v39
	v_cvt_pk_bf16_f32 v39, v40, v41
	v_cvt_pk_bf16_f32 v40, v34, v35
	v_cvt_pk_bf16_f32 v37, v36, v37
	s_nop 1
	ds_bpermute_b32 v34, v132, v38
	ds_bpermute_b32 v35, v132, v39
	ds_bpermute_b32 v36, v132, v40
	ds_bpermute_b32 v37, v132, v37
	s_waitcnt lgkmcnt(0)
	global_store_dwordx4 v[134:135], v[34:37], off offset:256
	s_waitcnt vmcnt(14)
	ds_bpermute_b32 v143, v133, v127
	ds_bpermute_b32 v142, v133, v126
	ds_bpermute_b32 v145, v133, v129
	ds_bpermute_b32 v144, v133, v128
	s_mov_b64 s[12:13], 0x50000
	v_lshl_add_u64 v[134:135], v[140:141], 0, s[12:13]
	s_waitcnt lgkmcnt(3)
	v_lshlrev_b32_e32 v136, 16, v143
	v_and_b32_e32 v137, 0xffff0000, v143
	s_waitcnt lgkmcnt(2)
	v_and_b32_e32 v143, 0xffff0000, v142
	v_lshlrev_b32_e32 v142, 16, v142
	v_pk_mul_f32 v[136:137], v[136:137], s[96:97] op_sel_hi:[1,0]
	v_pk_fma_f32 v[32:33], v[32:33], 0.5, v[136:137] op_sel_hi:[1,0,1]
	v_pk_mul_f32 v[142:143], v[142:143], s[96:97] op_sel_hi:[1,0]
	v_pk_fma_f32 v[30:31], v[30:31], 0.5, v[142:143] op_sel_hi:[1,0,1]
	s_waitcnt lgkmcnt(1)
	v_lshlrev_b32_e32 v136, 16, v145
	v_and_b32_e32 v137, 0xffff0000, v145
	s_waitcnt lgkmcnt(0)
	v_and_b32_e32 v145, 0xffff0000, v144
	v_lshlrev_b32_e32 v144, 16, v144
	v_pk_mul_f32 v[136:137], v[136:137], s[96:97] op_sel_hi:[1,0]
	v_pk_fma_f32 v[28:29], v[28:29], 0.5, v[136:137] op_sel_hi:[1,0,1]
	v_pk_mul_f32 v[144:145], v[144:145], s[96:97] op_sel_hi:[1,0]
	v_pk_fma_f32 v[26:27], v[26:27], 0.5, v[144:145] op_sel_hi:[1,0,1]
	v_cvt_pk_bf16_f32 v30, v30, v31
	v_cvt_pk_bf16_f32 v31, v32, v33
	v_cvt_pk_bf16_f32 v32, v26, v27
	v_cvt_pk_bf16_f32 v29, v28, v29
	s_nop 1
	ds_bpermute_b32 v26, v132, v30
	ds_bpermute_b32 v27, v132, v31
	ds_bpermute_b32 v28, v132, v32
	ds_bpermute_b32 v29, v132, v29
	s_waitcnt lgkmcnt(0)
; #define PG8_BAR __builtin_amdgcn_s_barrier()
; #define GAS __attribute__((address_space(1)))
; __device__ __forceinline__ v4u tr4(int a, v4u x) { return (v4u){bperm(a, x.x), bperm(a, x.y), bperm(a, x.z), bperm(a, x.w)}; }
; __device__ __forceinline__ v4u pack8(const f32x4& a, const f32x4& b) { return (v4u){pg8::cvt_pk_bf16(a[0], a[1]), pg8::cvt_pk_bf16(a[2], a[3]), pg8::cvt_pk_bf16(b[0], b[1]), pg8::cvt_pk_bf16(b[2], b[3])}; }
; template <class Epi, class Sched, bool ALIGN_EPI = false, bool SP2 = false>
; __device__ __forceinline__ void gemm_phase(PG8_LAS unsigned char* lds, const Gemm g, const Sched& S, const Epi& E, const int wave_id) {
;     ...
;         if (!has_next) break;
;         if (!keep_acc) {
; #pragma unroll
;         for (int a = 0; a < 2; ++a)
; #pragma unroll
;             for (int b = 0; b < 2; ++b)
; #pragma unroll
;                 for (int m = 0; m < 4; ++m)
; #pragma unroll
;                     for (int n = 0; n < 2; ++n) acc[a][b][m][n] = (f32x4){0.f, 0.f, 0.f, 0.f};
;         }
;         cur = nxt; cA = nA; cB = nB; ++ui;
;         if constexpr (ALIGN_EPI) { if (wr == 1) PG8_BAR; }
;     __device__ __forceinline__ bool operator()(AccT& acc, const Unit& u, int wr, int wc, int fr, int fq) const {
;     ...
;             for (int m = 0; m < 4; ++m) { const size_t off = (size_t)(row0 + ai * 128 + m * 16) * D + col0;
; #pragma unroll
;                 for (int bj = 0; bj < 2; ++bj) { const v4u r = tr4(t.push, *(const GAS v4u*)(src + off + bj * 128));
;                     const f32x4 y0 = (f32x4){bflo(r.x), bfhi(r.x), bflo(r.y), bfhi(r.y)} * ca + acc[ai][bj][m][0] * cb, y1 = (f32x4){bflo(r.z), bfhi(r.z), bflo(r.w), bfhi(r.w)} * ca + acc[ai][bj][m][1] * cb;
;                     *(GAS v4u*)(dst + off + bj * 128) = tr4(t.pull, pack8(y0, y1)); } }
	global_store_dwordx4 v[134:135], v[26:29], off
	s_waitcnt vmcnt(13)
	ds_bpermute_b32 v143, v133, v119
	ds_bpermute_b32 v142, v133, v118
	ds_bpermute_b32 v145, v133, v121
	ds_bpermute_b32 v144, v133, v120
	s_waitcnt lgkmcnt(3)
	v_lshlrev_b32_e32 v136, 16, v143
	v_and_b32_e32 v137, 0xffff0000, v143
	s_waitcnt lgkmcnt(2)
	v_and_b32_e32 v143, 0xffff0000, v142
	v_lshlrev_b32_e32 v142, 16, v142
	v_pk_mul_f32 v[136:137], v[136:137], s[96:97] op_sel_hi:[1,0]
	v_pk_fma_f32 v[24:25], v[24:25], 0.5, v[136:137] op_sel_hi:[1,0,1]
	v_pk_mul_f32 v[142:143], v[142:143], s[96:97] op_sel_hi:[1,0]
	v_pk_fma_f32 v[22:23], v[22:23], 0.5, v[142:143] op_sel_hi:[1,0,1]
	s_waitcnt lgkmcnt(1)
	v_lshlrev_b32_e32 v136, 16, v145
	v_and_b32_e32 v137, 0xffff0000, v145
	s_waitcnt lgkmcnt(0)
	v_and_b32_e32 v145, 0xffff0000, v144
	v_lshlrev_b32_e32 v144, 16, v144
	v_pk_mul_f32 v[136:137], v[136:137], s[96:97] op_sel_hi:[1,0]
	v_pk_fma_f32 v[20:21], v[20:21], 0.5, v[136:137] op_sel_hi:[1,0,1]
	v_pk_mul_f32 v[144:145], v[144:145], s[96:97] op_sel_hi:[1,0]
	v_pk_fma_f32 v[18:19], v[18:19], 0.5, v[144:145] op_sel_hi:[1,0,1]
	v_cvt_pk_bf16_f32 v22, v22, v23
	v_cvt_pk_bf16_f32 v23, v24, v25
	v_cvt_pk_bf16_f32 v24, v18, v19
	v_cvt_pk_bf16_f32 v21, v20, v21
	s_nop 1
	ds_bpermute_b32 v18, v132, v22
	ds_bpermute_b32 v19, v132, v23
	ds_bpermute_b32 v20, v132, v24
	ds_bpermute_b32 v21, v132, v21
	s_waitcnt lgkmcnt(0)
	global_store_dwordx4 v[134:135], v[18:21], off offset:256
	s_waitcnt vmcnt(12)
	ds_bpermute_b32 v143, v133, v111
	ds_bpermute_b32 v142, v133, v110
	ds_bpermute_b32 v145, v133, v113
	ds_bpermute_b32 v144, v133, v112
	s_mov_b64 s[12:13], 0x58000
	v_lshl_add_u64 v[134:135], v[140:141], 0, s[12:13]
	s_waitcnt lgkmcnt(3)
	v_lshlrev_b32_e32 v136, 16, v143
	v_and_b32_e32 v137, 0xffff0000, v143
	s_waitcnt lgkmcnt(2)
	v_and_b32_e32 v143, 0xffff0000, v142
	v_lshlrev_b32_e32 v142, 16, v142
	v_pk_mul_f32 v[136:137], v[136:137], s[96:97] op_sel_hi:[1,0]
	v_pk_fma_f32 v[16:17], v[16:17], 0.5, v[136:137] op_sel_hi:[1,0,1]
	v_pk_mul_f32 v[142:143], v[142:143], s[96:97] op_sel_hi:[1,0]
	v_pk_fma_f32 v[14:15], v[14:15], 0.5, v[142:143] op_sel_hi:[1,0,1]
	s_waitcnt lgkmcnt(1)
	v_lshlrev_b32_e32 v136, 16, v145
	v_and_b32_e32 v137, 0xffff0000, v145
	s_waitcnt lgkmcnt(0)
	v_and_b32_e32 v145, 0xffff0000, v144
	v_lshlrev_b32_e32 v144, 16, v144
	v_pk_mul_f32 v[136:137], v[136:137], s[96:97] op_sel_hi:[1,0]
	v_pk_fma_f32 v[12:13], v[12:13], 0.5, v[136:137] op_sel_hi:[1,0,1]
	v_pk_mul_f32 v[144:145], v[144:145], s[96:97] op_sel_hi:[1,0]
	v_pk_fma_f32 v[10:11], v[10:11], 0.5, v[144:145] op_sel_hi:[1,0,1]
	v_cvt_pk_bf16_f32 v14, v14, v15
	v_cvt_pk_bf16_f32 v15, v16, v17
	v_cvt_pk_bf16_f32 v16, v10, v11
	v_cvt_pk_bf16_f32 v13, v12, v13
	s_nop 1
	ds_bpermute_b32 v10, v132, v14
	ds_bpermute_b32 v11, v132, v15
	ds_bpermute_b32 v12, v132, v16
	ds_bpermute_b32 v13, v132, v13
	s_waitcnt lgkmcnt(0)
	global_store_dwordx4 v[134:135], v[10:13], off
	s_waitcnt vmcnt(11)
	ds_bpermute_b32 v143, v133, v103
	ds_bpermute_b32 v142, v133, v102
	ds_bpermute_b32 v145, v133, v105
	ds_bpermute_b32 v144, v133, v104
	s_waitcnt lgkmcnt(3)
	v_lshlrev_b32_e32 v136, 16, v143
	v_and_b32_e32 v137, 0xffff0000, v143
	s_waitcnt lgkmcnt(2)
	v_and_b32_e32 v143, 0xffff0000, v142
	v_lshlrev_b32_e32 v142, 16, v142
	v_pk_mul_f32 v[136:137], v[136:137], s[96:97] op_sel_hi:[1,0]
	v_pk_fma_f32 v[8:9], v[8:9], 0.5, v[136:137] op_sel_hi:[1,0,1]
	v_pk_mul_f32 v[142:143], v[142:143], s[96:97] op_sel_hi:[1,0]
	v_pk_fma_f32 v[6:7], v[6:7], 0.5, v[142:143] op_sel_hi:[1,0,1]
	s_waitcnt lgkmcnt(1)
	v_lshlrev_b32_e32 v136, 16, v145
	v_and_b32_e32 v137, 0xffff0000, v145
	s_waitcnt lgkmcnt(0)
	v_and_b32_e32 v145, 0xffff0000, v144
	v_lshlrev_b32_e32 v144, 16, v144
	v_pk_mul_f32 v[136:137], v[136:137], s[96:97] op_sel_hi:[1,0]
	v_pk_fma_f32 v[4:5], v[4:5], 0.5, v[136:137] op_sel_hi:[1,0,1]
	v_pk_mul_f32 v[144:145], v[144:145], s[96:97] op_sel_hi:[1,0]
	v_pk_fma_f32 v[2:3], v[2:3], 0.5, v[144:145] op_sel_hi:[1,0,1]
	v_cvt_pk_bf16_f32 v6, v6, v7
	v_cvt_pk_bf16_f32 v7, v8, v9
	v_cvt_pk_bf16_f32 v8, v2, v3
	v_cvt_pk_bf16_f32 v5, v4, v5
	s_nop 1
	ds_bpermute_b32 v2, v132, v6
	ds_bpermute_b32 v3, v132, v7
	ds_bpermute_b32 v4, v132, v8
	ds_bpermute_b32 v5, v132, v5
	s_waitcnt lgkmcnt(0)
	global_store_dwordx4 v[134:135], v[2:5], off offset:256
	s_mov_b64 s[12:13], -1
	s_cbranch_vccnz .LBB0_223
	s_andn2_b64 vcc, exec, s[2:3]
	s_cbranch_vccnz .LBB0_222
	s_barrier
	s_branch .LBB0_222

; #define PG8_STAGE(bufoff, gbase, voff) do { _Pragma("unroll") for (int _i = 0; _i < 2; ++_i) \
;         __builtin_amdgcn_global_load_lds((const unsigned*)((const char*)(gbase) + (voff)[_i]), (PG8_LAS unsigned*)(lds + (bufoff) + ldsw + _i * 8192), 16, 0, 0); } while (0)
; #define PG8_LDA(dst, b, h) do { _Pragma("unroll") for (int m = 0; m < 4; ++m) _Pragma("unroll") for (int k = 0; k < 2; ++k) dst[m][k] = *(const PG8_LAS bf16x8*)(lds + PG8_SA(b, h) + aoff + m * 2048 + k * 1024); } while (0)
; #define PG8_LDB(dst, b, h) do { _Pragma("unroll") for (int n = 0; n < 2; ++n) _Pragma("unroll") for (int k = 0; k < 2; ++k) dst[n][k] = *(const PG8_LAS bf16x8*)(lds + PG8_SB(b, h) + boff + n * 2048 + k * 1024); } while (0)
; #define PG8_MMA(ai, bj, At, Bt) do { __builtin_amdgcn_s_setprio(1); _Pragma("unroll") for (int m = 0; m < 4; ++m) _Pragma("unroll") for (int n = 0; n < 2; ++n) _Pragma("unroll") for (int k = 0; k < 2; ++k) \
;         acc[ai][bj][m][n] = __builtin_amdgcn_mfma_f32_16x16x32_bf16(Bt[n][k], At[m][k], acc[ai][bj][m][n], 0, 0, 0); __builtin_amdgcn_s_setprio(0); } while (0)
; #define PG8_WAIT_V(n) asm volatile("s_waitcnt vmcnt(" #n ")" ::: "memory")
; #define PG8_WAIT_VN(n) asm volatile("s_waitcnt vmcnt(%0)" :: "n"(n) : "memory")
; #define PG8_WAIT_L(n) asm volatile("s_waitcnt lgkmcnt(" #n ")" ::: "memory")
; #define PG8_BAR __builtin_amdgcn_s_barrier()
; #define PG8_SCHED __builtin_amdgcn_sched_barrier(0)
; template <class Epi, class Sched, bool ALIGN_EPI = false, bool SP2 = false>
; __device__ __forceinline__ void gemm_phase(PG8_LAS unsigned char* lds, const Gemm g, const Sched& S, const Epi& E, const int wave_id) {
;     ...
;             PG8_WAIT_VN(8 + Epi::NS); if (strict) PG8_WAIT_V(8); PG8_WAIT_L(0); PG8_BAR; PG8_MMA(1, 0, At, B0); PG8_MMA(1, 1, At, B1); PG8_BAR; PG8_SCHED;
;             PG8_LDB(B0, 1, 0); PG8_LDB(B1, 1, 1); PG8_SCHED; PG8_LDA(At, 1, 0); PG8_STAGE(PG8_SA(0, 1), a2 + hstep, voffA);
;             PG8_WAIT_V(8); PG8_WAIT_L(0); PG8_BAR; PG8_MMA(0, 0, At, B0); PG8_MMA(0, 1, At, B1); PG8_BAR; PG8_SCHED;
.LBB0_420:
	s_waitcnt lgkmcnt(0)
	s_barrier
	s_setprio 1
	s_waitcnt lgkmcnt(0)
	v_mfma_f32_16x16x32_bf16 v[62:65], v[146:149], v[186:189], v[62:65]
	v_mfma_f32_16x16x32_bf16 v[58:61], v[154:157], v[186:189], v[58:61]
	v_mfma_f32_16x16x32_bf16 v[46:49], v[146:149], v[178:181], v[46:49]
	v_mfma_f32_16x16x32_bf16 v[42:45], v[154:157], v[178:181], v[42:45]
	v_mfma_f32_16x16x32_bf16 v[30:33], v[146:149], v[170:173], v[30:33]
	v_mfma_f32_16x16x32_bf16 v[26:29], v[154:157], v[170:173], v[26:29]
	v_mfma_f32_16x16x32_bf16 v[14:17], v[146:149], v[162:165], v[14:17]
	v_mfma_f32_16x16x32_bf16 v[10:13], v[154:157], v[162:165], v[10:13]
	v_mfma_f32_16x16x32_bf16 v[62:65], v[150:153], v[190:193], v[62:65]
	v_mfma_f32_16x16x32_bf16 v[58:61], v[158:161], v[190:193], v[58:61]
	v_mfma_f32_16x16x32_bf16 v[46:49], v[150:153], v[182:185], v[46:49]
	v_mfma_f32_16x16x32_bf16 v[42:45], v[158:161], v[182:185], v[42:45]
	v_mfma_f32_16x16x32_bf16 v[30:33], v[150:153], v[174:177], v[30:33]
	v_mfma_f32_16x16x32_bf16 v[26:29], v[158:161], v[174:177], v[26:29]
	v_mfma_f32_16x16x32_bf16 v[14:17], v[150:153], v[166:169], v[14:17]
	v_mfma_f32_16x16x32_bf16 v[10:13], v[158:161], v[166:169], v[10:13]
	s_setprio 0
	s_setprio 1
	v_mfma_f32_16x16x32_bf16 v[54:57], v[130:133], v[186:189], v[54:57]
	v_mfma_f32_16x16x32_bf16 v[50:53], v[138:141], v[186:189], v[50:53]
	v_mfma_f32_16x16x32_bf16 v[38:41], v[130:133], v[178:181], v[38:41]
	v_mfma_f32_16x16x32_bf16 v[34:37], v[138:141], v[178:181], v[34:37]
	v_mfma_f32_16x16x32_bf16 v[22:25], v[130:133], v[170:173], v[22:25]
	v_mfma_f32_16x16x32_bf16 v[18:21], v[138:141], v[170:173], v[18:21]
	v_mfma_f32_16x16x32_bf16 v[6:9], v[130:133], v[162:165], v[6:9]
	v_mfma_f32_16x16x32_bf16 v[2:5], v[138:141], v[162:165], v[2:5]
	v_mfma_f32_16x16x32_bf16 v[54:57], v[134:137], v[190:193], v[54:57]
	v_mfma_f32_16x16x32_bf16 v[50:53], v[142:145], v[190:193], v[50:53]
	v_mfma_f32_16x16x32_bf16 v[38:41], v[134:137], v[182:185], v[38:41]
	v_mfma_f32_16x16x32_bf16 v[34:37], v[142:145], v[182:185], v[34:37]
	v_mfma_f32_16x16x32_bf16 v[22:25], v[134:137], v[174:177], v[22:25]
	v_mfma_f32_16x16x32_bf16 v[18:21], v[142:145], v[174:177], v[18:21]
	v_mfma_f32_16x16x32_bf16 v[6:9], v[134:137], v[166:169], v[6:9]
	v_mfma_f32_16x16x32_bf16 v[2:5], v[142:145], v[166:169], v[2:5]
	s_setprio 0
	s_barrier
	s_add_i32 s34, 0, 0x18000
	s_add_i32 s35, 0, 0x1c000
	v_add_u32_e32 v142, s34, v246
	v_add_u32_e32 v158, s35, v246
	ds_read_b128 v[130:133], v142
	ds_read_b128 v[134:137], v142 offset:1024
	ds_read_b128 v[138:141], v142 offset:2048
	ds_read_b128 v[142:145], v142 offset:3072
	ds_read_b128 v[146:149], v158
	ds_read_b128 v[150:153], v158 offset:1024
	ds_read_b128 v[154:157], v158 offset:2048
	ds_read_b128 v[158:161], v158 offset:3072
	s_add_u32 s14, s14, 0x40000
	s_addc_u32 s15, s15, 0
	s_mov_b32 m0, s3
	v_lshl_add_u64 v[194:195], s[14:15], 0, v[210:211]
	ds_read_b128 v[162:165], v247 offset:32768
	ds_read_b128 v[166:169], v247 offset:33792
	ds_read_b128 v[170:173], v247 offset:34816
	ds_read_b128 v[174:177], v247 offset:35840
	ds_read_b128 v[178:181], v247 offset:36864
	ds_read_b128 v[182:185], v247 offset:37888
	ds_read_b128 v[186:189], v247 offset:38912
	ds_read_b128 v[190:193], v247 offset:39936
	global_load_lds_dwordx4 v[194:195], off
	v_lshl_add_u64 v[194:195], s[14:15], 0, v[214:215]
	s_mov_b32 m0, s4
	s_nop 0
	global_load_lds_dwordx4 v[194:195], off
	s_waitcnt vmcnt(26)
	s_cmp_eq_u32 s100, 0
	s_cbranch_scc1 .Lthird_wait_relaxed_4
	s_waitcnt vmcnt(8)
.Lthird_wait_relaxed_4:
	s_waitcnt lgkmcnt(0)
	s_barrier
	s_setprio 1
	s_waitcnt lgkmcnt(0)
	v_mfma_f32_16x16x32_bf16 v[126:129], v[130:133], v[162:165], v[126:129]
	v_mfma_f32_16x16x32_bf16 v[122:125], v[138:141], v[162:165], v[122:125]
	v_mfma_f32_16x16x32_bf16 v[110:113], v[130:133], v[170:173], v[110:113]
	v_mfma_f32_16x16x32_bf16 v[106:109], v[138:141], v[170:173], v[106:109]
	v_mfma_f32_16x16x32_bf16 v[94:97], v[130:133], v[178:181], v[94:97]
	v_mfma_f32_16x16x32_bf16 v[90:93], v[138:141], v[178:181], v[90:93]
	v_mfma_f32_16x16x32_bf16 v[78:81], v[130:133], v[186:189], v[78:81]
	v_mfma_f32_16x16x32_bf16 v[74:77], v[138:141], v[186:189], v[74:77]
	v_mfma_f32_16x16x32_bf16 v[126:129], v[134:137], v[166:169], v[126:129]
	v_mfma_f32_16x16x32_bf16 v[122:125], v[142:145], v[166:169], v[122:125]
	v_mfma_f32_16x16x32_bf16 v[110:113], v[134:137], v[174:177], v[110:113]
	v_mfma_f32_16x16x32_bf16 v[106:109], v[142:145], v[174:177], v[106:109]
	v_mfma_f32_16x16x32_bf16 v[94:97], v[134:137], v[182:185], v[94:97]
	v_mfma_f32_16x16x32_bf16 v[90:93], v[142:145], v[182:185], v[90:93]
	v_mfma_f32_16x16x32_bf16 v[78:81], v[134:137], v[190:193], v[78:81]
	v_mfma_f32_16x16x32_bf16 v[74:77], v[142:145], v[190:193], v[74:77]
	s_setprio 0
	s_setprio 1
	v_mfma_f32_16x16x32_bf16 v[118:121], v[146:149], v[162:165], v[118:121]
	v_mfma_f32_16x16x32_bf16 v[114:117], v[154:157], v[162:165], v[114:117]
	v_mfma_f32_16x16x32_bf16 v[102:105], v[146:149], v[170:173], v[102:105]
	v_mfma_f32_16x16x32_bf16 v[98:101], v[154:157], v[170:173], v[98:101]
	v_mfma_f32_16x16x32_bf16 v[86:89], v[146:149], v[178:181], v[86:89]
	v_mfma_f32_16x16x32_bf16 v[82:85], v[154:157], v[178:181], v[82:85]
	v_mfma_f32_16x16x32_bf16 v[70:73], v[146:149], v[186:189], v[70:73]
	v_mfma_f32_16x16x32_bf16 v[66:69], v[154:157], v[186:189], v[66:69]
	v_mfma_f32_16x16x32_bf16 v[118:121], v[150:153], v[166:169], v[118:121]
	v_mfma_f32_16x16x32_bf16 v[114:117], v[158:161], v[166:169], v[114:117]
	v_mfma_f32_16x16x32_bf16 v[102:105], v[150:153], v[174:177], v[102:105]
	v_mfma_f32_16x16x32_bf16 v[98:101], v[158:161], v[174:177], v[98:101]
	v_mfma_f32_16x16x32_bf16 v[86:89], v[150:153], v[182:185], v[86:89]
	v_mfma_f32_16x16x32_bf16 v[82:85], v[158:161], v[182:185], v[82:85]
	v_mfma_f32_16x16x32_bf16 v[70:73], v[150:153], v[190:193], v[70:73]
	v_mfma_f32_16x16x32_bf16 v[66:69], v[158:161], v[190:193], v[66:69]
	s_setprio 0
	s_barrier
; #define PG8_STAGE(bufoff, gbase, voff) do { _Pragma("unroll") for (int _i = 0; _i < 2; ++_i) \
;         __builtin_amdgcn_global_load_lds((const unsigned*)((const char*)(gbase) + (voff)[_i]), (PG8_LAS unsigned*)(lds + (bufoff) + ldsw + _i * 8192), 16, 0, 0); } while (0)
; #define PG8_LDA(dst, b, h) do { _Pragma("unroll") for (int m = 0; m < 4; ++m) _Pragma("unroll") for (int k = 0; k < 2; ++k) dst[m][k] = *(const PG8_LAS bf16x8*)(lds + PG8_SA(b, h) + aoff + m * 2048 + k * 1024); } while (0)
; #define PG8_LDB(dst, b, h) do { _Pragma("unroll") for (int n = 0; n < 2; ++n) _Pragma("unroll") for (int k = 0; k < 2; ++k) dst[n][k] = *(const PG8_LAS bf16x8*)(lds + PG8_SB(b, h) + boff + n * 2048 + k * 1024); } while (0)
; #define PG8_WAIT_V(n) asm volatile("s_waitcnt vmcnt(" #n ")" ::: "memory")
; #define PG8_WAIT_VN(n) asm volatile("s_waitcnt vmcnt(%0)" :: "n"(n) : "memory")
; template <class Epi, class Sched, bool ALIGN_EPI = false, bool SP2 = false>
; __device__ __forceinline__ void gemm_phase(PG8_LAS unsigned char* lds, const Gemm g, const Sched& S, const Epi& E, const int wave_id) {
;     ...
;             int tz_ = __builtin_amdgcn_readfirstlane(t | (ui > 0 ? 0 : 1)); asm volatile("" : "+s"(tz_));
;             const bool strict = !(Epi::NS > 0 && tz_ == 0);
;             PG8_LDB(B0, 0, 0); PG8_LDB(B1, 0, 1); PG8_SCHED; PG8_LDA(At, 0, 0); PG8_STAGE(PG8_SA(1, 1), a1 + hstep, voffA);
;             PG8_WAIT_VN(8 + Epi::NS); if (strict) PG8_WAIT_V(8); PG8_WAIT_L(0); PG8_BAR; PG8_MMA(0, 0, At, B0); PG8_MMA(0, 1, At, B1); PG8_BAR; PG8_SCHED;
;             PG8_LDA(At, 0, 1); PG8_STAGE(PG8_SB(0, 0), b2, voffB); PG8_STAGE(PG8_SB(0, 1), b2 + hstep, voffB); PG8_STAGE(PG8_SA(0, 0), a2, voffA);
;             PG8_WAIT_VN(8 + Epi::NS); if (strict) PG8_WAIT_V(8); PG8_WAIT_L(0); PG8_BAR; PG8_MMA(1, 0, At, B0); PG8_MMA(1, 1, At, B1); PG8_BAR; PG8_SCHED;
;             PG8_LDB(B0, 1, 0); PG8_LDB(B1, 1, 1); PG8_SCHED; PG8_LDA(At, 1, 0); PG8_STAGE(PG8_SA(0, 1), a2 + hstep, voffA);
;             PG8_WAIT_V(8); PG8_WAIT_L(0); PG8_BAR; PG8_MMA(0, 0, At, B0); PG8_MMA(0, 1, At, B1); PG8_BAR; PG8_SCHED;
;             PG8_LDA(At, 1, 1); PG8_STAGE(PG8_SB(1, 0), b3, voffB); PG8_STAGE(PG8_SB(1, 1), b3 + hstep, voffB); PG8_STAGE(PG8_SA(1, 0), a3, voffA);
;             PG8_WAIT_V(8); PG8_WAIT_L(0); PG8_BAR; PG8_MMA(1, 0, At, B0); PG8_MMA(1, 1, At, B1); PG8_BAR; PG8_SCHED;
	s_add_i32 s14, s34, s90
	v_lshl_add_u64 v[194:195], v[232:233], 0, s[64:65]
	s_mov_b32 m0, s14
	ds_read_b128 v[162:165], v247 offset:49152
	ds_read_b128 v[166:169], v247 offset:50176
	ds_read_b128 v[170:173], v247 offset:51200
	ds_read_b128 v[174:177], v247 offset:52224
	ds_read_b128 v[178:181], v247 offset:53248
	ds_read_b128 v[182:185], v247 offset:54272
	ds_read_b128 v[186:189], v247 offset:55296
	ds_read_b128 v[190:193], v247 offset:56320
	global_load_lds_dwordx4 v[194:195], off
	s_add_i32 m0, s14, 0x2000
	s_add_u32 s12, s12, 0x40080
	v_lshl_add_u64 v[194:195], v[230:231], 0, s[64:65]
	s_addc_u32 s13, s13, 0
	s_add_i32 s14, s35, s90
	global_load_lds_dwordx4 v[194:195], off
	v_lshl_add_u64 v[194:195], s[12:13], 0, v[212:213]
	s_mov_b32 m0, s14
	s_nop 0
	global_load_lds_dwordx4 v[194:195], off
	v_lshl_add_u64 v[194:195], s[12:13], 0, v[216:217]
	s_add_i32 m0, s14, 0x2000
	s_nop 0
	global_load_lds_dwordx4 v[194:195], off
	v_lshl_add_u64 v[194:195], v[226:227], 0, s[64:65]
	s_mov_b32 m0, s63
	s_nop 0
	global_load_lds_dwordx4 v[194:195], off
	v_lshl_add_u64 v[194:195], v[228:229], 0, s[64:65]
	s_mov_b32 m0, s68
	s_nop 0
	global_load_lds_dwordx4 v[194:195], off
	s_waitcnt vmcnt(8)
	s_waitcnt lgkmcnt(0)
	s_barrier
	s_setprio 1
	s_waitcnt lgkmcnt(0)
	v_mfma_f32_16x16x32_bf16 v[62:65], v[130:133], v[162:165], v[62:65]
	v_mfma_f32_16x16x32_bf16 v[58:61], v[138:141], v[162:165], v[58:61]
	v_mfma_f32_16x16x32_bf16 v[46:49], v[130:133], v[170:173], v[46:49]
	v_mfma_f32_16x16x32_bf16 v[42:45], v[138:141], v[170:173], v[42:45]
	v_mfma_f32_16x16x32_bf16 v[30:33], v[130:133], v[178:181], v[30:33]
	v_mfma_f32_16x16x32_bf16 v[26:29], v[138:141], v[178:181], v[26:29]
	v_mfma_f32_16x16x32_bf16 v[14:17], v[130:133], v[186:189], v[14:17]
	v_mfma_f32_16x16x32_bf16 v[10:13], v[138:141], v[186:189], v[10:13]
	v_mfma_f32_16x16x32_bf16 v[62:65], v[134:137], v[166:169], v[62:65]
	v_mfma_f32_16x16x32_bf16 v[58:61], v[142:145], v[166:169], v[58:61]
	v_mfma_f32_16x16x32_bf16 v[46:49], v[134:137], v[174:177], v[46:49]
	v_mfma_f32_16x16x32_bf16 v[42:45], v[142:145], v[174:177], v[42:45]
	v_mfma_f32_16x16x32_bf16 v[30:33], v[134:137], v[182:185], v[30:33]
	v_mfma_f32_16x16x32_bf16 v[26:29], v[142:145], v[182:185], v[26:29]
	v_mfma_f32_16x16x32_bf16 v[14:17], v[134:137], v[190:193], v[14:17]
	v_mfma_f32_16x16x32_bf16 v[10:13], v[142:145], v[190:193], v[10:13]
	s_setprio 0
	s_setprio 1
	v_mfma_f32_16x16x32_bf16 v[54:57], v[146:149], v[162:165], v[54:57]
	v_mfma_f32_16x16x32_bf16 v[50:53], v[154:157], v[162:165], v[50:53]
	v_mfma_f32_16x16x32_bf16 v[38:41], v[146:149], v[170:173], v[38:41]
	v_mfma_f32_16x16x32_bf16 v[34:37], v[154:157], v[170:173], v[34:37]
	v_mfma_f32_16x16x32_bf16 v[22:25], v[146:149], v[178:181], v[22:25]
	v_mfma_f32_16x16x32_bf16 v[18:21], v[154:157], v[178:181], v[18:21]
	v_mfma_f32_16x16x32_bf16 v[6:9], v[146:149], v[186:189], v[6:9]
	v_mfma_f32_16x16x32_bf16 v[2:5], v[154:157], v[186:189], v[2:5]
	v_mfma_f32_16x16x32_bf16 v[54:57], v[150:153], v[166:169], v[54:57]
	v_mfma_f32_16x16x32_bf16 v[50:53], v[158:161], v[166:169], v[50:53]
	v_mfma_f32_16x16x32_bf16 v[38:41], v[150:153], v[174:177], v[38:41]
	v_mfma_f32_16x16x32_bf16 v[34:37], v[158:161], v[174:177], v[34:37]
	v_mfma_f32_16x16x32_bf16 v[22:25], v[150:153], v[182:185], v[22:25]
	v_mfma_f32_16x16x32_bf16 v[18:21], v[158:161], v[182:185], v[18:21]
	v_mfma_f32_16x16x32_bf16 v[6:9], v[150:153], v[190:193], v[6:9]
	v_mfma_f32_16x16x32_bf16 v[2:5], v[158:161], v[190:193], v[2:5]
	s_setprio 0
	s_barrier
	s_add_i32 s40, s40, 2
	s_add_u32 s10, s10, 0x100
	s_addc_u32 s11, s11, 0
	s_cmp_gt_u32 s40, 13
	s_cbranch_scc1 .LBB0_425
.LBB0_421:
	s_waitcnt lgkmcnt(0)
	v_add_u32_e32 v130, s40, v248
	v_add_u32_e32 v130, 2, v130
	s_nop 0
	v_readfirstlane_b32 s12, v130
	s_nop 0
	s_mov_b32 s100, s12
	v_add_u32_e32 v130, 0, v246
	v_add_u32_e32 v131, 0x10000, v130
	v_add_u32_e32 v142, 0x14000, v130
	ds_read_b128 v[146:149], v131
	ds_read_b128 v[150:153], v131 offset:1024
	ds_read_b128 v[154:157], v131 offset:2048
	ds_read_b128 v[158:161], v131 offset:3072
	ds_read_b128 v[130:133], v142
	ds_read_b128 v[134:137], v142 offset:1024
	ds_read_b128 v[138:141], v142 offset:2048
	ds_read_b128 v[142:145], v142 offset:3072
	v_lshl_add_u64 v[194:195], v[224:225], 0, s[10:11]
	s_add_i32 m0, s91, 0xc000
	ds_read_b128 v[186:189], v247
	ds_read_b128 v[190:193], v247 offset:1024
	ds_read_b128 v[178:181], v247 offset:2048
	ds_read_b128 v[182:185], v247 offset:3072
	ds_read_b128 v[170:173], v247 offset:4096
	ds_read_b128 v[174:177], v247 offset:5120
	ds_read_b128 v[162:165], v247 offset:6144
	ds_read_b128 v[166:169], v247 offset:7168
	global_load_lds_dwordx4 v[194:195], off
	v_lshl_add_u64 v[194:195], v[222:223], 0, s[10:11]
	s_add_i32 m0, s91, 0xe000
	s_cmp_lg_u32 s12, 0
	global_load_lds_dwordx4 v[194:195], off
	s_waitcnt vmcnt(24)
	s_cselect_b64 s[34:35], -1, 0
	s_cmp_eq_u32 s12, 0
	s_cbranch_scc1 .LBB0_423
	s_waitcnt vmcnt(8)

;     __device__ __forceinline__ bool operator()(AccT& acc, const Unit& u, int wr, int wc, int fr, int fq) const {
;     ...
;         const int seg = (pn - 4) >> 2;
;         const int colt = ((pn - 4) & 3) * 256 + wc * 32 + 8 * t.tfq;
;         if (seg == 0 || seg == 1 || seg == 2 || seg >= 6) {
;             bf16* dst = (bf16*)(ws + (seg == 0 ? WS_VR : seg == 1 ? WS_GR : seg == 2 ? WS_QS : WS_GT)); const int ld = seg >= 6 ? 3 * D : D; const int cofs = seg >= 6 ? (seg - 6) * D : 0;
; #pragma unroll
;             for (int ai = 0; ai < 2; ++ai)
; #pragma unroll
;                 for (int m = 0; m < 4; ++m) { const size_t r = (size_t)(pm * 256 + trl0 + ai * 128 + m * 16);
; #pragma unroll
;                     for (int bj = 0; bj < 2; ++bj) { f32x4 v0 = acc[ai][bj][m][0], v1 = acc[ai][bj][m][1];
;                         if (seg == 1) {
; #pragma unroll
;                             for (int e = 0; e < 4; ++e) { v0[e] = siluf_(v0[e]); v1[e] = siluf_(v1[e]); } }
;                         else if (seg == 2) { v0 = v0 * (0.08838834764831845f * LOG2E); v1 = v1 * (0.08838834764831845f * LOG2E); }
;                         else if (seg >= 6) {
; #pragma unroll
;                             for (int e = 0; e < 4; ++e) { v0[e] = sigmoidf_(v0[e]); v1[e] = sigmoidf_(v1[e]); } }
;                         *(GAS v4u*)(dst + r * ld + cofs + colt + bj * 128) = tr4(t.pull, pack8(v0, v1)); } }
;             return false;
;         }
;         if (seg == 3 || seg == 4) {
;             bf16* dst = (bf16*)(ws + (seg == 3 ? WS_KS : WS_VS));
;             float* op = out + (seg == 3 ? O_KP : O_VP) + (size_t)layer * NB * KT_PP * D;
;             float* os = out + (seg == 3 ? O_KS : O_VS) + (size_t)layer * SBATCH * ST * D;
; #pragma unroll
;             for (int ai = 0; ai < 2; ++ai)
; #pragma unroll
;                 for (int m = 0; m < 4; ++m) { const int rl = trl0 + ai * 128 + m * 16; const size_t r = (size_t)(pm * 256 + rl);
; #pragma unroll
;                     for (int bj = 0; bj < 2; ++bj) { const f32x4 v0 = tr4f(t.pull, acc[ai][bj][m][0]), v1 = tr4f(t.pull, acc[ai][bj][m][1]); const int c = colt + bj * 128;
;                         *(GAS v4u*)(dst + r * D + c) = pack8(v0, v1);
;                         if (pm < 256) { float* o = op + ((size_t)(r >> 11) * KT_PP + NMETA + (r & (T - 1))) * D + c; *(GAS f32x4*)o = v0; *(GAS f32x4*)(o + 4) = v1; }
.LBB0_427:
	s_add_u32 s100, s29, 0x40080
	s_addc_u32 s101, s23, 0
	v_lshl_add_u64 v[194:195], s[100:101], 0, v[220:221]
	s_add_i32 m0, s91, 0xc000
	s_nop 0
	global_load_lds_dwordx4 v[194:195], off
	v_lshl_add_u64 v[194:195], s[100:101], 0, v[218:219]
	s_add_i32 m0, s91, 0xe000
	s_nop 0
	global_load_lds_dwordx4 v[194:195], off
	s_mov_b32 s21, s5
	v_mov_b32_e32 v156, v245
	s_mov_b32 s8, s75
	v_mov_b32_e32 v154, v1
	s_lshl_b32 s23, s8, 6
	s_cmp_gt_i32 s30, 3
	v_lshlrev_b32_e32 v155, 4, v156
	v_readlane_b32 s40, v254, 55
	s_cbranch_scc0 .LBB0_432
	s_add_i32 s31, s30, -4
	s_lshl_b32 s8, s30, 8
	s_lshr_b32 s29, s31, 2
	s_and_b32 s8, s8, 0x300
	s_lshl_b32 s9, s21, 5
	s_add_i32 s9, s9, s8
	s_add_i32 s8, s29, -1
	v_and_b32_e32 v132, 3, v154
	s_cmp_gt_u32 s8, 1
	v_lshl_or_b32 v138, v132, 3, s9
	s_cselect_b64 s[8:9], -1, 0
	s_sub_i32 s10, s30, 28
	s_cmp_gt_u32 s10, 0xffffffeb
	v_add_u32_e32 v130, v155, v154
	s_cselect_b64 s[10:11], -1, 0
	v_ashrrev_i32_e32 v131, 2, v130
	v_and_b32_e32 v133, -4, v130
	s_and_b64 s[8:9], s[10:11], s[8:9]
	v_lshl_add_u32 v157, v132, 6, v133
	v_add_u32_e32 v140, s23, v131
	s_and_b64 vcc, exec, s[8:9]
	s_cbranch_vccz .LBB0_435
	s_add_i32 s8, s29, -3
	s_cmp_gt_u32 s8, 1
	s_cbranch_scc0 .LBB0_436
	s_lshl_b32 s42, s28, 8
	v_bfe_u32 v141, v130, 2, 5
	v_add_u32_e32 v144, s42, v140
	ds_bpermute_b32 v130, v157, v126
	ds_bpermute_b32 v131, v157, v127
	ds_bpermute_b32 v132, v157, v128
	ds_bpermute_b32 v133, v157, v129
	ds_bpermute_b32 v134, v157, v122
	ds_bpermute_b32 v135, v157, v123
	ds_bpermute_b32 v136, v157, v124
	ds_bpermute_b32 v137, v157, v125
	v_ashrrev_i32_e32 v145, 31, v144
	v_readlane_b32 s8, v253, 24
	s_cmpk_gt_i32 s28, 0xff
	v_lshlrev_b64 v[146:147], 11, v[144:145]
	v_readlane_b32 s9, v253, 25
	s_cselect_b64 s[14:15], -1, 0
	s_cmpk_lg_i32 s28, 0x100
	v_lshl_add_u64 v[146:147], s[8:9], 0, v[146:147]
	v_ashrrev_i32_e32 v139, 31, v138
	s_cselect_b64 s[34:35], -1, 0
	v_subrev_co_u32_e64 v142, s[10:11], 17, v141
	v_lshl_add_u64 v[148:149], v[138:139], 1, v[146:147]
	s_and_b64 vcc, exec, s[14:15]
	s_waitcnt lgkmcnt(0)
	v_cvt_pk_bf16_f32 v150, v130, v131
	v_cvt_pk_bf16_f32 v151, v132, v133
	v_cvt_pk_bf16_f32 v152, v134, v135
	v_cvt_pk_bf16_f32 v153, v136, v137
	global_store_dwordx4 v[148:149], v[150:153], off
	s_cbranch_vccz .LBB0_437
	s_nor_b64 s[8:9], s[34:35], s[10:11]
	s_mov_b64 s[36:37], 0
	s_and_b64 s[8:9], s[8:9], exec
	s_branch .LBB0_438

; __global__ void __launch_bounds__(512, 2) mega_fwd(Args args) {
;     ...
;               const bool t0 = F.wave == 0 && l0_ == 0u;
;               unsigned nx = 0u, hd = 0u, rd = 0u;
;               if (t0) { if (kq < 5) nx = __hip_atomic_fetch_add(q + 64 * qk, 1u, RLX_AGENT); if (chain_open) { hd = __hip_atomic_load(ch, RLX_AGENT); rd = __hip_atomic_load(ch + 64, RLX_AGENT); } }
.LBB0_1008:
	s_add_i32 s3, s4, -3
	s_cmp_lt_u32 s3, 2
	s_cselect_b64 s[8:9], -1, 0
	s_and_b64 s[8:9], s[74:75], s[8:9]
	s_sub_i32 s3, 7, s4
	s_and_b64 s[8:9], s[8:9], exec
	v_mbcnt_lo_u32_b32 v1, -1, 0
	v_readlane_b32 s8, v253, 30
	v_readlane_b32 s9, v253, 31
	v_cmp_eq_u32_e32 vcc, 0, v1
	s_cselect_b32 s3, s3, s4
	v_mov_b32_e32 v214, 0
	s_and_b64 s[62:63], s[8:9], vcc
	s_mov_b64 s[14:15], -1
	v_mov_b32_e32 v183, 0
	s_and_saveexec_b64 s[8:9], s[62:63]
	s_cbranch_execz .LBB0_1017
	v_mov_b32_e32 v214, 0
	s_andn2_b64 vcc, exec, s[10:11]
	s_cbranch_vccnz .LBB0_1013
	s_mov_b64 s[12:13], exec
	v_mbcnt_lo_u32_b32 v1, s12, 0
	v_mbcnt_hi_u32_b32 v1, s13, v1
	v_cmp_eq_u32_e32 vcc, 0, v1
	s_and_saveexec_b64 s[10:11], vcc
	s_cbranch_execz .LBB0_1012
	s_lshl_b32 s14, s3, 6
	s_ashr_i32 s15, s14, 31
	s_lshl_b64 s[14:15], s[14:15], 2
	v_readlane_b32 s16, v252, 2
	v_readlane_b32 s17, v252, 3
	s_add_u32 s14, s16, s14
	s_addc_u32 s15, s17, s15
	s_bcnt1_i32_b64 s12, s[12:13]
	v_mov_b32_e32 v2, s12
	global_atomic_add v214, v0, v2, s[14:15] sc0

; __global__ void __launch_bounds__(512, 2) mega_fwd(Args args) {
;     ...
;               if (t0) { if (kq < 5) nx = __hip_atomic_fetch_add(q + 64 * qk, 1u, RLX_AGENT); if (chain_open) { hd = __hip_atomic_load(ch, RLX_AGENT); rd = __hip_atomic_load(ch + 64, RLX_AGENT); } }
.LBB0_1013:
	v_readlane_b32 s10, v252, 1
	s_cmp_eq_u32 s10, 0
	s_cbranch_scc1 .LBB0_1015
	v_readlane_b32 s10, v252, 8
	v_readlane_b32 s11, v252, 9
	s_nop 4
	global_load_dword v183, v0, s[10:11] sc1
	global_load_dword v255, v0, s[10:11] offset:256 sc1
	s_mov_b64 s[10:11], -1
	s_branch .LBB0_1016
.LBB0_1015:
	s_mov_b64 s[10:11], -1
	v_mov_b32_e32 v183, 0
	v_mov_b32_e32 v255, 0

; #define GAS __attribute__((address_space(1)))
; #define WSB(F, off) ((bf16*)(wsq((F).ws) + (off)))
; __device__ __forceinline__ TC thread_coords(int wave) { TC c; int l = lane_id_(); asm volatile("" : "+v"(l)); c.lane = l; c.wave = wave; c.tid = wave * 64 + l; return c; }
; template <bool F32KV> __device__ __forceinline__ void attn_unit(const Frame& F, int layer, int uid) {
;     ...
;     const TC tc = thread_coords(F.wave); const int tid = tc.tid, lane = tc.lane, w = tc.wave, l15 = lane & 15, g = lane >> 4;
;     int qi[NQ]; bool valid_q[NQ]; int lim[NQ];
; #pragma unroll
;     for (int nb = 0; nb < NQ; ++nb) { qi[nb] = q0 + 16 * (NQ == 2 ? (nb == 0 ? w : 15 - w) : w) + l15; valid_q[nb] = qi[nb] < Tq; lim[nb] = len0 + qi[nb]; }
;     bf16x8 qf[NQ][4];
; #pragma unroll
;     for (int nb = 0; nb < NQ; ++nb)
; #pragma unroll
;     for (int ks = 0; ks < 4; ++ks) { v4u t4 = (v4u){0u, 0u, 0u, 0u}; if (valid_q[nb]) t4 = *(const GAS v4u*)(WSB(F, WS_QS) + (size_t)(rowbase + qi[nb]) * D + h * 128 + 32 * ks + 8 * g); qf[nb][ks] = __builtin_bit_cast(bf16x8, t4); }
.LBB0_1035:
	v_mbcnt_lo_u32_b32 v66, -1, 0
	v_mbcnt_hi_u32_b32 v66, -1, v66
	v_readlane_b32 s8, v253, 32
	s_lshl_b32 s10, s5, 7
	v_and_b32_e32 v1, 15, v66
	v_add_u32_e32 v5, s21, v1
	v_add_u32_e32 v4, s8, v5
	v_ashrrev_i32_e32 v67, 4, v66
	v_lshlrev_b32_e32 v2, 3, v67
	v_add_u32_e32 v184, s14, v4
	v_cmp_le_u32_e64 s[16:17], s20, v4
	v_cmp_gt_u32_e64 s[8:9], s20, v4
	s_and_b32 s40, s10, 0x380
	v_ashrrev_i32_e32 v3, 31, v2
	v_mov_b32_e32 v26, 0
	v_ashrrev_i32_e32 v185, 31, v184
	v_mov_b32_e32 v34, 0
	v_mov_b32_e32 v35, 0
	v_mov_b32_e32 v36, 0
	v_mov_b32_e32 v37, 0
	s_and_saveexec_b64 s[10:11], s[8:9]
	s_cbranch_execz .LBB0_1037
	s_mov_b64 s[12:13], s[46:47]
	v_lshlrev_b64 v[6:7], 11, v[184:185]
	s_lshl_b32 s78, s40, 1
	v_lshl_add_u64 v[6:7], s[12:13], 0, v[6:7]
	v_lshl_add_u64 v[6:7], v[6:7], 0, s[78:79]
	v_lshl_add_u64 v[6:7], v[2:3], 1, v[6:7]
	v_add_co_u32_e32 v6, vcc, 0x3e8c0000, v6
	s_nop 1
	v_addc_co_u32_e32 v7, vcc, 0, v7, vcc
	global_load_dwordx4 v[34:37], v[6:7], off

; #define GAS __attribute__((address_space(1)))
; #define WSB(F, off) ((bf16*)(wsq((F).ws) + (off)))
; __device__ __forceinline__ TC thread_coords(int wave) { TC c; int l = lane_id_(); asm volatile("" : "+v"(l)); c.lane = l; c.wave = wave; c.tid = wave * 64 + l; return c; }
; template <bool F32KV> __device__ __forceinline__ void attn_unit(const Frame& F, int layer, int uid) {
;     ...
;     const TC tc = thread_coords(F.wave); const int tid = tc.tid, lane = tc.lane, w = tc.wave, l15 = lane & 15, g = lane >> 4;
;     int qi[NQ]; bool valid_q[NQ]; int lim[NQ];
; #pragma unroll
;     for (int nb = 0; nb < NQ; ++nb) { qi[nb] = q0 + 16 * (NQ == 2 ? (nb == 0 ? w : 15 - w) : w) + l15; valid_q[nb] = qi[nb] < Tq; lim[nb] = len0 + qi[nb]; }
;     bf16x8 qf[NQ][4];
; #pragma unroll
;     for (int nb = 0; nb < NQ; ++nb)
; #pragma unroll
;     for (int ks = 0; ks < 4; ++ks) { v4u t4 = (v4u){0u, 0u, 0u, 0u}; if (valid_q[nb]) t4 = *(const GAS v4u*)(WSB(F, WS_QS) + (size_t)(rowbase + qi[nb]) * D + h * 128 + 32 * ks + 8 * g); qf[nb][ks] = __builtin_bit_cast(bf16x8, t4); }
.LBB0_1146:
	v_mbcnt_lo_u32_b32 v20, -1, 0
	v_mbcnt_hi_u32_b32 v20, -1, v20
	v_readlane_b32 s8, v253, 32
	s_add_i32 s35, s24, s8
	v_and_b32_e32 v1, 15, v20
	v_add_u32_e32 v22, s35, v1
	v_ashrrev_i32_e32 v21, 4, v20
	v_add_u32_e32 v2, s12, v22
	v_ashrrev_i32_e32 v3, 31, v2
	s_lshl_b32 s12, s5, 7
	v_lshlrev_b32_e32 v18, 3, v21
	v_cmp_le_u32_e64 s[10:11], s25, v22
	v_cmp_gt_u32_e64 s[8:9], s25, v22
	v_lshlrev_b64 v[84:85], 11, v[2:3]
	s_and_b32 s29, s12, 0x380
	v_ashrrev_i32_e32 v19, 31, v18
	v_mov_b32_e32 v2, 0
	v_mov_b32_e32 v6, 0
	v_mov_b32_e32 v7, 0
	v_mov_b32_e32 v8, 0
	v_mov_b32_e32 v9, 0
	s_and_saveexec_b64 s[12:13], s[8:9]
	s_cbranch_execz .LBB0_1148
	s_mov_b64 s[26:27], s[46:47]
	s_lshl_b32 s78, s29, 1
	v_lshl_add_u64 v[4:5], s[26:27], 0, v[84:85]
	v_lshl_add_u64 v[4:5], v[4:5], 0, s[78:79]
	v_lshl_add_u64 v[4:5], v[18:19], 1, v[4:5]
	v_add_co_u32_e32 v4, vcc, 0x3e8c0000, v4
	s_nop 1
	v_addc_co_u32_e32 v5, vcc, 0, v5, vcc
	global_load_dwordx4 v[6:9], v[4:5], off

; __device__ __forceinline__ void ret_unit(const Frame& F, int layer, int uid) {
;     ...
;     if (stream == 1) { const float* s0 = in_ptr(IN_SRET) + (((size_t)layer * SBATCH + b) * HRET + h) * DKR * DVR;
; #pragma unroll
;         for (int m = 0; m < 8; ++m)
; #pragma unroll
;             for (int n = 0; n < 2; ++n)
; #pragma unroll
;                 for (int r = 0; r < 4; ++r) accS[m][n][r] = s0[(size_t)(16 * m + 4 * g + r) * DVR + 32 * w + 16 * n + l15]; }
.LBB0_1364:
	v_mbcnt_lo_u32_b32 v100, -1, 0
	v_mbcnt_hi_u32_b32 v100, -1, v100
	s_and_b32 s5, s5, 3
	s_andn2_b64 vcc, exec, s[8:9]
	v_ashrrev_i32_e32 v101, 4, v100
	v_and_b32_e32 v153, 15, v100
	v_lshlrev_b32_e32 v148, 2, v101
	s_cbranch_vccnz .LBB0_1366
	s_mov_b64 s[12:13], s[0:1]
	s_load_dwordx2 s[12:13], s[12:13], 0x20
	s_ashr_i32 s15, s3, 31
	v_readlane_b32 s14, v252, 12
	s_add_u32 s14, s3, s14
	s_addc_u32 s15, s15, 0
	s_lshl_b64 s[14:15], s[14:15], 19
	s_waitcnt lgkmcnt(0)
	s_add_u32 s12, s12, s14
	s_addc_u32 s13, s13, s15
	s_lshl_b32 s14, s5, 17
	s_add_u32 s14, s12, s14
	s_addc_u32 s15, s13, 0
	v_readlane_b32 s12, v254, 34
	v_readlane_b32 s13, v254, 35
	s_lshl_b64 s[12:13], s[12:13], 2
	s_add_u32 s12, s14, s12
	v_or_b32_e32 v6, 1, v148
	s_addc_u32 s13, s15, s13
	v_lshlrev_b32_e32 v2, 2, v153
	v_mov_b32_e32 v3, v0
	v_ashrrev_i32_e32 v149, 31, v148
	v_ashrrev_i32_e32 v7, 31, v6
	v_or_b32_e32 v8, 2, v148
	v_or_b32_e32 v10, 3, v148
	v_lshl_add_u64 v[4:5], s[12:13], 0, v[2:3]
	v_lshlrev_b64 v[2:3], 10, v[148:149]
	v_lshlrev_b64 v[6:7], 10, v[6:7]
	v_ashrrev_i32_e32 v9, 31, v8
	v_ashrrev_i32_e32 v11, 31, v10
	v_lshl_add_u64 v[2:3], v[4:5], 0, v[2:3]
	v_lshl_add_u64 v[6:7], v[4:5], 0, v[6:7]
	v_lshlrev_b64 v[8:9], 10, v[8:9]
	v_lshlrev_b64 v[10:11], 10, v[10:11]
	s_movk_i32 s12, 0x4000
	v_lshl_add_u64 v[8:9], v[4:5], 0, v[8:9]
	v_lshl_add_u64 v[4:5], v[4:5], 0, v[10:11]
	global_load_dword v84, v[2:3], off
	global_load_dword v85, v[6:7], off
	global_load_dword v86, v[8:9], off
	global_load_dword v87, v[4:5], off
	global_load_dword v95, v[4:5], off offset:64
	global_load_dword v94, v[8:9], off offset:64
	global_load_dword v93, v[6:7], off offset:64
	global_load_dword v92, v[2:3], off offset:64
	v_add_co_u32_e32 v6, vcc, s12, v2
	s_mov_b64 s[12:13], 0x4400
	v_lshl_add_u64 v[8:9], v[2:3], 0, s[12:13]
	s_mov_b64 s[12:13], 0x4800
	v_lshl_add_u64 v[10:11], v[2:3], 0, s[12:13]
	s_mov_b64 s[12:13], 0x4c00
	v_lshl_add_u64 v[4:5], v[2:3], 0, s[58:59]
	v_addc_co_u32_e32 v7, vcc, 0, v3, vcc
	v_lshl_add_u64 v[12:13], v[2:3], 0, s[12:13]
	s_mov_b64 s[12:13], 0x8000
	global_load_dword v88, v[6:7], off
	global_load_dword v89, v[6:7], off offset:1024
	global_load_dword v90, v[6:7], off offset:2048
	global_load_dword v91, v[6:7], off offset:3072
	global_load_dword v97, v[8:9], off offset:64
	global_load_dword v98, v[10:11], off offset:64
	global_load_dword v99, v[12:13], off offset:64
	global_load_dword v96, v[4:5], off offset:64
	v_lshl_add_u64 v[4:5], v[2:3], 0, s[12:13]
	s_mov_b32 s12, 0x8000
	v_add_co_u32_e32 v6, vcc, s12, v2
	s_mov_b64 s[12:13], 0x8400
	v_lshl_add_u64 v[8:9], v[2:3], 0, s[12:13]
	s_mov_b64 s[12:13], 0x8800
	v_lshl_add_u64 v[10:11], v[2:3], 0, s[12:13]
	s_mov_b64 s[12:13], 0x8c00
	v_addc_co_u32_e32 v7, vcc, 0, v3, vcc
	v_lshl_add_u64 v[12:13], v[2:3], 0, s[12:13]
	s_mov_b64 s[12:13], 0xc000
	global_load_dword v76, v[6:7], off
	global_load_dword v77, v[6:7], off offset:1024
	global_load_dword v78, v[6:7], off offset:2048
	global_load_dword v79, v[6:7], off offset:3072
	global_load_dword v81, v[8:9], off offset:64
	global_load_dword v82, v[10:11], off offset:64
	global_load_dword v83, v[12:13], off offset:64
	global_load_dword v80, v[4:5], off offset:64
	v_lshl_add_u64 v[4:5], v[2:3], 0, s[12:13]
	s_mov_b32 s12, 0xc000
	v_add_co_u32_e32 v6, vcc, s12, v2
	s_mov_b64 s[12:13], 0xc400
	v_lshl_add_u64 v[8:9], v[2:3], 0, s[12:13]
	s_mov_b64 s[12:13], 0xc800
	v_lshl_add_u64 v[10:11], v[2:3], 0, s[12:13]
	s_mov_b64 s[12:13], 0xcc00
	v_addc_co_u32_e32 v7, vcc, 0, v3, vcc
	v_lshl_add_u64 v[12:13], v[2:3], 0, s[12:13]
	s_mov_b64 s[12:13], 0x10000
	global_load_dword v68, v[6:7], off
	global_load_dword v69, v[6:7], off offset:1024
	global_load_dword v70, v[6:7], off offset:2048
	global_load_dword v71, v[6:7], off offset:3072
	global_load_dword v73, v[8:9], off offset:64
	global_load_dword v74, v[10:11], off offset:64
	global_load_dword v75, v[12:13], off offset:64
	global_load_dword v72, v[4:5], off offset:64
	v_lshl_add_u64 v[4:5], v[2:3], 0, s[12:13]
	s_mov_b32 s12, 0x10000
	v_add_co_u32_e32 v6, vcc, s12, v2
	s_mov_b64 s[12:13], 0x10400
	v_lshl_add_u64 v[8:9], v[2:3], 0, s[12:13]
	s_mov_b64 s[12:13], 0x10800
	v_lshl_add_u64 v[10:11], v[2:3], 0, s[12:13]
	s_mov_b64 s[12:13], 0x10c00
	v_addc_co_u32_e32 v7, vcc, 0, v3, vcc
	v_lshl_add_u64 v[12:13], v[2:3], 0, s[12:13]
	s_mov_b64 s[12:13], 0x14000
	global_load_dword v52, v[6:7], off
	global_load_dword v53, v[6:7], off offset:1024
	global_load_dword v54, v[6:7], off offset:2048
	global_load_dword v55, v[6:7], off offset:3072
	global_load_dword v65, v[8:9], off offset:64
	global_load_dword v66, v[10:11], off offset:64
	global_load_dword v67, v[12:13], off offset:64
	global_load_dword v64, v[4:5], off offset:64
	v_lshl_add_u64 v[4:5], v[2:3], 0, s[12:13]
	s_mov_b32 s12, 0x14000
	v_add_co_u32_e32 v6, vcc, s12, v2
	s_mov_b64 s[12:13], 0x14400
	v_lshl_add_u64 v[8:9], v[2:3], 0, s[12:13]
	s_mov_b64 s[12:13], 0x14800
	v_lshl_add_u64 v[10:11], v[2:3], 0, s[12:13]
	s_mov_b64 s[12:13], 0x14c00
	v_addc_co_u32_e32 v7, vcc, 0, v3, vcc
	v_lshl_add_u64 v[12:13], v[2:3], 0, s[12:13]
	s_mov_b64 s[12:13], 0x18000
	global_load_dword v40, v[6:7], off
	global_load_dword v41, v[6:7], off offset:1024
	global_load_dword v42, v[6:7], off offset:2048
	global_load_dword v43, v[6:7], off offset:3072
	global_load_dword v57, v[8:9], off offset:64
	global_load_dword v58, v[10:11], off offset:64
	global_load_dword v59, v[12:13], off offset:64
	global_load_dword v56, v[4:5], off offset:64
	v_lshl_add_u64 v[4:5], v[2:3], 0, s[12:13]
	s_mov_b32 s12, 0x18000
	v_add_co_u32_e32 v6, vcc, s12, v2
	s_mov_b64 s[12:13], 0x18400
	v_lshl_add_u64 v[8:9], v[2:3], 0, s[12:13]
	s_mov_b64 s[12:13], 0x18800
	v_lshl_add_u64 v[10:11], v[2:3], 0, s[12:13]
	s_mov_b64 s[12:13], 0x18c00
	v_addc_co_u32_e32 v7, vcc, 0, v3, vcc
	v_lshl_add_u64 v[12:13], v[2:3], 0, s[12:13]
	s_mov_b64 s[12:13], 0x1c000
	global_load_dword v44, v[6:7], off
	global_load_dword v45, v[6:7], off offset:1024
	global_load_dword v46, v[6:7], off offset:2048
	global_load_dword v47, v[6:7], off offset:3072
	global_load_dword v61, v[8:9], off offset:64
	global_load_dword v62, v[10:11], off offset:64
	global_load_dword v63, v[12:13], off offset:64
	global_load_dword v60, v[4:5], off offset:64
	v_lshl_add_u64 v[4:5], v[2:3], 0, s[12:13]
	s_mov_b32 s12, 0x1c000
	v_add_co_u32_e32 v6, vcc, s12, v2
	s_mov_b64 s[12:13], 0x1c400
	v_lshl_add_u64 v[8:9], v[2:3], 0, s[12:13]
	s_mov_b64 s[12:13], 0x1c800
	v_addc_co_u32_e32 v7, vcc, 0, v3, vcc
	v_lshl_add_u64 v[10:11], v[2:3], 0, s[12:13]
	s_mov_b64 s[12:13], 0x1cc00
	v_lshl_add_u64 v[2:3], v[2:3], 0, s[12:13]
	global_load_dword v36, v[6:7], off
	global_load_dword v37, v[6:7], off offset:1024
	global_load_dword v38, v[6:7], off offset:2048
	global_load_dword v39, v[6:7], off offset:3072
	global_load_dword v49, v[8:9], off offset:64
	global_load_dword v50, v[10:11], off offset:64
	global_load_dword v51, v[2:3], off offset:64
	global_load_dword v48, v[4:5], off offset:64
	s_branch .LBB0_1367

; __device__ __forceinline__ unsigned xb_ld(unsigned* p)              { return __hip_atomic_load(p, __ATOMIC_RELAXED, __HIP_MEMORY_SCOPE_AGENT); }
; __global__ void __launch_bounds__(512, 2) mega_fwd(Args args) {
;     ...
;               if (t0) { int ci = -1;
;                   if (chain_open) {
;                       if (kq == 5 || wst > 0) { unsigned sp = 0u;
;                           for (;;) { hd = __hip_atomic_load(ch, RLX_AGENT); if (hd >= (unsigned)CH_TOTAL) { ci = kq == 5 ? -2 : -3; break; } if (kq != 5 && hd >= (unsigned)ch_first(wst + 1)) break; rd = __hip_atomic_load(ch + 64, RLX_AGENT);
;                               if (hd < rd) { unsigned e = hd; if (__hip_atomic_compare_exchange_strong(ch, &e, hd + 1u, __ATOMIC_RELAXED, __ATOMIC_RELAXED, __HIP_MEMORY_SCOPE_AGENT)) { ci = (int)hd; break; } }
;                               else { __builtin_amdgcn_s_sleep(2); if ((++sp & 255u) == 0u) { if (xb_ld((unsigned*)(F.ctl + CW_BAR) + XB_TMO)) { ci = kq == 5 ? -2 : -1; break; } if (sp > XB_SPIN_CAP) { atomicAdd((unsigned*)(F.ctl + CW_BAR) + XB_TMO, 1u); ci = kq == 5 ? -2 : -1; break; } } } } }
;                       else if (hd >= (unsigned)CH_TOTAL) ci = -3;
;                       else if (hd < rd) { unsigned e = hd; if (__hip_atomic_compare_exchange_strong(ch, &e, hd + 1u, __ATOMIC_RELAXED, __ATOMIC_RELAXED, __HIP_MEMORY_SCOPE_AGENT)) ci = (int)hd; }
;                       if (ci >= 0) { __builtin_amdgcn_fence(__ATOMIC_ACQUIRE, "agent"); asm volatile("s_waitcnt vmcnt(0)" ::: "memory"); }
.LBB0_1443:
	s_or_b64 exec, exec, s[8:9]
	s_waitcnt lgkmcnt(0)
	s_barrier
	s_and_saveexec_b64 s[8:9], s[62:63]
	v_readlane_b32 s40, v254, 55
	s_cbranch_execz .LBB0_1454
	s_cmp_eq_u32 s4, 5
	s_cbranch_scc0 .Lchain_poll_ready
	s_waitcnt vmcnt(0)
.Lchain_poll_ready:
	v_cmp_ge_u32_e64 s[10:11], v183, v255
	s_nop 1
	s_orn2_b64 s[14:15], s[10:11], exec
	v_writelane_b32 v252, s14, 4
	v_writelane_b32 v252, s15, 5
	s_nop 0
	s_cmp_eq_u32 s4, 5
	s_cselect_b64 s[10:11], -1, 0
	s_cmp_lg_u32 s4, 5
	v_readlane_b32 s3, v252, 1
	s_cselect_b64 s[12:13], -1, 0
	s_cmp_eq_u32 s3, 0
	s_cbranch_scc1 .LBB0_1496
	s_cmp_gt_i32 s2, 0
	s_cselect_b64 s[14:15], -1, 0
	s_or_b64 s[14:15], s[10:11], s[14:15]
	s_andn2_b64 vcc, exec, s[14:15]
	s_mov_b64 s[14:15], -1
	s_cbranch_vccz .LBB0_1469
	v_readlane_b32 s14, v252, 4
	v_cmp_lt_u32_e32 vcc, 24, v183
	v_readlane_b32 s15, v252, 5
	s_nor_b64 s[16:17], vcc, s[14:15]
	v_cndmask_b32_e64 v1, -1, -3, vcc
	s_and_saveexec_b64 s[14:15], s[16:17]
	s_cbranch_execz .LBB0_1448
	v_readlane_b32 s16, v252, 8
	v_add_u32_e32 v182, 1, v183
	v_readlane_b32 s17, v252, 9
	s_nop 4
	global_atomic_cmpswap v1, v0, v[182:183], s[16:17] sc0
	s_waitcnt vmcnt(0)
	v_cmp_eq_u32_e32 vcc, v1, v183
	s_nop 1
	v_cndmask_b32_e32 v1, -1, v183, vcc

; #define PG8_STAGE(bufoff, gbase, voff) do { _Pragma("unroll") for (int _i = 0; _i < 2; ++_i) \
;         __builtin_amdgcn_global_load_lds((const unsigned*)((const char*)(gbase) + (voff)[_i]), (PG8_LAS unsigned*)(lds + (bufoff) + ldsw + _i * 8192), 16, 0, 0); } while (0)
; #define PG8_LDA(dst, b, h) do { _Pragma("unroll") for (int m = 0; m < 4; ++m) _Pragma("unroll") for (int k = 0; k < 2; ++k) dst[m][k] = *(const PG8_LAS bf16x8*)(lds + PG8_SA(b, h) + aoff + m * 2048 + k * 1024); } while (0)
; #define PG8_LDB(dst, b, h) do { _Pragma("unroll") for (int n = 0; n < 2; ++n) _Pragma("unroll") for (int k = 0; k < 2; ++k) dst[n][k] = *(const PG8_LAS bf16x8*)(lds + PG8_SB(b, h) + boff + n * 2048 + k * 1024); } while (0)
; #define PG8_WAIT_V(n) asm volatile("s_waitcnt vmcnt(" #n ")" ::: "memory")
; #define PG8_WAIT_VN(n) asm volatile("s_waitcnt vmcnt(%0)" :: "n"(n) : "memory")
; #define PG8_WAIT_L(n) asm volatile("s_waitcnt lgkmcnt(" #n ")" ::: "memory")
; #define PG8_BAR __builtin_amdgcn_s_barrier()
; #define PG8_SCHED __builtin_amdgcn_sched_barrier(0)
; template <class Epi, class Sched, bool ALIGN_EPI = false, bool SP2 = false>
; __device__ __forceinline__ void gemm_phase(PG8_LAS unsigned char* lds, const Gemm g, const Sched& S, const Epi& E, const int wave_id) {
;     ...
;             PG8_LDB(B0, 0, 0); PG8_LDB(B1, 0, 1); PG8_SCHED; PG8_LDA(At, 0, 0); PG8_STAGE(PG8_SA(1, 1), a1 + hstep, voffA);
;             PG8_WAIT_VN(8 + Epi::NS); if (strict) PG8_WAIT_V(8); PG8_WAIT_L(0); PG8_BAR; PG8_MMA(0, 0, At, B0); PG8_MMA(0, 1, At, B1); PG8_BAR; PG8_SCHED;
;             PG8_LDA(At, 0, 1); PG8_STAGE(PG8_SB(0, 0), b2, voffB); PG8_STAGE(PG8_SB(0, 1), b2 + hstep, voffB); PG8_STAGE(PG8_SA(0, 0), a2, voffA);
;             PG8_WAIT_VN(8 + Epi::NS); if (strict) PG8_WAIT_V(8); PG8_WAIT_L(0); PG8_BAR; PG8_MMA(1, 0, At, B0); PG8_MMA(1, 1, At, B1); PG8_BAR; PG8_SCHED;
;             PG8_LDB(B0, 1, 0); PG8_LDB(B1, 1, 1); PG8_SCHED; PG8_LDA(At, 1, 0); PG8_STAGE(PG8_SA(0, 1), a2 + hstep, voffA);
;             PG8_WAIT_V(8); PG8_WAIT_L(0); PG8_BAR; PG8_MMA(0, 0, At, B0); PG8_MMA(0, 1, At, B1); PG8_BAR; PG8_SCHED;
;             PG8_LDA(At, 1, 1); PG8_STAGE(PG8_SB(1, 0), b3, voffB); PG8_STAGE(PG8_SB(1, 1), b3 + hstep, voffB); PG8_STAGE(PG8_SA(1, 0), a3, voffA);
;             PG8_WAIT_V(8); PG8_WAIT_L(0); PG8_BAR; PG8_MMA(1, 0, At, B0); PG8_MMA(1, 1, At, B1); PG8_BAR; PG8_SCHED;
.LBB0_1821:
	s_waitcnt lgkmcnt(0)
	s_barrier
	s_setprio 1
	s_waitcnt lgkmcnt(0)
	v_mfma_f32_16x16x32_bf16 v[62:65], v[146:149], v[186:189], v[62:65]
	v_mfma_f32_16x16x32_bf16 v[58:61], v[154:157], v[186:189], v[58:61]
	v_mfma_f32_16x16x32_bf16 v[46:49], v[146:149], v[178:181], v[46:49]
	v_mfma_f32_16x16x32_bf16 v[42:45], v[154:157], v[178:181], v[42:45]
	v_mfma_f32_16x16x32_bf16 v[30:33], v[146:149], v[170:173], v[30:33]
	v_mfma_f32_16x16x32_bf16 v[26:29], v[154:157], v[170:173], v[26:29]
	v_mfma_f32_16x16x32_bf16 v[14:17], v[146:149], v[162:165], v[14:17]
	v_mfma_f32_16x16x32_bf16 v[10:13], v[154:157], v[162:165], v[10:13]
	v_mfma_f32_16x16x32_bf16 v[62:65], v[150:153], v[190:193], v[62:65]
	v_mfma_f32_16x16x32_bf16 v[58:61], v[158:161], v[190:193], v[58:61]
	v_mfma_f32_16x16x32_bf16 v[46:49], v[150:153], v[182:185], v[46:49]
	v_mfma_f32_16x16x32_bf16 v[42:45], v[158:161], v[182:185], v[42:45]
	v_mfma_f32_16x16x32_bf16 v[30:33], v[150:153], v[174:177], v[30:33]
	v_mfma_f32_16x16x32_bf16 v[26:29], v[158:161], v[174:177], v[26:29]
	v_mfma_f32_16x16x32_bf16 v[14:17], v[150:153], v[166:169], v[14:17]
	v_mfma_f32_16x16x32_bf16 v[10:13], v[158:161], v[166:169], v[10:13]
	s_setprio 0
	s_setprio 1
	v_mfma_f32_16x16x32_bf16 v[54:57], v[130:133], v[186:189], v[54:57]
	v_mfma_f32_16x16x32_bf16 v[50:53], v[138:141], v[186:189], v[50:53]
	v_mfma_f32_16x16x32_bf16 v[38:41], v[130:133], v[178:181], v[38:41]
	v_mfma_f32_16x16x32_bf16 v[34:37], v[138:141], v[178:181], v[34:37]
	v_mfma_f32_16x16x32_bf16 v[22:25], v[130:133], v[170:173], v[22:25]
	v_mfma_f32_16x16x32_bf16 v[18:21], v[138:141], v[170:173], v[18:21]
	v_mfma_f32_16x16x32_bf16 v[6:9], v[130:133], v[162:165], v[6:9]
	v_mfma_f32_16x16x32_bf16 v[2:5], v[138:141], v[162:165], v[2:5]
	v_mfma_f32_16x16x32_bf16 v[54:57], v[134:137], v[190:193], v[54:57]
	v_mfma_f32_16x16x32_bf16 v[50:53], v[142:145], v[190:193], v[50:53]
	v_mfma_f32_16x16x32_bf16 v[38:41], v[134:137], v[182:185], v[38:41]
	v_mfma_f32_16x16x32_bf16 v[34:37], v[142:145], v[182:185], v[34:37]
	v_mfma_f32_16x16x32_bf16 v[22:25], v[134:137], v[174:177], v[22:25]
	v_mfma_f32_16x16x32_bf16 v[18:21], v[142:145], v[174:177], v[18:21]
	v_mfma_f32_16x16x32_bf16 v[6:9], v[134:137], v[166:169], v[6:9]
	v_mfma_f32_16x16x32_bf16 v[2:5], v[142:145], v[166:169], v[2:5]
	s_setprio 0
	s_barrier
	s_add_i32 s26, 0, 0x18000
	s_add_i32 s27, 0, 0x1c000
	v_add_u32_e32 v142, s26, v246
	v_add_u32_e32 v158, s27, v246
	ds_read_b128 v[130:133], v142
	ds_read_b128 v[134:137], v142 offset:1024
	ds_read_b128 v[138:141], v142 offset:2048
	ds_read_b128 v[142:145], v142 offset:3072
	ds_read_b128 v[146:149], v158
	ds_read_b128 v[150:153], v158 offset:1024
	ds_read_b128 v[154:157], v158 offset:2048
	ds_read_b128 v[158:161], v158 offset:3072
	s_add_u32 s24, s24, 0x40000
	s_addc_u32 s25, s25, 0
	s_mov_b32 m0, s50
	v_lshl_add_u64 v[194:195], s[24:25], 0, v[210:211]
	ds_read_b128 v[162:165], v247 offset:32768
	ds_read_b128 v[166:169], v247 offset:33792
	ds_read_b128 v[170:173], v247 offset:34816
	ds_read_b128 v[174:177], v247 offset:35840
	ds_read_b128 v[178:181], v247 offset:36864
	ds_read_b128 v[182:185], v247 offset:37888
	ds_read_b128 v[186:189], v247 offset:38912
	ds_read_b128 v[190:193], v247 offset:39936
	global_load_lds_dwordx4 v[194:195], off
	v_lshl_add_u64 v[194:195], s[24:25], 0, v[214:215]
	s_mov_b32 m0, s51
	s_nop 0
	global_load_lds_dwordx4 v[194:195], off
	s_waitcnt vmcnt(26)
	s_cmp_eq_u32 s100, 0
	s_cbranch_scc1 .Lthird_wait_relaxed_3
	s_waitcnt vmcnt(8)
.Lthird_wait_relaxed_3:
	s_waitcnt lgkmcnt(0)
	s_barrier
	s_setprio 1
	s_waitcnt lgkmcnt(0)
	v_mfma_f32_16x16x32_bf16 v[126:129], v[130:133], v[162:165], v[126:129]
	v_mfma_f32_16x16x32_bf16 v[122:125], v[138:141], v[162:165], v[122:125]
	v_mfma_f32_16x16x32_bf16 v[110:113], v[130:133], v[170:173], v[110:113]
	v_mfma_f32_16x16x32_bf16 v[106:109], v[138:141], v[170:173], v[106:109]
	v_mfma_f32_16x16x32_bf16 v[94:97], v[130:133], v[178:181], v[94:97]
	v_mfma_f32_16x16x32_bf16 v[90:93], v[138:141], v[178:181], v[90:93]
	v_mfma_f32_16x16x32_bf16 v[78:81], v[130:133], v[186:189], v[78:81]
	v_mfma_f32_16x16x32_bf16 v[74:77], v[138:141], v[186:189], v[74:77]
	v_mfma_f32_16x16x32_bf16 v[126:129], v[134:137], v[166:169], v[126:129]
	v_mfma_f32_16x16x32_bf16 v[122:125], v[142:145], v[166:169], v[122:125]
	v_mfma_f32_16x16x32_bf16 v[110:113], v[134:137], v[174:177], v[110:113]
	v_mfma_f32_16x16x32_bf16 v[106:109], v[142:145], v[174:177], v[106:109]
	v_mfma_f32_16x16x32_bf16 v[94:97], v[134:137], v[182:185], v[94:97]
	v_mfma_f32_16x16x32_bf16 v[90:93], v[142:145], v[182:185], v[90:93]
	v_mfma_f32_16x16x32_bf16 v[78:81], v[134:137], v[190:193], v[78:81]
	v_mfma_f32_16x16x32_bf16 v[74:77], v[142:145], v[190:193], v[74:77]
	s_setprio 0
	s_setprio 1
	v_mfma_f32_16x16x32_bf16 v[118:121], v[146:149], v[162:165], v[118:121]
	v_mfma_f32_16x16x32_bf16 v[114:117], v[154:157], v[162:165], v[114:117]
	v_mfma_f32_16x16x32_bf16 v[102:105], v[146:149], v[170:173], v[102:105]
	v_mfma_f32_16x16x32_bf16 v[98:101], v[154:157], v[170:173], v[98:101]
	v_mfma_f32_16x16x32_bf16 v[86:89], v[146:149], v[178:181], v[86:89]
	v_mfma_f32_16x16x32_bf16 v[82:85], v[154:157], v[178:181], v[82:85]
	v_mfma_f32_16x16x32_bf16 v[70:73], v[146:149], v[186:189], v[70:73]
	v_mfma_f32_16x16x32_bf16 v[66:69], v[154:157], v[186:189], v[66:69]
	v_mfma_f32_16x16x32_bf16 v[118:121], v[150:153], v[166:169], v[118:121]
	v_mfma_f32_16x16x32_bf16 v[114:117], v[158:161], v[166:169], v[114:117]
	v_mfma_f32_16x16x32_bf16 v[102:105], v[150:153], v[174:177], v[102:105]
	v_mfma_f32_16x16x32_bf16 v[98:101], v[158:161], v[174:177], v[98:101]
	v_mfma_f32_16x16x32_bf16 v[86:89], v[150:153], v[182:185], v[86:89]
	v_mfma_f32_16x16x32_bf16 v[82:85], v[158:161], v[182:185], v[82:85]
	v_mfma_f32_16x16x32_bf16 v[70:73], v[150:153], v[190:193], v[70:73]
	v_mfma_f32_16x16x32_bf16 v[66:69], v[158:161], v[190:193], v[66:69]
	s_setprio 0
	s_barrier
; #define PG8_STAGE(bufoff, gbase, voff) do { _Pragma("unroll") for (int _i = 0; _i < 2; ++_i) \
;         __builtin_amdgcn_global_load_lds((const unsigned*)((const char*)(gbase) + (voff)[_i]), (PG8_LAS unsigned*)(lds + (bufoff) + ldsw + _i * 8192), 16, 0, 0); } while (0)
; #define PG8_LDA(dst, b, h) do { _Pragma("unroll") for (int m = 0; m < 4; ++m) _Pragma("unroll") for (int k = 0; k < 2; ++k) dst[m][k] = *(const PG8_LAS bf16x8*)(lds + PG8_SA(b, h) + aoff + m * 2048 + k * 1024); } while (0)
; #define PG8_LDB(dst, b, h) do { _Pragma("unroll") for (int n = 0; n < 2; ++n) _Pragma("unroll") for (int k = 0; k < 2; ++k) dst[n][k] = *(const PG8_LAS bf16x8*)(lds + PG8_SB(b, h) + boff + n * 2048 + k * 1024); } while (0)
; #define PG8_WAIT_V(n) asm volatile("s_waitcnt vmcnt(" #n ")" ::: "memory")
; #define PG8_WAIT_VN(n) asm volatile("s_waitcnt vmcnt(%0)" :: "n"(n) : "memory")
; template <class Epi, class Sched, bool ALIGN_EPI = false, bool SP2 = false>
; __device__ __forceinline__ void gemm_phase(PG8_LAS unsigned char* lds, const Gemm g, const Sched& S, const Epi& E, const int wave_id) {
;     ...
;             int tz_ = __builtin_amdgcn_readfirstlane(t | (ui > 0 ? 0 : 1)); asm volatile("" : "+s"(tz_));
;             const bool strict = !(Epi::NS > 0 && tz_ == 0);
;             PG8_LDB(B0, 0, 0); PG8_LDB(B1, 0, 1); PG8_SCHED; PG8_LDA(At, 0, 0); PG8_STAGE(PG8_SA(1, 1), a1 + hstep, voffA);
;             PG8_WAIT_VN(8 + Epi::NS); if (strict) PG8_WAIT_V(8); PG8_WAIT_L(0); PG8_BAR; PG8_MMA(0, 0, At, B0); PG8_MMA(0, 1, At, B1); PG8_BAR; PG8_SCHED;
;             PG8_LDA(At, 0, 1); PG8_STAGE(PG8_SB(0, 0), b2, voffB); PG8_STAGE(PG8_SB(0, 1), b2 + hstep, voffB); PG8_STAGE(PG8_SA(0, 0), a2, voffA);
;             PG8_WAIT_VN(8 + Epi::NS); if (strict) PG8_WAIT_V(8); PG8_WAIT_L(0); PG8_BAR; PG8_MMA(1, 0, At, B0); PG8_MMA(1, 1, At, B1); PG8_BAR; PG8_SCHED;
;             PG8_LDB(B0, 1, 0); PG8_LDB(B1, 1, 1); PG8_SCHED; PG8_LDA(At, 1, 0); PG8_STAGE(PG8_SA(0, 1), a2 + hstep, voffA);
;             PG8_WAIT_V(8); PG8_WAIT_L(0); PG8_BAR; PG8_MMA(0, 0, At, B0); PG8_MMA(0, 1, At, B1); PG8_BAR; PG8_SCHED;
;             PG8_LDA(At, 1, 1); PG8_STAGE(PG8_SB(1, 0), b3, voffB); PG8_STAGE(PG8_SB(1, 1), b3 + hstep, voffB); PG8_STAGE(PG8_SA(1, 0), a3, voffA);
;             PG8_WAIT_V(8); PG8_WAIT_L(0); PG8_BAR; PG8_MMA(1, 0, At, B0); PG8_MMA(1, 1, At, B1); PG8_BAR; PG8_SCHED;
	s_add_i32 s24, s26, s38
	v_lshl_add_u64 v[194:195], v[232:233], 0, s[64:65]
	s_mov_b32 m0, s24
	ds_read_b128 v[162:165], v247 offset:49152
	ds_read_b128 v[166:169], v247 offset:50176
	ds_read_b128 v[170:173], v247 offset:51200
	ds_read_b128 v[174:177], v247 offset:52224
	ds_read_b128 v[178:181], v247 offset:53248
	ds_read_b128 v[182:185], v247 offset:54272
	ds_read_b128 v[186:189], v247 offset:55296
	ds_read_b128 v[190:193], v247 offset:56320
	global_load_lds_dwordx4 v[194:195], off
	s_add_i32 m0, s24, 0x2000
	s_add_u32 s22, s22, 0x40080
	v_lshl_add_u64 v[194:195], v[230:231], 0, s[64:65]
	s_addc_u32 s23, s23, 0
	s_add_i32 s24, s27, s38
	global_load_lds_dwordx4 v[194:195], off
	v_lshl_add_u64 v[194:195], s[22:23], 0, v[212:213]
	s_mov_b32 m0, s24
	s_nop 0
	global_load_lds_dwordx4 v[194:195], off
	v_lshl_add_u64 v[194:195], s[22:23], 0, v[216:217]
	s_add_i32 m0, s24, 0x2000
	s_nop 0
	global_load_lds_dwordx4 v[194:195], off
	v_lshl_add_u64 v[194:195], v[226:227], 0, s[64:65]
	s_mov_b32 m0, s54
	s_nop 0
	global_load_lds_dwordx4 v[194:195], off
	v_lshl_add_u64 v[194:195], v[228:229], 0, s[64:65]
	s_mov_b32 m0, s56
	s_nop 0
	global_load_lds_dwordx4 v[194:195], off
	s_waitcnt vmcnt(8)
	s_waitcnt lgkmcnt(0)
	s_barrier
	s_setprio 1
	s_waitcnt lgkmcnt(0)
	v_mfma_f32_16x16x32_bf16 v[62:65], v[130:133], v[162:165], v[62:65]
	v_mfma_f32_16x16x32_bf16 v[58:61], v[138:141], v[162:165], v[58:61]
	v_mfma_f32_16x16x32_bf16 v[46:49], v[130:133], v[170:173], v[46:49]
	v_mfma_f32_16x16x32_bf16 v[42:45], v[138:141], v[170:173], v[42:45]
	v_mfma_f32_16x16x32_bf16 v[30:33], v[130:133], v[178:181], v[30:33]
	v_mfma_f32_16x16x32_bf16 v[26:29], v[138:141], v[178:181], v[26:29]
	v_mfma_f32_16x16x32_bf16 v[14:17], v[130:133], v[186:189], v[14:17]
	v_mfma_f32_16x16x32_bf16 v[10:13], v[138:141], v[186:189], v[10:13]
	v_mfma_f32_16x16x32_bf16 v[62:65], v[134:137], v[166:169], v[62:65]
	v_mfma_f32_16x16x32_bf16 v[58:61], v[142:145], v[166:169], v[58:61]
	v_mfma_f32_16x16x32_bf16 v[46:49], v[134:137], v[174:177], v[46:49]
	v_mfma_f32_16x16x32_bf16 v[42:45], v[142:145], v[174:177], v[42:45]
	v_mfma_f32_16x16x32_bf16 v[30:33], v[134:137], v[182:185], v[30:33]
	v_mfma_f32_16x16x32_bf16 v[26:29], v[142:145], v[182:185], v[26:29]
	v_mfma_f32_16x16x32_bf16 v[14:17], v[134:137], v[190:193], v[14:17]
	v_mfma_f32_16x16x32_bf16 v[10:13], v[142:145], v[190:193], v[10:13]
	s_setprio 0
	s_setprio 1
	v_mfma_f32_16x16x32_bf16 v[54:57], v[146:149], v[162:165], v[54:57]
	v_mfma_f32_16x16x32_bf16 v[50:53], v[154:157], v[162:165], v[50:53]
	v_mfma_f32_16x16x32_bf16 v[38:41], v[146:149], v[170:173], v[38:41]
	v_mfma_f32_16x16x32_bf16 v[34:37], v[154:157], v[170:173], v[34:37]
	v_mfma_f32_16x16x32_bf16 v[22:25], v[146:149], v[178:181], v[22:25]
	v_mfma_f32_16x16x32_bf16 v[18:21], v[154:157], v[178:181], v[18:21]
	v_mfma_f32_16x16x32_bf16 v[6:9], v[146:149], v[186:189], v[6:9]
	v_mfma_f32_16x16x32_bf16 v[2:5], v[154:157], v[186:189], v[2:5]
	v_mfma_f32_16x16x32_bf16 v[54:57], v[150:153], v[166:169], v[54:57]
	v_mfma_f32_16x16x32_bf16 v[50:53], v[158:161], v[166:169], v[50:53]
	v_mfma_f32_16x16x32_bf16 v[38:41], v[150:153], v[174:177], v[38:41]
	v_mfma_f32_16x16x32_bf16 v[34:37], v[158:161], v[174:177], v[34:37]
	v_mfma_f32_16x16x32_bf16 v[22:25], v[150:153], v[182:185], v[22:25]
	v_mfma_f32_16x16x32_bf16 v[18:21], v[158:161], v[182:185], v[18:21]
	v_mfma_f32_16x16x32_bf16 v[6:9], v[150:153], v[190:193], v[6:9]
	v_mfma_f32_16x16x32_bf16 v[2:5], v[158:161], v[190:193], v[2:5]
	s_setprio 0
	s_barrier
	s_add_i32 s74, s74, 2
	s_add_u32 s20, s20, 0x100
	s_addc_u32 s21, s21, 0
	s_cmp_gt_u32 s74, 13
	s_cbranch_scc1 .LBB0_1826
.LBB0_1822:
	v_add_u32_e32 v130, s74, v248
	v_add_u32_e32 v130, 2, v130
	s_nop 0
	v_readfirstlane_b32 s22, v130
	s_nop 0
	s_mov_b32 s100, s22
	v_add_u32_e32 v130, 0, v246
	v_add_u32_e32 v131, 0x10000, v130
	v_add_u32_e32 v142, 0x14000, v130
	ds_read_b128 v[146:149], v131
	ds_read_b128 v[150:153], v131 offset:1024
	ds_read_b128 v[154:157], v131 offset:2048
	ds_read_b128 v[158:161], v131 offset:3072
	ds_read_b128 v[130:133], v142
	ds_read_b128 v[134:137], v142 offset:1024
	ds_read_b128 v[138:141], v142 offset:2048
	ds_read_b128 v[142:145], v142 offset:3072
	v_lshl_add_u64 v[194:195], v[224:225], 0, s[20:21]
	s_add_i32 m0, s39, 0xc000
	ds_read_b128 v[186:189], v247
	ds_read_b128 v[190:193], v247 offset:1024
	ds_read_b128 v[178:181], v247 offset:2048
	ds_read_b128 v[182:185], v247 offset:3072
	ds_read_b128 v[170:173], v247 offset:4096
	ds_read_b128 v[174:177], v247 offset:5120
	ds_read_b128 v[162:165], v247 offset:6144
	ds_read_b128 v[166:169], v247 offset:7168
	global_load_lds_dwordx4 v[194:195], off
	v_lshl_add_u64 v[194:195], v[222:223], 0, s[20:21]
	s_add_i32 m0, s39, 0xe000
	s_cmp_lg_u32 s22, 0
	global_load_lds_dwordx4 v[194:195], off
	s_waitcnt vmcnt(24)
	s_cselect_b64 s[26:27], -1, 0
	s_cmp_eq_u32 s22, 0
	s_cbranch_scc1 .LBB0_1824
	s_waitcnt vmcnt(8)

; #define PG8_STAGE(bufoff, gbase, voff) do { _Pragma("unroll") for (int _i = 0; _i < 2; ++_i) \
;         __builtin_amdgcn_global_load_lds((const unsigned*)((const char*)(gbase) + (voff)[_i]), (PG8_LAS unsigned*)(lds + (bufoff) + ldsw + _i * 8192), 16, 0, 0); } while (0)
; #define PG8_LDA(dst, b, h) do { _Pragma("unroll") for (int m = 0; m < 4; ++m) _Pragma("unroll") for (int k = 0; k < 2; ++k) dst[m][k] = *(const PG8_LAS bf16x8*)(lds + PG8_SA(b, h) + aoff + m * 2048 + k * 1024); } while (0)
; #define PG8_LDB(dst, b, h) do { _Pragma("unroll") for (int n = 0; n < 2; ++n) _Pragma("unroll") for (int k = 0; k < 2; ++k) dst[n][k] = *(const PG8_LAS bf16x8*)(lds + PG8_SB(b, h) + boff + n * 2048 + k * 1024); } while (0)
; #define PG8_SCHED __builtin_amdgcn_sched_barrier(0)
; #define GAS __attribute__((address_space(1)))
; __device__ __forceinline__ v4u tr4(int a, v4u x) { return (v4u){bperm(a, x.x), bperm(a, x.y), bperm(a, x.z), bperm(a, x.w)}; }
; template <class Epi, class Sched, bool ALIGN_EPI = false, bool SP2 = false>
; __device__ __forceinline__ void gemm_phase(PG8_LAS unsigned char* lds, const Gemm g, const Sched& S, const Epi& E, const int wave_id) {
;     ...
;             PG8_LDB(B0, 0, 0); PG8_LDB(B1, 0, 1); PG8_SCHED; PG8_LDA(At, 0, 0); PG8_STAGE(PG8_SA(1, 1), a1 + hstep, voffA);
;     __device__ __forceinline__ bool operator()(AccT& acc, const Unit& u, int wr, int wc, int fr, int fq) const {
;     ...
;         const LaneT t = lane_t(fr, fq);
;         const bf16* src = (const bf16*)(ws + WS_HB); bf16* dst = (bf16*)(ws + WS_YB);
;         const int row0 = u.pm * 256 + wr * 64 + t.tfr, col0 = u.pn * 256 + wc * 32 + 8 * t.tfq;
; #pragma unroll
;         for (int ai = 0; ai < 2; ++ai)
; #pragma unroll
;             for (int m = 0; m < 4; ++m) { const size_t off = (size_t)(row0 + ai * 128 + m * 16) * D + col0;
; #pragma unroll
;                 for (int bj = 0; bj < 2; ++bj) { const v4u r = tr4(t.push, *(const GAS v4u*)(src + off + bj * 128));
;                     const f32x4 y0 = (f32x4){bflo(r.x), bfhi(r.x), bflo(r.y), bfhi(r.y)} * ca + acc[ai][bj][m][0] * cb, y1 = (f32x4){bflo(r.z), bfhi(r.z), bflo(r.w), bfhi(r.w)} * ca + acc[ai][bj][m][1] * cb;
;                     *(GAS v4u*)(dst + off + bj * 128) = tr4(t.pull, pack8(y0, y1)); } }
.LBB0_1828:
	s_add_u32 s100, s63, 0x40080
	s_addc_u32 s101, s11, 0
	v_lshl_add_u64 v[194:195], s[100:101], 0, v[220:221]
	s_add_i32 m0, s39, 0xc000
	s_nop 0
	global_load_lds_dwordx4 v[194:195], off
	v_lshl_add_u64 v[194:195], s[100:101], 0, v[218:219]
	s_add_i32 m0, s39, 0xe000
	s_nop 0
	global_load_lds_dwordx4 v[194:195], off
	s_mov_b32 s9, s37
	v_mov_b32_e32 v130, v245
	s_mov_b32 s11, s52
	v_mov_b32_e32 v131, v1
	s_lshl_b32 s16, s16, 8
	v_lshl_add_u32 v132, v131, 4, v130
	s_lshl_b32 s9, s9, 6
	v_ashrrev_i32_e32 v134, 2, v132
	v_and_b32_e32 v135, 3, v130
	v_lshlrev_b32_e32 v130, 4, v130
	s_add_i32 s9, s9, s16
	v_lshl_add_u32 v133, v131, 2, v130
	v_add_u32_e32 v130, s9, v134
	s_lshl_b32 s9, s17, 8
	s_lshl_b32 s11, s11, 5
	s_add_i32 s11, s11, s9
	v_and_b32_e32 v132, -4, v132
	v_lshl_or_b32 v134, v135, 3, s11
	v_ashrrev_i32_e32 v131, 31, v130
	v_lshl_add_u32 v132, v135, 6, v132
	v_ashrrev_i32_e32 v135, 31, v134
	v_lshlrev_b64 v[130:131], 10, v[130:131]
	v_lshl_add_u64 v[130:131], v[130:131], 0, v[134:135]
	v_readlane_b32 s18, v253, 11
	v_lshlrev_b64 v[130:131], 1, v[130:131]
	v_readlane_b32 s19, v253, 12
	v_lshl_add_u64 v[140:141], s[60:61], 0, v[130:131]
	s_mov_b64 s[16:17], 0x8000
	v_lshl_add_u64 v[138:139], s[18:19], 0, v[130:131]
	v_mov_b64_e32 v[130:131], v[138:139]
	global_load_dwordx4 v[146:149], v[130:131], off
	s_andn2_b64 vcc, exec, s[6:7]
	global_load_dwordx4 v[150:153], v[130:131], off offset:256
	s_mov_b64 s[16:17], 0x8000
	v_lshl_add_u64 v[130:131], v[138:139], 0, s[16:17]
	global_load_dwordx4 v[154:157], v[130:131], off
	global_load_dwordx4 v[158:161], v[130:131], off offset:256
	s_mov_b64 s[16:17], 0x10000
	v_lshl_add_u64 v[130:131], v[138:139], 0, s[16:17]
	global_load_dwordx4 v[162:165], v[130:131], off
	global_load_dwordx4 v[166:169], v[130:131], off offset:256
	s_mov_b64 s[16:17], 0x18000
	v_lshl_add_u64 v[130:131], v[138:139], 0, s[16:17]
	global_load_dwordx4 v[170:173], v[130:131], off
	global_load_dwordx4 v[174:177], v[130:131], off offset:256
	s_mov_b64 s[16:17], 0x40000
	v_lshl_add_u64 v[130:131], v[138:139], 0, s[16:17]
	global_load_dwordx4 v[178:181], v[130:131], off
	global_load_dwordx4 v[182:185], v[130:131], off offset:256
	s_mov_b64 s[16:17], 0x48000
	v_lshl_add_u64 v[130:131], v[138:139], 0, s[16:17]
	global_load_dwordx4 v[186:189], v[130:131], off
	global_load_dwordx4 v[190:193], v[130:131], off offset:256
	s_waitcnt vmcnt(11)
	ds_bpermute_b32 v143, v133, v147
	ds_bpermute_b32 v142, v133, v146
	ds_bpermute_b32 v145, v133, v149
	ds_bpermute_b32 v144, v133, v148
	v_mov_b64_e32 v[134:135], v[140:141]
	s_waitcnt lgkmcnt(3)
	v_lshlrev_b32_e32 v136, 16, v143
	v_and_b32_e32 v137, 0xffff0000, v143
	s_waitcnt lgkmcnt(2)
	v_and_b32_e32 v143, 0xffff0000, v142
	v_lshlrev_b32_e32 v142, 16, v142
	v_pk_fma_f32 v[128:129], v[136:137], s[96:97], v[128:129] op_sel_hi:[1,0,1]
	v_pk_fma_f32 v[126:127], v[142:143], s[96:97], v[126:127] op_sel_hi:[1,0,1]
	s_waitcnt lgkmcnt(1)
	v_lshlrev_b32_e32 v136, 16, v145
	v_and_b32_e32 v137, 0xffff0000, v145
	s_waitcnt lgkmcnt(0)
	v_and_b32_e32 v145, 0xffff0000, v144
	v_lshlrev_b32_e32 v144, 16, v144
	v_pk_fma_f32 v[124:125], v[136:137], s[96:97], v[124:125] op_sel_hi:[1,0,1]
	v_pk_fma_f32 v[122:123], v[144:145], s[96:97], v[122:123] op_sel_hi:[1,0,1]
	v_cvt_pk_bf16_f32 v126, v126, v127
	v_cvt_pk_bf16_f32 v127, v128, v129
	v_cvt_pk_bf16_f32 v128, v122, v123
	v_cvt_pk_bf16_f32 v125, v124, v125
	s_nop 1
	ds_bpermute_b32 v122, v132, v126
	ds_bpermute_b32 v123, v132, v127
	ds_bpermute_b32 v124, v132, v128
	ds_bpermute_b32 v125, v132, v125
	s_waitcnt lgkmcnt(0)
	global_store_dwordx4 v[134:135], v[122:125], off
	s_mov_b64 s[16:17], 0x50000
	v_lshl_add_u64 v[130:131], v[138:139], 0, s[16:17]
	global_load_dwordx4 v[126:129], v[130:131], off
	s_waitcnt vmcnt(12)
	ds_bpermute_b32 v143, v133, v151
	ds_bpermute_b32 v142, v133, v150
	ds_bpermute_b32 v145, v133, v153
	ds_bpermute_b32 v144, v133, v152
	s_waitcnt lgkmcnt(3)
	v_lshlrev_b32_e32 v136, 16, v143
	v_and_b32_e32 v137, 0xffff0000, v143
	s_waitcnt lgkmcnt(2)
	v_and_b32_e32 v143, 0xffff0000, v142
	v_lshlrev_b32_e32 v142, 16, v142
	v_pk_fma_f32 v[120:121], v[136:137], s[96:97], v[120:121] op_sel_hi:[1,0,1]
	v_pk_fma_f32 v[118:119], v[142:143], s[96:97], v[118:119] op_sel_hi:[1,0,1]
	s_waitcnt lgkmcnt(1)
	v_lshlrev_b32_e32 v136, 16, v145
	v_and_b32_e32 v137, 0xffff0000, v145
	s_waitcnt lgkmcnt(0)
	v_and_b32_e32 v145, 0xffff0000, v144
	v_lshlrev_b32_e32 v144, 16, v144
	v_pk_fma_f32 v[116:117], v[136:137], s[96:97], v[116:117] op_sel_hi:[1,0,1]
	v_pk_fma_f32 v[114:115], v[144:145], s[96:97], v[114:115] op_sel_hi:[1,0,1]
	v_cvt_pk_bf16_f32 v118, v118, v119
	v_cvt_pk_bf16_f32 v119, v120, v121
	v_cvt_pk_bf16_f32 v120, v114, v115
	v_cvt_pk_bf16_f32 v117, v116, v117
	s_nop 1
	ds_bpermute_b32 v114, v132, v118
	ds_bpermute_b32 v115, v132, v119
	ds_bpermute_b32 v116, v132, v120
	ds_bpermute_b32 v117, v132, v117
	s_waitcnt lgkmcnt(0)
	global_store_dwordx4 v[134:135], v[114:117], off offset:256
	global_load_dwordx4 v[118:121], v[130:131], off offset:256
	s_waitcnt vmcnt(13)
	ds_bpermute_b32 v143, v133, v155
	ds_bpermute_b32 v142, v133, v154
	ds_bpermute_b32 v145, v133, v157
	ds_bpermute_b32 v144, v133, v156
	s_mov_b64 s[16:17], 0x8000
	v_lshl_add_u64 v[134:135], v[140:141], 0, s[16:17]
	s_waitcnt lgkmcnt(3)
	v_lshlrev_b32_e32 v136, 16, v143
	v_and_b32_e32 v137, 0xffff0000, v143
	s_waitcnt lgkmcnt(2)
	v_and_b32_e32 v143, 0xffff0000, v142
	v_lshlrev_b32_e32 v142, 16, v142
	v_pk_fma_f32 v[112:113], v[136:137], s[96:97], v[112:113] op_sel_hi:[1,0,1]
	v_pk_fma_f32 v[110:111], v[142:143], s[96:97], v[110:111] op_sel_hi:[1,0,1]
	s_waitcnt lgkmcnt(1)
; #define GAS __attribute__((address_space(1)))
; __device__ __forceinline__ v4u tr4(int a, v4u x) { return (v4u){bperm(a, x.x), bperm(a, x.y), bperm(a, x.z), bperm(a, x.w)}; }
; __device__ __forceinline__ v4u pack8(const f32x4& a, const f32x4& b) { return (v4u){pg8::cvt_pk_bf16(a[0], a[1]), pg8::cvt_pk_bf16(a[2], a[3]), pg8::cvt_pk_bf16(b[0], b[1]), pg8::cvt_pk_bf16(b[2], b[3])}; }
;     __device__ __forceinline__ bool operator()(AccT& acc, const Unit& u, int wr, int wc, int fr, int fq) const {
;     ...
;             for (int m = 0; m < 4; ++m) { const size_t off = (size_t)(row0 + ai * 128 + m * 16) * D + col0;
; #pragma unroll
;                 for (int bj = 0; bj < 2; ++bj) { const v4u r = tr4(t.push, *(const GAS v4u*)(src + off + bj * 128));
;                     const f32x4 y0 = (f32x4){bflo(r.x), bfhi(r.x), bflo(r.y), bfhi(r.y)} * ca + acc[ai][bj][m][0] * cb, y1 = (f32x4){bflo(r.z), bfhi(r.z), bflo(r.w), bfhi(r.w)} * ca + acc[ai][bj][m][1] * cb;
;                     *(GAS v4u*)(dst + off + bj * 128) = tr4(t.pull, pack8(y0, y1)); } }
	v_lshlrev_b32_e32 v136, 16, v145
	v_and_b32_e32 v137, 0xffff0000, v145
	s_waitcnt lgkmcnt(0)
	v_and_b32_e32 v145, 0xffff0000, v144
	v_lshlrev_b32_e32 v144, 16, v144
	v_pk_fma_f32 v[108:109], v[136:137], s[96:97], v[108:109] op_sel_hi:[1,0,1]
	v_pk_fma_f32 v[106:107], v[144:145], s[96:97], v[106:107] op_sel_hi:[1,0,1]
	v_cvt_pk_bf16_f32 v110, v110, v111
	v_cvt_pk_bf16_f32 v111, v112, v113
	v_cvt_pk_bf16_f32 v112, v106, v107
	v_cvt_pk_bf16_f32 v109, v108, v109
	s_nop 1
	ds_bpermute_b32 v106, v132, v110
	ds_bpermute_b32 v107, v132, v111
	ds_bpermute_b32 v108, v132, v112
	ds_bpermute_b32 v109, v132, v109
	s_waitcnt lgkmcnt(0)
	global_store_dwordx4 v[134:135], v[106:109], off
	s_mov_b64 s[16:17], 0x58000
	v_lshl_add_u64 v[130:131], v[138:139], 0, s[16:17]
	global_load_dwordx4 v[110:113], v[130:131], off
	s_waitcnt vmcnt(14)
	ds_bpermute_b32 v143, v133, v159
	ds_bpermute_b32 v142, v133, v158
	ds_bpermute_b32 v145, v133, v161
	ds_bpermute_b32 v144, v133, v160
	s_waitcnt lgkmcnt(3)
	v_lshlrev_b32_e32 v136, 16, v143
	v_and_b32_e32 v137, 0xffff0000, v143
	s_waitcnt lgkmcnt(2)
	v_and_b32_e32 v143, 0xffff0000, v142
	v_lshlrev_b32_e32 v142, 16, v142
	v_pk_fma_f32 v[104:105], v[136:137], s[96:97], v[104:105] op_sel_hi:[1,0,1]
	v_pk_fma_f32 v[102:103], v[142:143], s[96:97], v[102:103] op_sel_hi:[1,0,1]
	s_waitcnt lgkmcnt(1)
	v_lshlrev_b32_e32 v136, 16, v145
	v_and_b32_e32 v137, 0xffff0000, v145
	s_waitcnt lgkmcnt(0)
	v_and_b32_e32 v145, 0xffff0000, v144
	v_lshlrev_b32_e32 v144, 16, v144
	v_pk_fma_f32 v[100:101], v[136:137], s[96:97], v[100:101] op_sel_hi:[1,0,1]
	v_pk_fma_f32 v[98:99], v[144:145], s[96:97], v[98:99] op_sel_hi:[1,0,1]
	v_cvt_pk_bf16_f32 v102, v102, v103
	v_cvt_pk_bf16_f32 v103, v104, v105
	v_cvt_pk_bf16_f32 v104, v98, v99
	v_cvt_pk_bf16_f32 v101, v100, v101
	s_nop 1
	ds_bpermute_b32 v98, v132, v102
	ds_bpermute_b32 v99, v132, v103
	ds_bpermute_b32 v100, v132, v104
	ds_bpermute_b32 v101, v132, v101
	s_waitcnt lgkmcnt(0)
	global_store_dwordx4 v[134:135], v[98:101], off offset:256
	global_load_dwordx4 v[102:105], v[130:131], off offset:256
	s_waitcnt vmcnt(15)
	ds_bpermute_b32 v143, v133, v163
	ds_bpermute_b32 v142, v133, v162
	ds_bpermute_b32 v145, v133, v165
	ds_bpermute_b32 v144, v133, v164
	s_mov_b64 s[16:17], 0x10000
	v_lshl_add_u64 v[134:135], v[140:141], 0, s[16:17]
	s_waitcnt lgkmcnt(3)
	v_lshlrev_b32_e32 v136, 16, v143
	v_and_b32_e32 v137, 0xffff0000, v143
	s_waitcnt lgkmcnt(2)
	v_and_b32_e32 v143, 0xffff0000, v142
	v_lshlrev_b32_e32 v142, 16, v142
	v_pk_fma_f32 v[96:97], v[136:137], s[96:97], v[96:97] op_sel_hi:[1,0,1]
	v_pk_fma_f32 v[94:95], v[142:143], s[96:97], v[94:95] op_sel_hi:[1,0,1]
	s_waitcnt lgkmcnt(1)
	v_lshlrev_b32_e32 v136, 16, v145
	v_and_b32_e32 v137, 0xffff0000, v145
	s_waitcnt lgkmcnt(0)
	v_and_b32_e32 v145, 0xffff0000, v144
	v_lshlrev_b32_e32 v144, 16, v144
	v_pk_fma_f32 v[92:93], v[136:137], s[96:97], v[92:93] op_sel_hi:[1,0,1]
	v_pk_fma_f32 v[90:91], v[144:145], s[96:97], v[90:91] op_sel_hi:[1,0,1]
	v_cvt_pk_bf16_f32 v94, v94, v95
	v_cvt_pk_bf16_f32 v95, v96, v97
	v_cvt_pk_bf16_f32 v96, v90, v91
	v_cvt_pk_bf16_f32 v93, v92, v93
	s_nop 1
	ds_bpermute_b32 v90, v132, v94
	ds_bpermute_b32 v91, v132, v95
	ds_bpermute_b32 v92, v132, v96
	ds_bpermute_b32 v93, v132, v93
	s_waitcnt lgkmcnt(0)
	global_store_dwordx4 v[134:135], v[90:93], off
	s_waitcnt vmcnt(15)
	ds_bpermute_b32 v143, v133, v167
	ds_bpermute_b32 v142, v133, v166
	ds_bpermute_b32 v145, v133, v169
	ds_bpermute_b32 v144, v133, v168
	s_waitcnt lgkmcnt(3)
	v_lshlrev_b32_e32 v136, 16, v143
	v_and_b32_e32 v137, 0xffff0000, v143
	s_waitcnt lgkmcnt(2)
	v_and_b32_e32 v143, 0xffff0000, v142
	v_lshlrev_b32_e32 v142, 16, v142
	v_pk_fma_f32 v[88:89], v[136:137], s[96:97], v[88:89] op_sel_hi:[1,0,1]
	v_pk_fma_f32 v[86:87], v[142:143], s[96:97], v[86:87] op_sel_hi:[1,0,1]
	s_waitcnt lgkmcnt(1)
	v_lshlrev_b32_e32 v136, 16, v145
	v_and_b32_e32 v137, 0xffff0000, v145
	s_waitcnt lgkmcnt(0)
	v_and_b32_e32 v145, 0xffff0000, v144
	v_lshlrev_b32_e32 v144, 16, v144
	v_pk_fma_f32 v[84:85], v[136:137], s[96:97], v[84:85] op_sel_hi:[1,0,1]
	v_pk_fma_f32 v[82:83], v[144:145], s[96:97], v[82:83] op_sel_hi:[1,0,1]
	v_cvt_pk_bf16_f32 v86, v86, v87
	v_cvt_pk_bf16_f32 v87, v88, v89
	v_cvt_pk_bf16_f32 v88, v82, v83
	v_cvt_pk_bf16_f32 v85, v84, v85
	s_nop 1
	ds_bpermute_b32 v82, v132, v86
	ds_bpermute_b32 v83, v132, v87
	ds_bpermute_b32 v84, v132, v88
	ds_bpermute_b32 v85, v132, v85
	s_waitcnt lgkmcnt(0)
	global_store_dwordx4 v[134:135], v[82:85], off offset:256
	s_waitcnt vmcnt(15)
	ds_bpermute_b32 v143, v133, v171
	ds_bpermute_b32 v142, v133, v170
	ds_bpermute_b32 v145, v133, v173
	ds_bpermute_b32 v144, v133, v172
	s_mov_b64 s[16:17], 0x18000
	v_lshl_add_u64 v[134:135], v[140:141], 0, s[16:17]
	s_waitcnt lgkmcnt(3)
	v_lshlrev_b32_e32 v136, 16, v143
	v_and_b32_e32 v137, 0xffff0000, v143
	s_waitcnt lgkmcnt(2)
	v_and_b32_e32 v143, 0xffff0000, v142
	v_lshlrev_b32_e32 v142, 16, v142
	v_pk_fma_f32 v[80:81], v[136:137], s[96:97], v[80:81] op_sel_hi:[1,0,1]
	v_pk_fma_f32 v[78:79], v[142:143], s[96:97], v[78:79] op_sel_hi:[1,0,1]
	s_waitcnt lgkmcnt(1)
	v_lshlrev_b32_e32 v136, 16, v145
	v_and_b32_e32 v137, 0xffff0000, v145
	s_waitcnt lgkmcnt(0)
	v_and_b32_e32 v145, 0xffff0000, v144
	v_lshlrev_b32_e32 v144, 16, v144
	v_pk_fma_f32 v[76:77], v[136:137], s[96:97], v[76:77] op_sel_hi:[1,0,1]
	v_pk_fma_f32 v[74:75], v[144:145], s[96:97], v[74:75] op_sel_hi:[1,0,1]
	v_cvt_pk_bf16_f32 v78, v78, v79
	v_cvt_pk_bf16_f32 v79, v80, v81
	v_cvt_pk_bf16_f32 v80, v74, v75
	v_cvt_pk_bf16_f32 v77, v76, v77
	s_nop 1
	ds_bpermute_b32 v74, v132, v78
	ds_bpermute_b32 v75, v132, v79
	ds_bpermute_b32 v76, v132, v80
	ds_bpermute_b32 v77, v132, v77
	s_waitcnt lgkmcnt(0)
; #define GAS __attribute__((address_space(1)))
; __device__ __forceinline__ v4u tr4(int a, v4u x) { return (v4u){bperm(a, x.x), bperm(a, x.y), bperm(a, x.z), bperm(a, x.w)}; }
; __device__ __forceinline__ v4u pack8(const f32x4& a, const f32x4& b) { return (v4u){pg8::cvt_pk_bf16(a[0], a[1]), pg8::cvt_pk_bf16(a[2], a[3]), pg8::cvt_pk_bf16(b[0], b[1]), pg8::cvt_pk_bf16(b[2], b[3])}; }
;     __device__ __forceinline__ bool operator()(AccT& acc, const Unit& u, int wr, int wc, int fr, int fq) const {
;     ...
;             for (int m = 0; m < 4; ++m) { const size_t off = (size_t)(row0 + ai * 128 + m * 16) * D + col0;
; #pragma unroll
;                 for (int bj = 0; bj < 2; ++bj) { const v4u r = tr4(t.push, *(const GAS v4u*)(src + off + bj * 128));
;                     const f32x4 y0 = (f32x4){bflo(r.x), bfhi(r.x), bflo(r.y), bfhi(r.y)} * ca + acc[ai][bj][m][0] * cb, y1 = (f32x4){bflo(r.z), bfhi(r.z), bflo(r.w), bfhi(r.w)} * ca + acc[ai][bj][m][1] * cb;
;                     *(GAS v4u*)(dst + off + bj * 128) = tr4(t.pull, pack8(y0, y1)); } }
	global_store_dwordx4 v[134:135], v[74:77], off
	s_waitcnt vmcnt(15)
	ds_bpermute_b32 v143, v133, v175
	ds_bpermute_b32 v142, v133, v174
	ds_bpermute_b32 v145, v133, v177
	ds_bpermute_b32 v144, v133, v176
	s_waitcnt lgkmcnt(3)
	v_lshlrev_b32_e32 v136, 16, v143
	v_and_b32_e32 v137, 0xffff0000, v143
	s_waitcnt lgkmcnt(2)
	v_and_b32_e32 v143, 0xffff0000, v142
	v_lshlrev_b32_e32 v142, 16, v142
	v_pk_fma_f32 v[72:73], v[136:137], s[96:97], v[72:73] op_sel_hi:[1,0,1]
	v_pk_fma_f32 v[70:71], v[142:143], s[96:97], v[70:71] op_sel_hi:[1,0,1]
	s_waitcnt lgkmcnt(1)
	v_lshlrev_b32_e32 v136, 16, v145
	v_and_b32_e32 v137, 0xffff0000, v145
	s_waitcnt lgkmcnt(0)
	v_and_b32_e32 v145, 0xffff0000, v144
	v_lshlrev_b32_e32 v144, 16, v144
	v_pk_fma_f32 v[68:69], v[136:137], s[96:97], v[68:69] op_sel_hi:[1,0,1]
	v_pk_fma_f32 v[66:67], v[144:145], s[96:97], v[66:67] op_sel_hi:[1,0,1]
	v_cvt_pk_bf16_f32 v70, v70, v71
	v_cvt_pk_bf16_f32 v71, v72, v73
	v_cvt_pk_bf16_f32 v72, v66, v67
	v_cvt_pk_bf16_f32 v69, v68, v69
	s_nop 1
	ds_bpermute_b32 v66, v132, v70
	ds_bpermute_b32 v67, v132, v71
	ds_bpermute_b32 v68, v132, v72
	ds_bpermute_b32 v69, v132, v69
	s_waitcnt lgkmcnt(0)
	global_store_dwordx4 v[134:135], v[66:69], off offset:256
	s_waitcnt vmcnt(15)
	ds_bpermute_b32 v143, v133, v179
	ds_bpermute_b32 v142, v133, v178
	ds_bpermute_b32 v145, v133, v181
	ds_bpermute_b32 v144, v133, v180
	s_mov_b64 s[16:17], 0x40000
	v_lshl_add_u64 v[134:135], v[140:141], 0, s[16:17]
	s_waitcnt lgkmcnt(3)
	v_lshlrev_b32_e32 v136, 16, v143
	v_and_b32_e32 v137, 0xffff0000, v143
	s_waitcnt lgkmcnt(2)
	v_and_b32_e32 v143, 0xffff0000, v142
	v_lshlrev_b32_e32 v142, 16, v142
	v_pk_fma_f32 v[64:65], v[136:137], s[96:97], v[64:65] op_sel_hi:[1,0,1]
	v_pk_fma_f32 v[62:63], v[142:143], s[96:97], v[62:63] op_sel_hi:[1,0,1]
	s_waitcnt lgkmcnt(1)
	v_lshlrev_b32_e32 v136, 16, v145
	v_and_b32_e32 v137, 0xffff0000, v145
	s_waitcnt lgkmcnt(0)
	v_and_b32_e32 v145, 0xffff0000, v144
	v_lshlrev_b32_e32 v144, 16, v144
	v_pk_fma_f32 v[60:61], v[136:137], s[96:97], v[60:61] op_sel_hi:[1,0,1]
	v_pk_fma_f32 v[58:59], v[144:145], s[96:97], v[58:59] op_sel_hi:[1,0,1]
	v_cvt_pk_bf16_f32 v62, v62, v63
	v_cvt_pk_bf16_f32 v63, v64, v65
	v_cvt_pk_bf16_f32 v64, v58, v59
	v_cvt_pk_bf16_f32 v61, v60, v61
	s_nop 1
	ds_bpermute_b32 v58, v132, v62
	ds_bpermute_b32 v59, v132, v63
	ds_bpermute_b32 v60, v132, v64
	ds_bpermute_b32 v61, v132, v61
	s_waitcnt lgkmcnt(0)
	global_store_dwordx4 v[134:135], v[58:61], off
	s_waitcnt vmcnt(15)
	ds_bpermute_b32 v143, v133, v183
	ds_bpermute_b32 v142, v133, v182
	ds_bpermute_b32 v145, v133, v185
	ds_bpermute_b32 v144, v133, v184
	s_waitcnt lgkmcnt(3)
	v_lshlrev_b32_e32 v136, 16, v143
	v_and_b32_e32 v137, 0xffff0000, v143
	s_waitcnt lgkmcnt(2)
	v_and_b32_e32 v143, 0xffff0000, v142
	v_lshlrev_b32_e32 v142, 16, v142
	v_pk_fma_f32 v[56:57], v[136:137], s[96:97], v[56:57] op_sel_hi:[1,0,1]
	v_pk_fma_f32 v[54:55], v[142:143], s[96:97], v[54:55] op_sel_hi:[1,0,1]
	s_waitcnt lgkmcnt(1)
	v_lshlrev_b32_e32 v136, 16, v145
	v_and_b32_e32 v137, 0xffff0000, v145
	s_waitcnt lgkmcnt(0)
	v_and_b32_e32 v145, 0xffff0000, v144
	v_lshlrev_b32_e32 v144, 16, v144
	v_pk_fma_f32 v[52:53], v[136:137], s[96:97], v[52:53] op_sel_hi:[1,0,1]
	v_pk_fma_f32 v[50:51], v[144:145], s[96:97], v[50:51] op_sel_hi:[1,0,1]
	v_cvt_pk_bf16_f32 v54, v54, v55
	v_cvt_pk_bf16_f32 v55, v56, v57
	v_cvt_pk_bf16_f32 v56, v50, v51
	v_cvt_pk_bf16_f32 v53, v52, v53
	s_nop 1
	ds_bpermute_b32 v50, v132, v54
	ds_bpermute_b32 v51, v132, v55
	ds_bpermute_b32 v52, v132, v56
	ds_bpermute_b32 v53, v132, v53
	s_waitcnt lgkmcnt(0)
	global_store_dwordx4 v[134:135], v[50:53], off offset:256
	s_waitcnt vmcnt(15)
	ds_bpermute_b32 v143, v133, v187
	ds_bpermute_b32 v142, v133, v186
	ds_bpermute_b32 v145, v133, v189
	ds_bpermute_b32 v144, v133, v188
	s_mov_b64 s[16:17], 0x48000
	v_lshl_add_u64 v[134:135], v[140:141], 0, s[16:17]
	s_waitcnt lgkmcnt(3)
	v_lshlrev_b32_e32 v136, 16, v143
	v_and_b32_e32 v137, 0xffff0000, v143
	s_waitcnt lgkmcnt(2)
	v_and_b32_e32 v143, 0xffff0000, v142
	v_lshlrev_b32_e32 v142, 16, v142
	v_pk_fma_f32 v[48:49], v[136:137], s[96:97], v[48:49] op_sel_hi:[1,0,1]
	v_pk_fma_f32 v[46:47], v[142:143], s[96:97], v[46:47] op_sel_hi:[1,0,1]
	s_waitcnt lgkmcnt(1)
	v_lshlrev_b32_e32 v136, 16, v145
	v_and_b32_e32 v137, 0xffff0000, v145
	s_waitcnt lgkmcnt(0)
	v_and_b32_e32 v145, 0xffff0000, v144
	v_lshlrev_b32_e32 v144, 16, v144
	v_pk_fma_f32 v[44:45], v[136:137], s[96:97], v[44:45] op_sel_hi:[1,0,1]
	v_pk_fma_f32 v[42:43], v[144:145], s[96:97], v[42:43] op_sel_hi:[1,0,1]
	v_cvt_pk_bf16_f32 v46, v46, v47
	v_cvt_pk_bf16_f32 v47, v48, v49
	v_cvt_pk_bf16_f32 v48, v42, v43
	v_cvt_pk_bf16_f32 v45, v44, v45
	s_nop 1
	ds_bpermute_b32 v42, v132, v46
	ds_bpermute_b32 v43, v132, v47
	ds_bpermute_b32 v44, v132, v48
	ds_bpermute_b32 v45, v132, v45
	s_waitcnt lgkmcnt(0)
	global_store_dwordx4 v[134:135], v[42:45], off
	s_waitcnt vmcnt(15)
	ds_bpermute_b32 v143, v133, v191
	ds_bpermute_b32 v142, v133, v190
	ds_bpermute_b32 v145, v133, v193
	ds_bpermute_b32 v144, v133, v192
	s_waitcnt lgkmcnt(3)
	v_lshlrev_b32_e32 v136, 16, v143
	v_and_b32_e32 v137, 0xffff0000, v143
	s_waitcnt lgkmcnt(2)
	v_and_b32_e32 v143, 0xffff0000, v142
	v_lshlrev_b32_e32 v142, 16, v142
	v_pk_fma_f32 v[40:41], v[136:137], s[96:97], v[40:41] op_sel_hi:[1,0,1]
	v_pk_fma_f32 v[38:39], v[142:143], s[96:97], v[38:39] op_sel_hi:[1,0,1]
	s_waitcnt lgkmcnt(1)
	v_lshlrev_b32_e32 v136, 16, v145
	v_and_b32_e32 v137, 0xffff0000, v145
	s_waitcnt lgkmcnt(0)
; #define PG8_BAR __builtin_amdgcn_s_barrier()
; #define GAS __attribute__((address_space(1)))
; __device__ __forceinline__ v4u tr4(int a, v4u x) { return (v4u){bperm(a, x.x), bperm(a, x.y), bperm(a, x.z), bperm(a, x.w)}; }
; __device__ __forceinline__ v4u pack8(const f32x4& a, const f32x4& b) { return (v4u){pg8::cvt_pk_bf16(a[0], a[1]), pg8::cvt_pk_bf16(a[2], a[3]), pg8::cvt_pk_bf16(b[0], b[1]), pg8::cvt_pk_bf16(b[2], b[3])}; }
; template <class Epi, class Sched, bool ALIGN_EPI = false, bool SP2 = false>
; __device__ __forceinline__ void gemm_phase(PG8_LAS unsigned char* lds, const Gemm g, const Sched& S, const Epi& E, const int wave_id) {
;     ...
;         if (!has_next) break;
;         if (!keep_acc) {
; #pragma unroll
;         for (int a = 0; a < 2; ++a)
; #pragma unroll
;             for (int b = 0; b < 2; ++b)
; #pragma unroll
;                 for (int m = 0; m < 4; ++m)
; #pragma unroll
;                     for (int n = 0; n < 2; ++n) acc[a][b][m][n] = (f32x4){0.f, 0.f, 0.f, 0.f};
;         }
;         cur = nxt; cA = nA; cB = nB; ++ui;
;         if constexpr (ALIGN_EPI) { if (wr == 1) PG8_BAR; }
;     }
;     __device__ __forceinline__ bool operator()(AccT& acc, const Unit& u, int wr, int wc, int fr, int fq) const {
;     ...
;             for (int m = 0; m < 4; ++m) { const size_t off = (size_t)(row0 + ai * 128 + m * 16) * D + col0;
; #pragma unroll
;                 for (int bj = 0; bj < 2; ++bj) { const v4u r = tr4(t.push, *(const GAS v4u*)(src + off + bj * 128));
;                     const f32x4 y0 = (f32x4){bflo(r.x), bfhi(r.x), bflo(r.y), bfhi(r.y)} * ca + acc[ai][bj][m][0] * cb, y1 = (f32x4){bflo(r.z), bfhi(r.z), bflo(r.w), bfhi(r.w)} * ca + acc[ai][bj][m][1] * cb;
;                     *(GAS v4u*)(dst + off + bj * 128) = tr4(t.pull, pack8(y0, y1)); } }
	v_and_b32_e32 v145, 0xffff0000, v144
	v_lshlrev_b32_e32 v144, 16, v144
	v_pk_fma_f32 v[36:37], v[136:137], s[96:97], v[36:37] op_sel_hi:[1,0,1]
	v_pk_fma_f32 v[34:35], v[144:145], s[96:97], v[34:35] op_sel_hi:[1,0,1]
	v_cvt_pk_bf16_f32 v38, v38, v39
	v_cvt_pk_bf16_f32 v39, v40, v41
	v_cvt_pk_bf16_f32 v40, v34, v35
	v_cvt_pk_bf16_f32 v37, v36, v37
	s_nop 1
	ds_bpermute_b32 v34, v132, v38
	ds_bpermute_b32 v35, v132, v39
	ds_bpermute_b32 v36, v132, v40
	ds_bpermute_b32 v37, v132, v37
	s_waitcnt lgkmcnt(0)
	global_store_dwordx4 v[134:135], v[34:37], off offset:256
	s_waitcnt vmcnt(14)
	ds_bpermute_b32 v143, v133, v127
	ds_bpermute_b32 v142, v133, v126
	ds_bpermute_b32 v145, v133, v129
	ds_bpermute_b32 v144, v133, v128
	s_mov_b64 s[16:17], 0x50000
	v_lshl_add_u64 v[134:135], v[140:141], 0, s[16:17]
	s_waitcnt lgkmcnt(3)
	v_lshlrev_b32_e32 v136, 16, v143
	v_and_b32_e32 v137, 0xffff0000, v143
	s_waitcnt lgkmcnt(2)
	v_and_b32_e32 v143, 0xffff0000, v142
	v_lshlrev_b32_e32 v142, 16, v142
	v_pk_fma_f32 v[32:33], v[136:137], s[96:97], v[32:33] op_sel_hi:[1,0,1]
	v_pk_fma_f32 v[30:31], v[142:143], s[96:97], v[30:31] op_sel_hi:[1,0,1]
	s_waitcnt lgkmcnt(1)
	v_lshlrev_b32_e32 v136, 16, v145
	v_and_b32_e32 v137, 0xffff0000, v145
	s_waitcnt lgkmcnt(0)
	v_and_b32_e32 v145, 0xffff0000, v144
	v_lshlrev_b32_e32 v144, 16, v144
	v_pk_fma_f32 v[28:29], v[136:137], s[96:97], v[28:29] op_sel_hi:[1,0,1]
	v_pk_fma_f32 v[26:27], v[144:145], s[96:97], v[26:27] op_sel_hi:[1,0,1]
	v_cvt_pk_bf16_f32 v30, v30, v31
	v_cvt_pk_bf16_f32 v31, v32, v33
	v_cvt_pk_bf16_f32 v32, v26, v27
	v_cvt_pk_bf16_f32 v29, v28, v29
	s_nop 1
	ds_bpermute_b32 v26, v132, v30
	ds_bpermute_b32 v27, v132, v31
	ds_bpermute_b32 v28, v132, v32
	ds_bpermute_b32 v29, v132, v29
	s_waitcnt lgkmcnt(0)
	global_store_dwordx4 v[134:135], v[26:29], off
	s_waitcnt vmcnt(13)
	ds_bpermute_b32 v143, v133, v119
	ds_bpermute_b32 v142, v133, v118
	ds_bpermute_b32 v145, v133, v121
	ds_bpermute_b32 v144, v133, v120
	s_waitcnt lgkmcnt(3)
	v_lshlrev_b32_e32 v136, 16, v143
	v_and_b32_e32 v137, 0xffff0000, v143
	s_waitcnt lgkmcnt(2)
	v_and_b32_e32 v143, 0xffff0000, v142
	v_lshlrev_b32_e32 v142, 16, v142
	v_pk_fma_f32 v[24:25], v[136:137], s[96:97], v[24:25] op_sel_hi:[1,0,1]
	v_pk_fma_f32 v[22:23], v[142:143], s[96:97], v[22:23] op_sel_hi:[1,0,1]
	s_waitcnt lgkmcnt(1)
	v_lshlrev_b32_e32 v136, 16, v145
	v_and_b32_e32 v137, 0xffff0000, v145
	s_waitcnt lgkmcnt(0)
	v_and_b32_e32 v145, 0xffff0000, v144
	v_lshlrev_b32_e32 v144, 16, v144
	v_pk_fma_f32 v[20:21], v[136:137], s[96:97], v[20:21] op_sel_hi:[1,0,1]
	v_pk_fma_f32 v[18:19], v[144:145], s[96:97], v[18:19] op_sel_hi:[1,0,1]
	v_cvt_pk_bf16_f32 v22, v22, v23
	v_cvt_pk_bf16_f32 v23, v24, v25
	v_cvt_pk_bf16_f32 v24, v18, v19
	v_cvt_pk_bf16_f32 v21, v20, v21
	s_nop 1
	ds_bpermute_b32 v18, v132, v22
	ds_bpermute_b32 v19, v132, v23
	ds_bpermute_b32 v20, v132, v24
	ds_bpermute_b32 v21, v132, v21
	s_waitcnt lgkmcnt(0)
	global_store_dwordx4 v[134:135], v[18:21], off offset:256
	s_waitcnt vmcnt(12)
	ds_bpermute_b32 v143, v133, v111
	ds_bpermute_b32 v142, v133, v110
	ds_bpermute_b32 v145, v133, v113
	ds_bpermute_b32 v144, v133, v112
	s_mov_b64 s[16:17], 0x58000
	v_lshl_add_u64 v[134:135], v[140:141], 0, s[16:17]
	s_waitcnt lgkmcnt(3)
	v_lshlrev_b32_e32 v136, 16, v143
	v_and_b32_e32 v137, 0xffff0000, v143
	s_waitcnt lgkmcnt(2)
	v_and_b32_e32 v143, 0xffff0000, v142
	v_lshlrev_b32_e32 v142, 16, v142
	v_pk_fma_f32 v[16:17], v[136:137], s[96:97], v[16:17] op_sel_hi:[1,0,1]
	v_pk_fma_f32 v[14:15], v[142:143], s[96:97], v[14:15] op_sel_hi:[1,0,1]
	s_waitcnt lgkmcnt(1)
	v_lshlrev_b32_e32 v136, 16, v145
	v_and_b32_e32 v137, 0xffff0000, v145
	s_waitcnt lgkmcnt(0)
	v_and_b32_e32 v145, 0xffff0000, v144
	v_lshlrev_b32_e32 v144, 16, v144
	v_pk_fma_f32 v[12:13], v[136:137], s[96:97], v[12:13] op_sel_hi:[1,0,1]
	v_pk_fma_f32 v[10:11], v[144:145], s[96:97], v[10:11] op_sel_hi:[1,0,1]
	v_cvt_pk_bf16_f32 v14, v14, v15
	v_cvt_pk_bf16_f32 v15, v16, v17
	v_cvt_pk_bf16_f32 v16, v10, v11
	v_cvt_pk_bf16_f32 v13, v12, v13
	s_nop 1
	ds_bpermute_b32 v10, v132, v14
	ds_bpermute_b32 v11, v132, v15
	ds_bpermute_b32 v12, v132, v16
	ds_bpermute_b32 v13, v132, v13
	s_waitcnt lgkmcnt(0)
	global_store_dwordx4 v[134:135], v[10:13], off
	s_waitcnt vmcnt(11)
	ds_bpermute_b32 v143, v133, v103
	ds_bpermute_b32 v142, v133, v102
	ds_bpermute_b32 v145, v133, v105
	ds_bpermute_b32 v144, v133, v104
	s_waitcnt lgkmcnt(3)
	v_lshlrev_b32_e32 v136, 16, v143
	v_and_b32_e32 v137, 0xffff0000, v143
	s_waitcnt lgkmcnt(2)
	v_and_b32_e32 v143, 0xffff0000, v142
	v_lshlrev_b32_e32 v142, 16, v142
	v_pk_fma_f32 v[8:9], v[136:137], s[96:97], v[8:9] op_sel_hi:[1,0,1]
	v_pk_fma_f32 v[6:7], v[142:143], s[96:97], v[6:7] op_sel_hi:[1,0,1]
	s_waitcnt lgkmcnt(1)
	v_lshlrev_b32_e32 v136, 16, v145
	v_and_b32_e32 v137, 0xffff0000, v145
	s_waitcnt lgkmcnt(0)
	v_and_b32_e32 v145, 0xffff0000, v144
	v_lshlrev_b32_e32 v144, 16, v144
	v_pk_fma_f32 v[4:5], v[136:137], s[96:97], v[4:5] op_sel_hi:[1,0,1]
	v_pk_fma_f32 v[2:3], v[144:145], s[96:97], v[2:3] op_sel_hi:[1,0,1]
	v_cvt_pk_bf16_f32 v6, v6, v7
	v_cvt_pk_bf16_f32 v7, v8, v9
	v_cvt_pk_bf16_f32 v8, v2, v3
	v_cvt_pk_bf16_f32 v5, v4, v5
	s_nop 1
	ds_bpermute_b32 v2, v132, v6
	ds_bpermute_b32 v3, v132, v7
	ds_bpermute_b32 v4, v132, v8
	ds_bpermute_b32 v5, v132, v5
	s_waitcnt lgkmcnt(0)
	global_store_dwordx4 v[134:135], v[2:5], off offset:256
	s_mov_b64 s[16:17], -1
	s_cbranch_vccnz .LBB0_1813
	s_andn2_b64 vcc, exec, s[2:3]
	s_cbranch_vccnz .LBB0_1812
	s_barrier
	s_branch .LBB0_1812

; #define PG8_STAGE(bufoff, gbase, voff) do { _Pragma("unroll") for (int _i = 0; _i < 2; ++_i) \
;         __builtin_amdgcn_global_load_lds((const unsigned*)((const char*)(gbase) + (voff)[_i]), (PG8_LAS unsigned*)(lds + (bufoff) + ldsw + _i * 8192), 16, 0, 0); } while (0)
; #define PG8_LDA(dst, b, h) do { _Pragma("unroll") for (int m = 0; m < 4; ++m) _Pragma("unroll") for (int k = 0; k < 2; ++k) dst[m][k] = *(const PG8_LAS bf16x8*)(lds + PG8_SA(b, h) + aoff + m * 2048 + k * 1024); } while (0)
; #define PG8_LDB(dst, b, h) do { _Pragma("unroll") for (int n = 0; n < 2; ++n) _Pragma("unroll") for (int k = 0; k < 2; ++k) dst[n][k] = *(const PG8_LAS bf16x8*)(lds + PG8_SB(b, h) + boff + n * 2048 + k * 1024); } while (0)
; #define PG8_WAIT_V(n) asm volatile("s_waitcnt vmcnt(" #n ")" ::: "memory")
; #define PG8_WAIT_VN(n) asm volatile("s_waitcnt vmcnt(%0)" :: "n"(n) : "memory")
; #define PG8_WAIT_L(n) asm volatile("s_waitcnt lgkmcnt(" #n ")" ::: "memory")
; #define PG8_BAR __builtin_amdgcn_s_barrier()
; #define PG8_SCHED __builtin_amdgcn_sched_barrier(0)
; template <class Epi, class Sched, bool ALIGN_EPI = false, bool SP2 = false>
; __device__ __forceinline__ void gemm_phase(PG8_LAS unsigned char* lds, const Gemm g, const Sched& S, const Epi& E, const int wave_id) {
;     ...
;             PG8_LDB(B0, 0, 0); PG8_LDB(B1, 0, 1); PG8_SCHED; PG8_LDA(At, 0, 0); PG8_STAGE(PG8_SA(1, 1), a1 + hstep, voffA);
;             PG8_WAIT_VN(8 + Epi::NS); if (strict) PG8_WAIT_V(8); PG8_WAIT_L(0); PG8_BAR; PG8_MMA(0, 0, At, B0); PG8_MMA(0, 1, At, B1); PG8_BAR; PG8_SCHED;
;             PG8_LDA(At, 0, 1); PG8_STAGE(PG8_SB(0, 0), b2, voffB); PG8_STAGE(PG8_SB(0, 1), b2 + hstep, voffB); PG8_STAGE(PG8_SA(0, 0), a2, voffA);
;             PG8_WAIT_VN(8 + Epi::NS); if (strict) PG8_WAIT_V(8); PG8_WAIT_L(0); PG8_BAR; PG8_MMA(1, 0, At, B0); PG8_MMA(1, 1, At, B1); PG8_BAR; PG8_SCHED;
;             PG8_LDB(B0, 1, 0); PG8_LDB(B1, 1, 1); PG8_SCHED; PG8_LDA(At, 1, 0); PG8_STAGE(PG8_SA(0, 1), a2 + hstep, voffA);
;             PG8_WAIT_V(8); PG8_WAIT_L(0); PG8_BAR; PG8_MMA(0, 0, At, B0); PG8_MMA(0, 1, At, B1); PG8_BAR; PG8_SCHED;
;             PG8_LDA(At, 1, 1); PG8_STAGE(PG8_SB(1, 0), b3, voffB); PG8_STAGE(PG8_SB(1, 1), b3 + hstep, voffB); PG8_STAGE(PG8_SA(1, 0), a3, voffA);
;             PG8_WAIT_V(8); PG8_WAIT_L(0); PG8_BAR; PG8_MMA(1, 0, At, B0); PG8_MMA(1, 1, At, B1); PG8_BAR; PG8_SCHED;
.LBB0_1952:
	s_waitcnt lgkmcnt(0)
	s_barrier
	s_setprio 1
	s_waitcnt lgkmcnt(0)
	v_mfma_f32_16x16x32_bf16 v[62:65], v[146:149], v[186:189], v[62:65]
	v_mfma_f32_16x16x32_bf16 v[58:61], v[154:157], v[186:189], v[58:61]
	v_mfma_f32_16x16x32_bf16 v[54:57], v[146:149], v[178:181], v[54:57]
	v_mfma_f32_16x16x32_bf16 v[50:53], v[154:157], v[178:181], v[50:53]
	v_mfma_f32_16x16x32_bf16 v[30:33], v[146:149], v[170:173], v[30:33]
	v_mfma_f32_16x16x32_bf16 v[26:29], v[154:157], v[170:173], v[26:29]
	v_mfma_f32_16x16x32_bf16 v[22:25], v[146:149], v[162:165], v[22:25]
	v_mfma_f32_16x16x32_bf16 v[18:21], v[154:157], v[162:165], v[18:21]
	v_mfma_f32_16x16x32_bf16 v[62:65], v[150:153], v[190:193], v[62:65]
	v_mfma_f32_16x16x32_bf16 v[58:61], v[158:161], v[190:193], v[58:61]
	v_mfma_f32_16x16x32_bf16 v[54:57], v[150:153], v[182:185], v[54:57]
	v_mfma_f32_16x16x32_bf16 v[50:53], v[158:161], v[182:185], v[50:53]
	v_mfma_f32_16x16x32_bf16 v[30:33], v[150:153], v[174:177], v[30:33]
	v_mfma_f32_16x16x32_bf16 v[26:29], v[158:161], v[174:177], v[26:29]
	v_mfma_f32_16x16x32_bf16 v[22:25], v[150:153], v[166:169], v[22:25]
	v_mfma_f32_16x16x32_bf16 v[18:21], v[158:161], v[166:169], v[18:21]
	s_setprio 0
	s_setprio 1
	v_mfma_f32_16x16x32_bf16 v[46:49], v[130:133], v[186:189], v[46:49]
	v_mfma_f32_16x16x32_bf16 v[42:45], v[138:141], v[186:189], v[42:45]
	v_mfma_f32_16x16x32_bf16 v[38:41], v[130:133], v[178:181], v[38:41]
	v_mfma_f32_16x16x32_bf16 v[34:37], v[138:141], v[178:181], v[34:37]
	v_mfma_f32_16x16x32_bf16 v[14:17], v[130:133], v[170:173], v[14:17]
	v_mfma_f32_16x16x32_bf16 v[10:13], v[138:141], v[170:173], v[10:13]
	v_mfma_f32_16x16x32_bf16 v[6:9], v[130:133], v[162:165], v[6:9]
	v_mfma_f32_16x16x32_bf16 v[2:5], v[138:141], v[162:165], v[2:5]
	v_mfma_f32_16x16x32_bf16 v[46:49], v[134:137], v[190:193], v[46:49]
	v_mfma_f32_16x16x32_bf16 v[42:45], v[142:145], v[190:193], v[42:45]
	v_mfma_f32_16x16x32_bf16 v[38:41], v[134:137], v[182:185], v[38:41]
	v_mfma_f32_16x16x32_bf16 v[34:37], v[142:145], v[182:185], v[34:37]
	v_mfma_f32_16x16x32_bf16 v[14:17], v[134:137], v[174:177], v[14:17]
	v_mfma_f32_16x16x32_bf16 v[10:13], v[142:145], v[174:177], v[10:13]
	v_mfma_f32_16x16x32_bf16 v[6:9], v[134:137], v[166:169], v[6:9]
	v_mfma_f32_16x16x32_bf16 v[2:5], v[142:145], v[166:169], v[2:5]
	s_setprio 0
	s_barrier
	s_add_i32 s28, 0, 0x18000
	s_add_i32 s29, 0, 0x1c000
	v_add_u32_e32 v142, s28, v246
	v_add_u32_e32 v158, s29, v246
	ds_read_b128 v[130:133], v142
	ds_read_b128 v[134:137], v142 offset:1024
	ds_read_b128 v[138:141], v142 offset:2048
	ds_read_b128 v[142:145], v142 offset:3072
	ds_read_b128 v[146:149], v158
	ds_read_b128 v[150:153], v158 offset:1024
	ds_read_b128 v[154:157], v158 offset:2048
	ds_read_b128 v[158:161], v158 offset:3072
	s_add_u32 s26, s26, 0x40000
	s_addc_u32 s27, s27, 0
	s_mov_b32 m0, s52
	v_lshl_add_u64 v[194:195], s[26:27], 0, v[216:217]
	ds_read_b128 v[162:165], v247 offset:32768
	ds_read_b128 v[166:169], v247 offset:33792
	ds_read_b128 v[170:173], v247 offset:34816
	ds_read_b128 v[174:177], v247 offset:35840
	ds_read_b128 v[178:181], v247 offset:36864
	ds_read_b128 v[182:185], v247 offset:37888
	ds_read_b128 v[186:189], v247 offset:38912
	ds_read_b128 v[190:193], v247 offset:39936
	global_load_lds_dwordx4 v[194:195], off
	v_lshl_add_u64 v[194:195], s[26:27], 0, v[212:213]
	s_mov_b32 m0, s54
	s_nop 0
	global_load_lds_dwordx4 v[194:195], off
	s_waitcnt vmcnt(18)
	s_cmp_eq_u32 s100, 0
	s_cbranch_scc1 .Lthird_wait_relaxed_2
	s_waitcnt vmcnt(8)
.Lthird_wait_relaxed_2:
	s_waitcnt lgkmcnt(0)
	s_barrier
	s_setprio 1
	s_waitcnt lgkmcnt(0)
	v_mfma_f32_16x16x32_bf16 v[126:129], v[130:133], v[162:165], v[126:129]
	v_mfma_f32_16x16x32_bf16 v[122:125], v[138:141], v[162:165], v[122:125]
	v_mfma_f32_16x16x32_bf16 v[118:121], v[130:133], v[170:173], v[118:121]
	v_mfma_f32_16x16x32_bf16 v[114:117], v[138:141], v[170:173], v[114:117]
	v_mfma_f32_16x16x32_bf16 v[94:97], v[130:133], v[178:181], v[94:97]
	v_mfma_f32_16x16x32_bf16 v[90:93], v[138:141], v[178:181], v[90:93]
	v_mfma_f32_16x16x32_bf16 v[86:89], v[130:133], v[186:189], v[86:89]
	v_mfma_f32_16x16x32_bf16 v[82:85], v[138:141], v[186:189], v[82:85]
	v_mfma_f32_16x16x32_bf16 v[126:129], v[134:137], v[166:169], v[126:129]
	v_mfma_f32_16x16x32_bf16 v[122:125], v[142:145], v[166:169], v[122:125]
	v_mfma_f32_16x16x32_bf16 v[118:121], v[134:137], v[174:177], v[118:121]
	v_mfma_f32_16x16x32_bf16 v[114:117], v[142:145], v[174:177], v[114:117]
	v_mfma_f32_16x16x32_bf16 v[94:97], v[134:137], v[182:185], v[94:97]
	v_mfma_f32_16x16x32_bf16 v[90:93], v[142:145], v[182:185], v[90:93]
	v_mfma_f32_16x16x32_bf16 v[86:89], v[134:137], v[190:193], v[86:89]
	v_mfma_f32_16x16x32_bf16 v[82:85], v[142:145], v[190:193], v[82:85]
	s_setprio 0
	s_setprio 1
	v_mfma_f32_16x16x32_bf16 v[110:113], v[146:149], v[162:165], v[110:113]
	v_mfma_f32_16x16x32_bf16 v[106:109], v[154:157], v[162:165], v[106:109]
	v_mfma_f32_16x16x32_bf16 v[102:105], v[146:149], v[170:173], v[102:105]
	v_mfma_f32_16x16x32_bf16 v[98:101], v[154:157], v[170:173], v[98:101]
	v_mfma_f32_16x16x32_bf16 v[78:81], v[146:149], v[178:181], v[78:81]
	v_mfma_f32_16x16x32_bf16 v[74:77], v[154:157], v[178:181], v[74:77]
	v_mfma_f32_16x16x32_bf16 v[70:73], v[146:149], v[186:189], v[70:73]
	v_mfma_f32_16x16x32_bf16 v[66:69], v[154:157], v[186:189], v[66:69]
	v_mfma_f32_16x16x32_bf16 v[110:113], v[150:153], v[166:169], v[110:113]
	v_mfma_f32_16x16x32_bf16 v[106:109], v[158:161], v[166:169], v[106:109]
	v_mfma_f32_16x16x32_bf16 v[102:105], v[150:153], v[174:177], v[102:105]
	v_mfma_f32_16x16x32_bf16 v[98:101], v[158:161], v[174:177], v[98:101]
	v_mfma_f32_16x16x32_bf16 v[78:81], v[150:153], v[182:185], v[78:81]
	v_mfma_f32_16x16x32_bf16 v[74:77], v[158:161], v[182:185], v[74:77]
	v_mfma_f32_16x16x32_bf16 v[70:73], v[150:153], v[190:193], v[70:73]
	v_mfma_f32_16x16x32_bf16 v[66:69], v[158:161], v[190:193], v[66:69]
	s_setprio 0
	s_barrier
; #define PG8_STAGE(bufoff, gbase, voff) do { _Pragma("unroll") for (int _i = 0; _i < 2; ++_i) \
;         __builtin_amdgcn_global_load_lds((const unsigned*)((const char*)(gbase) + (voff)[_i]), (PG8_LAS unsigned*)(lds + (bufoff) + ldsw + _i * 8192), 16, 0, 0); } while (0)
; #define PG8_LDA(dst, b, h) do { _Pragma("unroll") for (int m = 0; m < 4; ++m) _Pragma("unroll") for (int k = 0; k < 2; ++k) dst[m][k] = *(const PG8_LAS bf16x8*)(lds + PG8_SA(b, h) + aoff + m * 2048 + k * 1024); } while (0)
; #define PG8_LDB(dst, b, h) do { _Pragma("unroll") for (int n = 0; n < 2; ++n) _Pragma("unroll") for (int k = 0; k < 2; ++k) dst[n][k] = *(const PG8_LAS bf16x8*)(lds + PG8_SB(b, h) + boff + n * 2048 + k * 1024); } while (0)
; #define PG8_WAIT_V(n) asm volatile("s_waitcnt vmcnt(" #n ")" ::: "memory")
; #define PG8_WAIT_VN(n) asm volatile("s_waitcnt vmcnt(%0)" :: "n"(n) : "memory")
; template <class Epi, class Sched, bool ALIGN_EPI = false, bool SP2 = false>
; __device__ __forceinline__ void gemm_phase(PG8_LAS unsigned char* lds, const Gemm g, const Sched& S, const Epi& E, const int wave_id) {
;     ...
;             int tz_ = __builtin_amdgcn_readfirstlane(t | (ui > 0 ? 0 : 1)); asm volatile("" : "+s"(tz_));
;             const bool strict = !(Epi::NS > 0 && tz_ == 0);
;             PG8_LDB(B0, 0, 0); PG8_LDB(B1, 0, 1); PG8_SCHED; PG8_LDA(At, 0, 0); PG8_STAGE(PG8_SA(1, 1), a1 + hstep, voffA);
;             PG8_WAIT_VN(8 + Epi::NS); if (strict) PG8_WAIT_V(8); PG8_WAIT_L(0); PG8_BAR; PG8_MMA(0, 0, At, B0); PG8_MMA(0, 1, At, B1); PG8_BAR; PG8_SCHED;
;             PG8_LDA(At, 0, 1); PG8_STAGE(PG8_SB(0, 0), b2, voffB); PG8_STAGE(PG8_SB(0, 1), b2 + hstep, voffB); PG8_STAGE(PG8_SA(0, 0), a2, voffA);
;             PG8_WAIT_VN(8 + Epi::NS); if (strict) PG8_WAIT_V(8); PG8_WAIT_L(0); PG8_BAR; PG8_MMA(1, 0, At, B0); PG8_MMA(1, 1, At, B1); PG8_BAR; PG8_SCHED;
;             PG8_LDB(B0, 1, 0); PG8_LDB(B1, 1, 1); PG8_SCHED; PG8_LDA(At, 1, 0); PG8_STAGE(PG8_SA(0, 1), a2 + hstep, voffA);
;             PG8_WAIT_V(8); PG8_WAIT_L(0); PG8_BAR; PG8_MMA(0, 0, At, B0); PG8_MMA(0, 1, At, B1); PG8_BAR; PG8_SCHED;
;             PG8_LDA(At, 1, 1); PG8_STAGE(PG8_SB(1, 0), b3, voffB); PG8_STAGE(PG8_SB(1, 1), b3 + hstep, voffB); PG8_STAGE(PG8_SA(1, 0), a3, voffA);
;             PG8_WAIT_V(8); PG8_WAIT_L(0); PG8_BAR; PG8_MMA(1, 0, At, B0); PG8_MMA(1, 1, At, B1); PG8_BAR; PG8_SCHED;
	s_add_i32 s26, s28, s39
	v_lshl_add_u64 v[194:195], v[232:233], 0, s[64:65]
	s_mov_b32 m0, s26
	ds_read_b128 v[162:165], v247 offset:49152
	ds_read_b128 v[166:169], v247 offset:50176
	ds_read_b128 v[170:173], v247 offset:51200
	ds_read_b128 v[174:177], v247 offset:52224
	ds_read_b128 v[178:181], v247 offset:53248
	ds_read_b128 v[182:185], v247 offset:54272
	ds_read_b128 v[186:189], v247 offset:55296
	ds_read_b128 v[190:193], v247 offset:56320
	global_load_lds_dwordx4 v[194:195], off
	s_add_i32 m0, s26, 0x2000
	s_add_u32 s24, s24, 0x40080
	v_lshl_add_u64 v[194:195], v[230:231], 0, s[64:65]
	s_addc_u32 s25, s25, 0
	s_add_i32 s26, s29, s39
	global_load_lds_dwordx4 v[194:195], off
	v_lshl_add_u64 v[194:195], s[24:25], 0, v[214:215]
	s_mov_b32 m0, s26
	s_nop 0
	global_load_lds_dwordx4 v[194:195], off
	v_lshl_add_u64 v[194:195], s[24:25], 0, v[210:211]
	s_add_i32 m0, s26, 0x2000
	s_nop 0
	global_load_lds_dwordx4 v[194:195], off
	v_lshl_add_u64 v[194:195], v[226:227], 0, s[64:65]
	s_mov_b32 m0, s57
	s_nop 0
	global_load_lds_dwordx4 v[194:195], off
	v_lshl_add_u64 v[194:195], v[228:229], 0, s[64:65]
	s_mov_b32 m0, s62
	s_nop 0
	global_load_lds_dwordx4 v[194:195], off
	s_waitcnt vmcnt(8)
	s_waitcnt lgkmcnt(0)
	s_barrier
	s_setprio 1
	s_waitcnt lgkmcnt(0)
	v_mfma_f32_16x16x32_bf16 v[62:65], v[130:133], v[162:165], v[62:65]
	v_mfma_f32_16x16x32_bf16 v[58:61], v[138:141], v[162:165], v[58:61]
	v_mfma_f32_16x16x32_bf16 v[54:57], v[130:133], v[170:173], v[54:57]
	v_mfma_f32_16x16x32_bf16 v[50:53], v[138:141], v[170:173], v[50:53]
	v_mfma_f32_16x16x32_bf16 v[30:33], v[130:133], v[178:181], v[30:33]
	v_mfma_f32_16x16x32_bf16 v[26:29], v[138:141], v[178:181], v[26:29]
	v_mfma_f32_16x16x32_bf16 v[22:25], v[130:133], v[186:189], v[22:25]
	v_mfma_f32_16x16x32_bf16 v[18:21], v[138:141], v[186:189], v[18:21]
	v_mfma_f32_16x16x32_bf16 v[62:65], v[134:137], v[166:169], v[62:65]
	v_mfma_f32_16x16x32_bf16 v[58:61], v[142:145], v[166:169], v[58:61]
	v_mfma_f32_16x16x32_bf16 v[54:57], v[134:137], v[174:177], v[54:57]
	v_mfma_f32_16x16x32_bf16 v[50:53], v[142:145], v[174:177], v[50:53]
	v_mfma_f32_16x16x32_bf16 v[30:33], v[134:137], v[182:185], v[30:33]
	v_mfma_f32_16x16x32_bf16 v[26:29], v[142:145], v[182:185], v[26:29]
	v_mfma_f32_16x16x32_bf16 v[22:25], v[134:137], v[190:193], v[22:25]
	v_mfma_f32_16x16x32_bf16 v[18:21], v[142:145], v[190:193], v[18:21]
	s_setprio 0
	s_setprio 1
	v_mfma_f32_16x16x32_bf16 v[46:49], v[146:149], v[162:165], v[46:49]
	v_mfma_f32_16x16x32_bf16 v[42:45], v[154:157], v[162:165], v[42:45]
	v_mfma_f32_16x16x32_bf16 v[38:41], v[146:149], v[170:173], v[38:41]
	v_mfma_f32_16x16x32_bf16 v[34:37], v[154:157], v[170:173], v[34:37]
	v_mfma_f32_16x16x32_bf16 v[14:17], v[146:149], v[178:181], v[14:17]
	v_mfma_f32_16x16x32_bf16 v[10:13], v[154:157], v[178:181], v[10:13]
	v_mfma_f32_16x16x32_bf16 v[6:9], v[146:149], v[186:189], v[6:9]
	v_mfma_f32_16x16x32_bf16 v[2:5], v[154:157], v[186:189], v[2:5]
	v_mfma_f32_16x16x32_bf16 v[46:49], v[150:153], v[166:169], v[46:49]
	v_mfma_f32_16x16x32_bf16 v[42:45], v[158:161], v[166:169], v[42:45]
	v_mfma_f32_16x16x32_bf16 v[38:41], v[150:153], v[174:177], v[38:41]
	v_mfma_f32_16x16x32_bf16 v[34:37], v[158:161], v[174:177], v[34:37]
	v_mfma_f32_16x16x32_bf16 v[14:17], v[150:153], v[182:185], v[14:17]
	v_mfma_f32_16x16x32_bf16 v[10:13], v[158:161], v[182:185], v[10:13]
	v_mfma_f32_16x16x32_bf16 v[6:9], v[150:153], v[190:193], v[6:9]
	v_mfma_f32_16x16x32_bf16 v[2:5], v[158:161], v[190:193], v[2:5]
	s_setprio 0
	s_barrier
	s_add_i32 s76, s76, 2
	s_add_u32 s22, s22, 0x100
	s_addc_u32 s23, s23, 0
	s_cmp_gt_u32 s76, 13
	s_cbranch_scc1 .LBB0_1957
.LBB0_1953:
	v_add_u32_e32 v130, s76, v248
	v_add_u32_e32 v130, 2, v130
	s_nop 0
	v_readfirstlane_b32 s24, v130
	s_nop 0
	s_mov_b32 s100, s24
	v_add_u32_e32 v130, 0, v246
	v_add_u32_e32 v131, 0x10000, v130
	v_add_u32_e32 v142, 0x14000, v130
	ds_read_b128 v[146:149], v131
	ds_read_b128 v[150:153], v131 offset:1024
	ds_read_b128 v[154:157], v131 offset:2048
	ds_read_b128 v[158:161], v131 offset:3072
	ds_read_b128 v[130:133], v142
	ds_read_b128 v[134:137], v142 offset:1024
	ds_read_b128 v[138:141], v142 offset:2048
	ds_read_b128 v[142:145], v142 offset:3072
	v_lshl_add_u64 v[194:195], v[224:225], 0, s[22:23]
	s_add_i32 m0, s41, 0xc000
	ds_read_b128 v[186:189], v247
	ds_read_b128 v[190:193], v247 offset:1024
	ds_read_b128 v[178:181], v247 offset:2048
	ds_read_b128 v[182:185], v247 offset:3072
	ds_read_b128 v[170:173], v247 offset:4096
	ds_read_b128 v[174:177], v247 offset:5120
	ds_read_b128 v[162:165], v247 offset:6144
	ds_read_b128 v[166:169], v247 offset:7168
	global_load_lds_dwordx4 v[194:195], off
	v_lshl_add_u64 v[194:195], v[222:223], 0, s[22:23]
	s_add_i32 m0, s41, 0xe000
	s_cmp_lg_u32 s24, 0
	global_load_lds_dwordx4 v[194:195], off
	s_waitcnt vmcnt(16)
	s_cselect_b64 s[28:29], -1, 0
	s_cmp_eq_u32 s24, 0
	s_cbranch_scc1 .LBB0_1955
	s_waitcnt vmcnt(8)

; __device__ __forceinline__ unsigned cvt_pk_bf16(float lo, float hi) { unsigned r; asm volatile("v_cvt_pk_bf16_f32 %0, %1, %2" : "=v"(r) : "v"(lo), "v"(hi)); return r; }
; #define PG8_STAGE(bufoff, gbase, voff) do { _Pragma("unroll") for (int _i = 0; _i < 2; ++_i) \
;         __builtin_amdgcn_global_load_lds((const unsigned*)((const char*)(gbase) + (voff)[_i]), (PG8_LAS unsigned*)(lds + (bufoff) + ldsw + _i * 8192), 16, 0, 0); } while (0)
; #define PG8_LDA(dst, b, h) do { _Pragma("unroll") for (int m = 0; m < 4; ++m) _Pragma("unroll") for (int k = 0; k < 2; ++k) dst[m][k] = *(const PG8_LAS bf16x8*)(lds + PG8_SA(b, h) + aoff + m * 2048 + k * 1024); } while (0)
; #define PG8_LDB(dst, b, h) do { _Pragma("unroll") for (int n = 0; n < 2; ++n) _Pragma("unroll") for (int k = 0; k < 2; ++k) dst[n][k] = *(const PG8_LAS bf16x8*)(lds + PG8_SB(b, h) + boff + n * 2048 + k * 1024); } while (0)
; #define PG8_SCHED __builtin_amdgcn_sched_barrier(0)
; #define GAS __attribute__((address_space(1)))
; __device__ __forceinline__ float siluf_(float x) { return x * sigmoidf_(x); }
; template <class Epi, class Sched, bool ALIGN_EPI = false, bool SP2 = false>
; __device__ __forceinline__ void gemm_phase(PG8_LAS unsigned char* lds, const Gemm g, const Sched& S, const Epi& E, const int wave_id) {
;     ...
;             PG8_LDB(B0, 0, 0); PG8_LDB(B1, 0, 1); PG8_SCHED; PG8_LDA(At, 0, 0); PG8_STAGE(PG8_SA(1, 1), a1 + hstep, voffA);
;     __device__ __forceinline__ bool operator()(AccT& acc, const Unit& u, int wr, int wc, int fr, int fq) const {
;     ...
;             for (int mp = 0; mp < 2; ++mp) { bf16* rowp = act + (size_t)(row0 + ai * 128 + mp * 32) * DFF + col0;
; #pragma unroll
;                 for (int bj = 0; bj < 2; ++bj) { unsigned pk[2][2];
; #pragma unroll
;                     for (int k = 0; k < 2; ++k) { const f32x4 g = acc[ai][bj][2 * mp + k][0], up = acc[ai][bj][2 * mp + k][1];
;                         pk[k][0] = pg8::cvt_pk_bf16(siluf_(g[0]) * up[0], siluf_(g[1]) * up[1]); pk[k][1] = pg8::cvt_pk_bf16(siluf_(g[2]) * up[2], siluf_(g[3]) * up[3]); }
;                     const auto sx = __builtin_amdgcn_permlane16_swap(pk[0][0], pk[1][0], false, false), sy = __builtin_amdgcn_permlane16_swap(pk[0][1], pk[1][1], false, false);
;                     *(GAS v4u*)(rowp + bj * 64) = (v4u){sx[0], sy[0], sx[1], sy[1]}; } }
.LBB0_1959:
	s_add_u32 s100, s68, 0x40080
	s_addc_u32 s101, s13, 0
	v_lshl_add_u64 v[194:195], s[100:101], 0, v[220:221]
	s_add_i32 m0, s41, 0xc000
	s_nop 0
	global_load_lds_dwordx4 v[194:195], off
	v_lshl_add_u64 v[194:195], s[100:101], 0, v[218:219]
	s_add_i32 m0, s41, 0xe000
	s_nop 0
	global_load_lds_dwordx4 v[194:195], off
	v_mul_f32_e32 v137, 0xbfb8aa3b, v126
	v_exp_f32_e32 v137, v137
	s_mov_b32 s11, s56
	v_mov_b32_e32 v130, v245
	s_mov_b32 s13, s38
	v_add_f32_e32 v137, 1.0, v137
	v_rcp_f32_e32 v137, v137
	v_mov_b32_e32 v131, v1
	s_lshl_b32 s19, s19, 7
	v_mul_f32_e32 v126, v126, v137
	v_mul_f32_e32 v122, v122, v126
	v_mul_f32_e32 v126, 0xbfb8aa3b, v127
	v_exp_f32_e32 v126, v126
	s_lshl_b32 s11, s11, 4
	s_lshl_b32 s18, s18, 8
	s_lshl_b32 s13, s13, 6
	v_add_f32_e32 v126, 1.0, v126
	v_rcp_f32_e32 v126, v126
	v_lshlrev_b32_e32 v132, 4, v130
	s_add_i32 s11, s11, s19
	v_lshlrev_b32_e32 v130, 2, v130
	v_mul_f32_e32 v126, v127, v126
	v_mul_f32_e32 v123, v123, v126
	v_cvt_pk_bf16_f32 v122, v122, v123
	v_mul_f32_e32 v123, 0xbfb8aa3b, v128
	v_exp_f32_e32 v123, v123
	v_and_b32_e32 v133, 16, v132
	v_and_or_b32 v132, v130, 8, s11
	s_add_i32 s13, s13, s18
	v_add_f32_e32 v123, 1.0, v123
	v_rcp_f32_e32 v123, v123
	v_add3_u32 v136, s13, v131, v133
	v_ashrrev_i32_e32 v133, 31, v132
	v_mov_b64_e32 v[130:131], s[4:5]
	v_mul_f32_e32 v123, v128, v123
	v_mul_f32_e32 v123, v124, v123
	v_mul_f32_e32 v124, 0xbfb8aa3b, v129
	v_exp_f32_e32 v124, v124
	s_movk_i32 s11, 0x1600
	v_mad_i64_i32 v[134:135], s[18:19], v136, s11, v[130:131]
	v_add_f32_e32 v124, 1.0, v124
	v_rcp_f32_e32 v124, v124
	v_lshlrev_b64 v[132:133], 1, v[132:133]
	v_lshl_add_u64 v[134:135], v[134:135], 0, v[132:133]
	s_andn2_b64 vcc, exec, s[6:7]
	v_mul_f32_e32 v124, v129, v124
	v_mul_f32_e32 v124, v125, v124
	v_cvt_pk_bf16_f32 v123, v123, v124
	v_mul_f32_e32 v124, 0xbfb8aa3b, v118
	v_exp_f32_e32 v124, v124
	s_nop 0
	v_add_f32_e32 v124, 1.0, v124
	v_rcp_f32_e32 v124, v124
	s_nop 0
	v_mul_f32_e32 v118, v118, v124
	v_mul_f32_e32 v114, v114, v118
	v_mul_f32_e32 v118, 0xbfb8aa3b, v119
	v_exp_f32_e32 v118, v118
	s_nop 0
	v_add_f32_e32 v118, 1.0, v118
	v_rcp_f32_e32 v118, v118
	s_nop 0
	v_mul_f32_e32 v118, v119, v118
	v_mul_f32_e32 v115, v115, v118
	v_cvt_pk_bf16_f32 v124, v114, v115
	v_mul_f32_e32 v114, 0xbfb8aa3b, v120
	v_exp_f32_e32 v114, v114
	v_mul_f32_e32 v115, 0xbfb8aa3b, v121
	v_exp_f32_e32 v115, v115
	v_permlane16_swap_b32_e32 v122, v124
	v_add_f32_e32 v114, 1.0, v114
	v_rcp_f32_e32 v114, v114
	v_add_f32_e32 v115, 1.0, v115
	v_rcp_f32_e32 v115, v115
	v_mul_f32_e32 v114, v120, v114
	v_mul_f32_e32 v114, v116, v114
	v_mul_f32_e32 v115, v121, v115
	v_mul_f32_e32 v115, v117, v115
	v_cvt_pk_bf16_f32 v125, v114, v115
	v_mul_f32_e32 v114, 0xbfb8aa3b, v110
	v_exp_f32_e32 v114, v114
	v_permlane16_swap_b32_e32 v123, v125
	global_store_dwordx4 v[134:135], v[122:125], off
	v_add_f32_e32 v114, 1.0, v114
	v_rcp_f32_e32 v114, v114
	s_nop 0
	v_mul_f32_e32 v110, v110, v114
	v_mul_f32_e32 v106, v106, v110
	v_mul_f32_e32 v110, 0xbfb8aa3b, v111
	v_exp_f32_e32 v110, v110
	s_nop 0
	v_add_f32_e32 v110, 1.0, v110
	v_rcp_f32_e32 v110, v110
	s_nop 0
	v_mul_f32_e32 v110, v111, v110
	v_mul_f32_e32 v107, v107, v110
	v_cvt_pk_bf16_f32 v106, v106, v107
	v_mul_f32_e32 v107, 0xbfb8aa3b, v112
	v_exp_f32_e32 v107, v107
	s_nop 0
	v_add_f32_e32 v107, 1.0, v107
	v_rcp_f32_e32 v107, v107
	s_nop 0
	v_mul_f32_e32 v107, v112, v107
	v_mul_f32_e32 v107, v108, v107
	v_mul_f32_e32 v108, 0xbfb8aa3b, v113
	v_exp_f32_e32 v108, v108
	s_nop 0
	v_add_f32_e32 v108, 1.0, v108
	v_rcp_f32_e32 v108, v108
	s_nop 0
	v_mul_f32_e32 v108, v113, v108
	v_mul_f32_e32 v108, v109, v108
	v_cvt_pk_bf16_f32 v107, v107, v108
	v_mul_f32_e32 v108, 0xbfb8aa3b, v102
	v_exp_f32_e32 v108, v108
	s_nop 0
	v_add_f32_e32 v108, 1.0, v108
	v_rcp_f32_e32 v108, v108
	s_nop 0
	v_mul_f32_e32 v102, v102, v108
	v_mul_f32_e32 v98, v98, v102
	v_mul_f32_e32 v102, 0xbfb8aa3b, v103
	v_exp_f32_e32 v102, v102
	s_nop 0
	v_add_f32_e32 v102, 1.0, v102
	v_rcp_f32_e32 v102, v102
	s_nop 0
	v_mul_f32_e32 v102, v103, v102
	v_mul_f32_e32 v99, v99, v102
	v_cvt_pk_bf16_f32 v108, v98, v99
	v_mul_f32_e32 v98, 0xbfb8aa3b, v104
	v_exp_f32_e32 v98, v98
	v_mul_f32_e32 v99, 0xbfb8aa3b, v105
	v_exp_f32_e32 v99, v99
	v_permlane16_swap_b32_e32 v106, v108
	v_add_f32_e32 v98, 1.0, v98
	v_rcp_f32_e32 v98, v98
	v_add_f32_e32 v99, 1.0, v99
	v_rcp_f32_e32 v99, v99
	v_mul_f32_e32 v98, v104, v98
	v_mul_f32_e32 v98, v100, v98
	v_mul_f32_e32 v100, 0xbfb8aa3b, v94
	v_exp_f32_e32 v100, v100
	v_mul_f32_e32 v99, v105, v99
	v_mul_f32_e32 v99, v101, v99
	v_cvt_pk_bf16_f32 v109, v98, v99
	v_add_f32_e32 v100, 1.0, v100
	v_rcp_f32_e32 v100, v100
	v_permlane16_swap_b32_e32 v107, v109
	global_store_dwordx4 v[134:135], v[106:109], off offset:128
	v_mul_f32_e32 v94, v94, v100
	v_mul_f32_e32 v90, v90, v94
	v_mul_f32_e32 v94, 0xbfb8aa3b, v95
	v_exp_f32_e32 v94, v94
	v_add_u32_e32 v98, 32, v136
	v_mad_i64_i32 v[98:99], s[18:19], v98, s11, v[130:131]
	v_add_f32_e32 v94, 1.0, v94
	v_rcp_f32_e32 v94, v94
	v_lshl_add_u64 v[98:99], v[98:99], 0, v[132:133]
	v_mul_f32_e32 v94, v95, v94
	v_mul_f32_e32 v91, v91, v94
	v_cvt_pk_bf16_f32 v90, v90, v91
	v_mul_f32_e32 v91, 0xbfb8aa3b, v96
	v_exp_f32_e32 v91, v91
	s_nop 0
	v_add_f32_e32 v91, 1.0, v91
	v_rcp_f32_e32 v91, v91
	s_nop 0
	v_mul_f32_e32 v91, v96, v91
	v_mul_f32_e32 v91, v92, v91
	v_mul_f32_e32 v92, 0xbfb8aa3b, v97
	v_exp_f32_e32 v92, v92
	s_nop 0
	v_add_f32_e32 v92, 1.0, v92
	v_rcp_f32_e32 v92, v92
	s_nop 0
	v_mul_f32_e32 v92, v97, v92
	v_mul_f32_e32 v92, v93, v92
	v_cvt_pk_bf16_f32 v91, v91, v92
	v_mul_f32_e32 v92, 0xbfb8aa3b, v86
	v_exp_f32_e32 v92, v92
	s_nop 0
	v_add_f32_e32 v92, 1.0, v92
; __device__ __forceinline__ unsigned cvt_pk_bf16(float lo, float hi) { unsigned r; asm volatile("v_cvt_pk_bf16_f32 %0, %1, %2" : "=v"(r) : "v"(lo), "v"(hi)); return r; }
; #define GAS __attribute__((address_space(1)))
; __device__ __forceinline__ float siluf_(float x) { return x * sigmoidf_(x); }
;     __device__ __forceinline__ bool operator()(AccT& acc, const Unit& u, int wr, int wc, int fr, int fq) const {
;     ...
;             for (int mp = 0; mp < 2; ++mp) { bf16* rowp = act + (size_t)(row0 + ai * 128 + mp * 32) * DFF + col0;
; #pragma unroll
;                 for (int bj = 0; bj < 2; ++bj) { unsigned pk[2][2];
; #pragma unroll
;                     for (int k = 0; k < 2; ++k) { const f32x4 g = acc[ai][bj][2 * mp + k][0], up = acc[ai][bj][2 * mp + k][1];
;                         pk[k][0] = pg8::cvt_pk_bf16(siluf_(g[0]) * up[0], siluf_(g[1]) * up[1]); pk[k][1] = pg8::cvt_pk_bf16(siluf_(g[2]) * up[2], siluf_(g[3]) * up[3]); }
;                     const auto sx = __builtin_amdgcn_permlane16_swap(pk[0][0], pk[1][0], false, false), sy = __builtin_amdgcn_permlane16_swap(pk[0][1], pk[1][1], false, false);
;                     *(GAS v4u*)(rowp + bj * 64) = (v4u){sx[0], sy[0], sx[1], sy[1]}; } }
	v_rcp_f32_e32 v92, v92
	s_nop 0
	v_mul_f32_e32 v86, v86, v92
	v_mul_f32_e32 v82, v82, v86
	v_mul_f32_e32 v86, 0xbfb8aa3b, v87
	v_exp_f32_e32 v86, v86
	s_nop 0
	v_add_f32_e32 v86, 1.0, v86
	v_rcp_f32_e32 v86, v86
	s_nop 0
	v_mul_f32_e32 v86, v87, v86
	v_mul_f32_e32 v83, v83, v86
	v_cvt_pk_bf16_f32 v92, v82, v83
	v_mul_f32_e32 v82, 0xbfb8aa3b, v88
	v_exp_f32_e32 v82, v82
	v_mul_f32_e32 v83, 0xbfb8aa3b, v89
	v_exp_f32_e32 v83, v83
	v_permlane16_swap_b32_e32 v90, v92
	v_add_f32_e32 v82, 1.0, v82
	v_rcp_f32_e32 v82, v82
	v_add_f32_e32 v83, 1.0, v83
	v_rcp_f32_e32 v83, v83
	v_mul_f32_e32 v82, v88, v82
	v_mul_f32_e32 v82, v84, v82
	v_mul_f32_e32 v83, v89, v83
	v_mul_f32_e32 v83, v85, v83
	v_cvt_pk_bf16_f32 v93, v82, v83
	v_mul_f32_e32 v82, 0xbfb8aa3b, v78
	v_exp_f32_e32 v82, v82
	v_permlane16_swap_b32_e32 v91, v93
	global_store_dwordx4 v[98:99], v[90:93], off
	v_add_f32_e32 v82, 1.0, v82
	v_rcp_f32_e32 v82, v82
	s_nop 0
	v_mul_f32_e32 v78, v78, v82
	v_mul_f32_e32 v74, v74, v78
	v_mul_f32_e32 v78, 0xbfb8aa3b, v79
	v_exp_f32_e32 v78, v78
	s_nop 0
	v_add_f32_e32 v78, 1.0, v78
	v_rcp_f32_e32 v78, v78
	s_nop 0
	v_mul_f32_e32 v78, v79, v78
	v_mul_f32_e32 v75, v75, v78
	v_cvt_pk_bf16_f32 v74, v74, v75
	v_mul_f32_e32 v75, 0xbfb8aa3b, v80
	v_exp_f32_e32 v75, v75
	s_nop 0
	v_add_f32_e32 v75, 1.0, v75
	v_rcp_f32_e32 v75, v75
	s_nop 0
	v_mul_f32_e32 v75, v80, v75
	v_mul_f32_e32 v75, v76, v75
	v_mul_f32_e32 v76, 0xbfb8aa3b, v81
	v_exp_f32_e32 v76, v76
	s_nop 0
	v_add_f32_e32 v76, 1.0, v76
	v_rcp_f32_e32 v76, v76
	s_nop 0
	v_mul_f32_e32 v76, v81, v76
	v_mul_f32_e32 v76, v77, v76
	v_cvt_pk_bf16_f32 v75, v75, v76
	v_mul_f32_e32 v76, 0xbfb8aa3b, v70
	v_exp_f32_e32 v76, v76
	s_nop 0
	v_add_f32_e32 v76, 1.0, v76
	v_rcp_f32_e32 v76, v76
	s_nop 0
	v_mul_f32_e32 v70, v70, v76
	v_mul_f32_e32 v66, v66, v70
	v_mul_f32_e32 v70, 0xbfb8aa3b, v71
	v_exp_f32_e32 v70, v70
	s_nop 0
	v_add_f32_e32 v70, 1.0, v70
	v_rcp_f32_e32 v70, v70
	s_nop 0
	v_mul_f32_e32 v70, v71, v70
	v_mul_f32_e32 v67, v67, v70
	v_cvt_pk_bf16_f32 v76, v66, v67
	v_mul_f32_e32 v66, 0xbfb8aa3b, v72
	v_exp_f32_e32 v66, v66
	v_mul_f32_e32 v67, 0xbfb8aa3b, v73
	v_exp_f32_e32 v67, v67
	v_permlane16_swap_b32_e32 v74, v76
	v_add_f32_e32 v66, 1.0, v66
	v_rcp_f32_e32 v66, v66
	v_add_f32_e32 v67, 1.0, v67
	v_rcp_f32_e32 v67, v67
	v_mul_f32_e32 v66, v72, v66
	v_mul_f32_e32 v66, v68, v66
	v_mul_f32_e32 v68, 0xbfb8aa3b, v62
	v_exp_f32_e32 v68, v68
	v_mul_f32_e32 v67, v73, v67
	v_mul_f32_e32 v67, v69, v67
	v_cvt_pk_bf16_f32 v77, v66, v67
	v_add_f32_e32 v68, 1.0, v68
	v_rcp_f32_e32 v68, v68
	v_permlane16_swap_b32_e32 v75, v77
	global_store_dwordx4 v[98:99], v[74:77], off offset:128
	v_mul_f32_e32 v62, v62, v68
	v_mul_f32_e32 v58, v58, v62
	v_mul_f32_e32 v62, 0xbfb8aa3b, v63
	v_exp_f32_e32 v62, v62
	v_add_u32_e32 v66, 0x80, v136
	v_mad_i64_i32 v[66:67], s[18:19], v66, s11, v[130:131]
	v_add_f32_e32 v62, 1.0, v62
	v_rcp_f32_e32 v62, v62
	v_lshl_add_u64 v[66:67], v[66:67], 0, v[132:133]
	v_mul_f32_e32 v62, v63, v62
	v_mul_f32_e32 v59, v59, v62
	v_cvt_pk_bf16_f32 v58, v58, v59
	v_mul_f32_e32 v59, 0xbfb8aa3b, v64
	v_exp_f32_e32 v59, v59
	s_nop 0
	v_add_f32_e32 v59, 1.0, v59
	v_rcp_f32_e32 v59, v59
	s_nop 0
	v_mul_f32_e32 v59, v64, v59
	v_mul_f32_e32 v59, v60, v59
	v_mul_f32_e32 v60, 0xbfb8aa3b, v65
	v_exp_f32_e32 v60, v60
	s_nop 0
	v_add_f32_e32 v60, 1.0, v60
	v_rcp_f32_e32 v60, v60
	s_nop 0
	v_mul_f32_e32 v60, v65, v60
	v_mul_f32_e32 v60, v61, v60
	v_cvt_pk_bf16_f32 v59, v59, v60
	v_mul_f32_e32 v60, 0xbfb8aa3b, v54
	v_exp_f32_e32 v60, v60
	s_nop 0
	v_add_f32_e32 v60, 1.0, v60
	v_rcp_f32_e32 v60, v60
	s_nop 0
	v_mul_f32_e32 v54, v54, v60
	v_mul_f32_e32 v50, v50, v54
	v_mul_f32_e32 v54, 0xbfb8aa3b, v55
	v_exp_f32_e32 v54, v54
	s_nop 0
	v_add_f32_e32 v54, 1.0, v54
	v_rcp_f32_e32 v54, v54
	s_nop 0
	v_mul_f32_e32 v54, v55, v54
	v_mul_f32_e32 v51, v51, v54
	v_cvt_pk_bf16_f32 v60, v50, v51
	v_mul_f32_e32 v50, 0xbfb8aa3b, v56
	v_exp_f32_e32 v50, v50
	v_mul_f32_e32 v51, 0xbfb8aa3b, v57
	v_exp_f32_e32 v51, v51
	v_permlane16_swap_b32_e32 v58, v60
	v_add_f32_e32 v50, 1.0, v50
	v_rcp_f32_e32 v50, v50
	v_add_f32_e32 v51, 1.0, v51
	v_rcp_f32_e32 v51, v51
	v_mul_f32_e32 v50, v56, v50
	v_mul_f32_e32 v50, v52, v50
	v_mul_f32_e32 v51, v57, v51
	v_mul_f32_e32 v51, v53, v51
	v_cvt_pk_bf16_f32 v61, v50, v51
	v_mul_f32_e32 v50, 0xbfb8aa3b, v46
	v_exp_f32_e32 v50, v50
	v_permlane16_swap_b32_e32 v59, v61
	global_store_dwordx4 v[66:67], v[58:61], off
	v_add_f32_e32 v50, 1.0, v50
	v_rcp_f32_e32 v50, v50
	s_nop 0
	v_mul_f32_e32 v46, v46, v50
	v_mul_f32_e32 v42, v42, v46
	v_mul_f32_e32 v46, 0xbfb8aa3b, v47
	v_exp_f32_e32 v46, v46
	s_nop 0
	v_add_f32_e32 v46, 1.0, v46
	v_rcp_f32_e32 v46, v46
	s_nop 0
	v_mul_f32_e32 v46, v47, v46
	v_mul_f32_e32 v43, v43, v46
	v_cvt_pk_bf16_f32 v42, v42, v43
	v_mul_f32_e32 v43, 0xbfb8aa3b, v48
	v_exp_f32_e32 v43, v43
	s_nop 0
	v_add_f32_e32 v43, 1.0, v43
; __device__ __forceinline__ unsigned cvt_pk_bf16(float lo, float hi) { unsigned r; asm volatile("v_cvt_pk_bf16_f32 %0, %1, %2" : "=v"(r) : "v"(lo), "v"(hi)); return r; }
; #define PG8_BAR __builtin_amdgcn_s_barrier()
; #define GAS __attribute__((address_space(1)))
; __device__ __forceinline__ float siluf_(float x) { return x * sigmoidf_(x); }
; template <class Epi, class Sched, bool ALIGN_EPI = false, bool SP2 = false>
; __device__ __forceinline__ void gemm_phase(PG8_LAS unsigned char* lds, const Gemm g, const Sched& S, const Epi& E, const int wave_id) {
;     ...
;         if (!has_next) break;
;         if (!keep_acc) {
; #pragma unroll
;         for (int a = 0; a < 2; ++a)
; #pragma unroll
;             for (int b = 0; b < 2; ++b)
; #pragma unroll
;                 for (int m = 0; m < 4; ++m)
; #pragma unroll
;                     for (int n = 0; n < 2; ++n) acc[a][b][m][n] = (f32x4){0.f, 0.f, 0.f, 0.f};
;         }
;         cur = nxt; cA = nA; cB = nB; ++ui;
;         if constexpr (ALIGN_EPI) { if (wr == 1) PG8_BAR; }
;     }
;     __device__ __forceinline__ bool operator()(AccT& acc, const Unit& u, int wr, int wc, int fr, int fq) const {
;     ...
;             for (int mp = 0; mp < 2; ++mp) { bf16* rowp = act + (size_t)(row0 + ai * 128 + mp * 32) * DFF + col0;
; #pragma unroll
;                 for (int bj = 0; bj < 2; ++bj) { unsigned pk[2][2];
; #pragma unroll
;                     for (int k = 0; k < 2; ++k) { const f32x4 g = acc[ai][bj][2 * mp + k][0], up = acc[ai][bj][2 * mp + k][1];
;                         pk[k][0] = pg8::cvt_pk_bf16(siluf_(g[0]) * up[0], siluf_(g[1]) * up[1]); pk[k][1] = pg8::cvt_pk_bf16(siluf_(g[2]) * up[2], siluf_(g[3]) * up[3]); }
;                     const auto sx = __builtin_amdgcn_permlane16_swap(pk[0][0], pk[1][0], false, false), sy = __builtin_amdgcn_permlane16_swap(pk[0][1], pk[1][1], false, false);
;                     *(GAS v4u*)(rowp + bj * 64) = (v4u){sx[0], sy[0], sx[1], sy[1]}; } }
	v_rcp_f32_e32 v43, v43
	s_nop 0
	v_mul_f32_e32 v43, v48, v43
	v_mul_f32_e32 v43, v44, v43
	v_mul_f32_e32 v44, 0xbfb8aa3b, v49
	v_exp_f32_e32 v44, v44
	s_nop 0
	v_add_f32_e32 v44, 1.0, v44
	v_rcp_f32_e32 v44, v44
	s_nop 0
	v_mul_f32_e32 v44, v49, v44
	v_mul_f32_e32 v44, v45, v44
	v_cvt_pk_bf16_f32 v43, v43, v44
	v_mul_f32_e32 v44, 0xbfb8aa3b, v38
	v_exp_f32_e32 v44, v44
	s_nop 0
	v_add_f32_e32 v44, 1.0, v44
	v_rcp_f32_e32 v44, v44
	s_nop 0
	v_mul_f32_e32 v38, v38, v44
	v_mul_f32_e32 v34, v34, v38
	v_mul_f32_e32 v38, 0xbfb8aa3b, v39
	v_exp_f32_e32 v38, v38
	s_nop 0
	v_add_f32_e32 v38, 1.0, v38
	v_rcp_f32_e32 v38, v38
	s_nop 0
	v_mul_f32_e32 v38, v39, v38
	v_mul_f32_e32 v35, v35, v38
	v_cvt_pk_bf16_f32 v44, v34, v35
	v_mul_f32_e32 v34, 0xbfb8aa3b, v40
	v_exp_f32_e32 v34, v34
	v_mul_f32_e32 v35, 0xbfb8aa3b, v41
	v_exp_f32_e32 v35, v35
	v_permlane16_swap_b32_e32 v42, v44
	v_add_f32_e32 v34, 1.0, v34
	v_rcp_f32_e32 v34, v34
	v_add_f32_e32 v35, 1.0, v35
	v_rcp_f32_e32 v35, v35
	v_mul_f32_e32 v34, v40, v34
	v_mul_f32_e32 v34, v36, v34
	v_mul_f32_e32 v36, 0xbfb8aa3b, v30
	v_exp_f32_e32 v36, v36
	v_mul_f32_e32 v35, v41, v35
	v_mul_f32_e32 v35, v37, v35
	v_cvt_pk_bf16_f32 v45, v34, v35
	v_add_f32_e32 v36, 1.0, v36
	v_rcp_f32_e32 v36, v36
	v_permlane16_swap_b32_e32 v43, v45
	global_store_dwordx4 v[66:67], v[42:45], off offset:128
	v_mul_f32_e32 v30, v30, v36
	v_mul_f32_e32 v26, v26, v30
	v_mul_f32_e32 v30, 0xbfb8aa3b, v31
	v_exp_f32_e32 v30, v30
	v_add_u32_e32 v34, 0xa0, v136
	v_mad_i64_i32 v[34:35], s[18:19], v34, s11, v[130:131]
	v_add_f32_e32 v30, 1.0, v30
	v_rcp_f32_e32 v30, v30
	v_lshl_add_u64 v[34:35], v[34:35], 0, v[132:133]
	s_mov_b64 s[18:19], -1
	v_mul_f32_e32 v30, v31, v30
	v_mul_f32_e32 v27, v27, v30
	v_cvt_pk_bf16_f32 v26, v26, v27
	v_mul_f32_e32 v27, 0xbfb8aa3b, v32
	v_exp_f32_e32 v27, v27
	s_nop 0
	v_add_f32_e32 v27, 1.0, v27
	v_rcp_f32_e32 v27, v27
	s_nop 0
	v_mul_f32_e32 v27, v32, v27
	v_mul_f32_e32 v27, v28, v27
	v_mul_f32_e32 v28, 0xbfb8aa3b, v33
	v_exp_f32_e32 v28, v28
	s_nop 0
	v_add_f32_e32 v28, 1.0, v28
	v_rcp_f32_e32 v28, v28
	s_nop 0
	v_mul_f32_e32 v28, v33, v28
	v_mul_f32_e32 v28, v29, v28
	v_cvt_pk_bf16_f32 v27, v27, v28
	v_mul_f32_e32 v28, 0xbfb8aa3b, v22
	v_exp_f32_e32 v28, v28
	s_nop 0
	v_add_f32_e32 v28, 1.0, v28
	v_rcp_f32_e32 v28, v28
	s_nop 0
	v_mul_f32_e32 v22, v22, v28
	v_mul_f32_e32 v18, v18, v22
	v_mul_f32_e32 v22, 0xbfb8aa3b, v23
	v_exp_f32_e32 v22, v22
	s_nop 0
	v_add_f32_e32 v22, 1.0, v22
	v_rcp_f32_e32 v22, v22
	s_nop 0
	v_mul_f32_e32 v22, v23, v22
	v_mul_f32_e32 v19, v19, v22
	v_cvt_pk_bf16_f32 v28, v18, v19
	v_mul_f32_e32 v18, 0xbfb8aa3b, v24
	v_exp_f32_e32 v18, v18
	v_mul_f32_e32 v19, 0xbfb8aa3b, v25
	v_exp_f32_e32 v19, v19
	v_permlane16_swap_b32_e32 v26, v28
	v_add_f32_e32 v18, 1.0, v18
	v_rcp_f32_e32 v18, v18
	v_add_f32_e32 v19, 1.0, v19
	v_rcp_f32_e32 v19, v19
	v_mul_f32_e32 v18, v24, v18
	v_mul_f32_e32 v18, v20, v18
	v_mul_f32_e32 v19, v25, v19
	v_mul_f32_e32 v19, v21, v19
	v_cvt_pk_bf16_f32 v29, v18, v19
	v_mul_f32_e32 v18, 0xbfb8aa3b, v14
	v_exp_f32_e32 v18, v18
	v_permlane16_swap_b32_e32 v27, v29
	global_store_dwordx4 v[34:35], v[26:29], off
	v_add_f32_e32 v18, 1.0, v18
	v_rcp_f32_e32 v18, v18
	s_nop 0
	v_mul_f32_e32 v14, v14, v18
	v_mul_f32_e32 v10, v10, v14
	v_mul_f32_e32 v14, 0xbfb8aa3b, v15
	v_exp_f32_e32 v14, v14
	s_nop 0
	v_add_f32_e32 v14, 1.0, v14
	v_rcp_f32_e32 v14, v14
	s_nop 0
	v_mul_f32_e32 v14, v15, v14
	v_mul_f32_e32 v11, v11, v14
	v_cvt_pk_bf16_f32 v10, v10, v11
	v_mul_f32_e32 v11, 0xbfb8aa3b, v16
	v_exp_f32_e32 v11, v11
	s_nop 0
	v_add_f32_e32 v11, 1.0, v11
	v_rcp_f32_e32 v11, v11
	s_nop 0
	v_mul_f32_e32 v11, v16, v11
	v_mul_f32_e32 v11, v12, v11
	v_mul_f32_e32 v12, 0xbfb8aa3b, v17
	v_exp_f32_e32 v12, v12
	s_nop 0
	v_add_f32_e32 v12, 1.0, v12
	v_rcp_f32_e32 v12, v12
	s_nop 0
	v_mul_f32_e32 v12, v17, v12
	v_mul_f32_e32 v12, v13, v12
	v_cvt_pk_bf16_f32 v11, v11, v12
	v_mul_f32_e32 v12, 0xbfb8aa3b, v6
	v_exp_f32_e32 v12, v12
	s_nop 0
	v_add_f32_e32 v12, 1.0, v12
	v_rcp_f32_e32 v12, v12
	s_nop 0
	v_mul_f32_e32 v6, v6, v12
	v_mul_f32_e32 v2, v2, v6
	v_mul_f32_e32 v6, 0xbfb8aa3b, v7
	v_exp_f32_e32 v6, v6
	s_nop 0
	v_add_f32_e32 v6, 1.0, v6
	v_rcp_f32_e32 v6, v6
	s_nop 0
	v_mul_f32_e32 v6, v7, v6
	v_mul_f32_e32 v3, v3, v6
	v_cvt_pk_bf16_f32 v12, v2, v3
	v_mul_f32_e32 v2, 0xbfb8aa3b, v8
	v_mul_f32_e32 v3, 0xbfb8aa3b, v9
	v_exp_f32_e32 v2, v2
	v_exp_f32_e32 v3, v3
	v_permlane16_swap_b32_e32 v10, v12
	v_add_f32_e32 v2, 1.0, v2
	v_add_f32_e32 v3, 1.0, v3
	v_rcp_f32_e32 v2, v2
	v_rcp_f32_e32 v3, v3
	v_mul_f32_e32 v2, v8, v2
	v_mul_f32_e32 v3, v9, v3
	v_mul_f32_e32 v2, v4, v2
	v_mul_f32_e32 v3, v5, v3
	v_cvt_pk_bf16_f32 v13, v2, v3
	s_nop 0
	v_permlane16_swap_b32_e32 v11, v13
	global_store_dwordx4 v[34:35], v[10:13], off offset:128
	s_cbranch_vccnz .LBB0_1948
	s_andn2_b64 vcc, exec, s[2:3]
	s_cbranch_vccnz .LBB0_1947
	s_barrier
	s_branch .LBB0_1947

; #define PG8_STAGE(bufoff, gbase, voff) do { _Pragma("unroll") for (int _i = 0; _i < 2; ++_i) \
;         __builtin_amdgcn_global_load_lds((const unsigned*)((const char*)(gbase) + (voff)[_i]), (PG8_LAS unsigned*)(lds + (bufoff) + ldsw + _i * 8192), 16, 0, 0); } while (0)
; #define PG8_LDA(dst, b, h) do { _Pragma("unroll") for (int m = 0; m < 4; ++m) _Pragma("unroll") for (int k = 0; k < 2; ++k) dst[m][k] = *(const PG8_LAS bf16x8*)(lds + PG8_SA(b, h) + aoff + m * 2048 + k * 1024); } while (0)
; #define PG8_LDB(dst, b, h) do { _Pragma("unroll") for (int n = 0; n < 2; ++n) _Pragma("unroll") for (int k = 0; k < 2; ++k) dst[n][k] = *(const PG8_LAS bf16x8*)(lds + PG8_SB(b, h) + boff + n * 2048 + k * 1024); } while (0)
; #define PG8_SCHED __builtin_amdgcn_sched_barrier(0)
; #define GAS __attribute__((address_space(1)))
; __device__ __forceinline__ v4u tr4(int a, v4u x) { return (v4u){bperm(a, x.x), bperm(a, x.y), bperm(a, x.z), bperm(a, x.w)}; }
; template <class Epi, class Sched, bool ALIGN_EPI = false, bool SP2 = false>
; __device__ __forceinline__ void gemm_phase(PG8_LAS unsigned char* lds, const Gemm g, const Sched& S, const Epi& E, const int wave_id) {
;     ...
;             PG8_LDB(B0, 0, 0); PG8_LDB(B1, 0, 1); PG8_SCHED; PG8_LDA(At, 0, 0); PG8_STAGE(PG8_SA(1, 1), a1 + hstep, voffA);
;     __device__ __forceinline__ bool operator()(AccT& acc, const Unit& u, int wr, int wc, int fr, int fq) const {
;     ...
;         const LaneT t = lane_t(fr, fq);
;         const bf16* src = (const bf16*)(ws + WS_HB); bf16* dst = (bf16*)(ws + WS_YB);
;         const int row0 = u.pm * 256 + wr * 64 + t.tfr, col0 = u.pn * 256 + wc * 32 + 8 * t.tfq;
; #pragma unroll
;         for (int ai = 0; ai < 2; ++ai)
; #pragma unroll
;             for (int m = 0; m < 4; ++m) { const size_t off = (size_t)(row0 + ai * 128 + m * 16) * D + col0;
; #pragma unroll
;                 for (int bj = 0; bj < 2; ++bj) { const v4u r = tr4(t.push, *(const GAS v4u*)(src + off + bj * 128));
;                     const f32x4 y0 = (f32x4){bflo(r.x), bfhi(r.x), bflo(r.y), bfhi(r.y)} * ca + acc[ai][bj][m][0] * cb, y1 = (f32x4){bflo(r.z), bfhi(r.z), bflo(r.w), bfhi(r.w)} * ca + acc[ai][bj][m][1] * cb;
;                     *(GAS v4u*)(dst + off + bj * 128) = tr4(t.pull, pack8(y0, y1)); } }
.LBB0_2037:
	s_add_u32 s100, s8, 0xb0080
	s_addc_u32 s101, s9, 0
	v_lshl_add_u64 v[194:195], s[100:101], 0, v[220:221]
	s_add_i32 m0, s31, 0xc000
	s_nop 0
	global_load_lds_dwordx4 v[194:195], off
	v_lshl_add_u64 v[194:195], s[100:101], 0, v[218:219]
	s_add_i32 m0, s31, 0xe000
	s_nop 0
	global_load_lds_dwordx4 v[194:195], off
	s_mov_b32 s12, s41
	v_mov_b32_e32 v130, v1
	s_mov_b32 s13, s29
	v_mov_b32_e32 v131, v245
	s_lshl_b32 s14, s54, 8
	v_lshl_add_u32 v132, v130, 4, v131
	s_lshl_b32 s13, s13, 6
	v_ashrrev_i32_e32 v134, 2, v132
	v_and_b32_e32 v135, 3, v131
	v_lshlrev_b32_e32 v131, 4, v131
	s_add_i32 s13, s13, s14
	v_lshl_add_u32 v133, v130, 2, v131
	v_add_u32_e32 v130, s13, v134
	s_lshl_b32 s13, s56, 8
	s_lshl_b32 s12, s12, 5
	s_add_i32 s12, s12, s13
	v_and_b32_e32 v132, -4, v132
	v_lshl_or_b32 v134, v135, 3, s12
	v_ashrrev_i32_e32 v131, 31, v130
	v_lshl_add_u32 v132, v135, 6, v132
	v_ashrrev_i32_e32 v135, 31, v134
	v_lshlrev_b64 v[130:131], 10, v[130:131]
	v_lshl_add_u64 v[130:131], v[130:131], 0, v[134:135]
	v_readlane_b32 s14, v253, 11
	v_lshlrev_b64 v[130:131], 1, v[130:131]
	v_readlane_b32 s15, v253, 12
	v_lshl_add_u64 v[140:141], s[60:61], 0, v[130:131]
	s_mov_b64 s[12:13], 0x8000
	v_lshl_add_u64 v[138:139], s[14:15], 0, v[130:131]
	v_mov_b64_e32 v[130:131], v[138:139]
	global_load_dwordx4 v[146:149], v[130:131], off
	s_and_b64 vcc, exec, s[6:7]
	global_load_dwordx4 v[150:153], v[130:131], off offset:256
	s_mov_b64 s[12:13], 0x8000
	v_lshl_add_u64 v[130:131], v[138:139], 0, s[12:13]
	global_load_dwordx4 v[154:157], v[130:131], off
	global_load_dwordx4 v[158:161], v[130:131], off offset:256
	s_mov_b64 s[12:13], 0x10000
	v_lshl_add_u64 v[130:131], v[138:139], 0, s[12:13]
	global_load_dwordx4 v[162:165], v[130:131], off
	global_load_dwordx4 v[166:169], v[130:131], off offset:256
	s_mov_b64 s[12:13], 0x18000
	v_lshl_add_u64 v[130:131], v[138:139], 0, s[12:13]
	global_load_dwordx4 v[170:173], v[130:131], off
	global_load_dwordx4 v[174:177], v[130:131], off offset:256
	s_mov_b64 s[12:13], 0x40000
	v_lshl_add_u64 v[130:131], v[138:139], 0, s[12:13]
	global_load_dwordx4 v[178:181], v[130:131], off
	global_load_dwordx4 v[182:185], v[130:131], off offset:256
	s_mov_b64 s[12:13], 0x48000
	v_lshl_add_u64 v[130:131], v[138:139], 0, s[12:13]
	global_load_dwordx4 v[186:189], v[130:131], off
	global_load_dwordx4 v[190:193], v[130:131], off offset:256
	s_waitcnt vmcnt(11)
	ds_bpermute_b32 v143, v133, v147
	ds_bpermute_b32 v142, v133, v146
	ds_bpermute_b32 v145, v133, v149
	ds_bpermute_b32 v144, v133, v148
	v_mov_b64_e32 v[134:135], v[140:141]
	s_waitcnt lgkmcnt(3)
	v_lshlrev_b32_e32 v136, 16, v143
	v_and_b32_e32 v137, 0xffff0000, v143
	s_waitcnt lgkmcnt(2)
	v_and_b32_e32 v143, 0xffff0000, v142
	v_lshlrev_b32_e32 v142, 16, v142
	v_pk_mul_f32 v[136:137], v[136:137], s[96:97] op_sel_hi:[1,0]
	v_pk_fma_f32 v[128:129], v[128:129], 0.5, v[136:137] op_sel_hi:[1,0,1]
	v_pk_mul_f32 v[142:143], v[142:143], s[96:97] op_sel_hi:[1,0]
	v_pk_fma_f32 v[126:127], v[126:127], 0.5, v[142:143] op_sel_hi:[1,0,1]
	s_waitcnt lgkmcnt(1)
	v_lshlrev_b32_e32 v136, 16, v145
	v_and_b32_e32 v137, 0xffff0000, v145
	s_waitcnt lgkmcnt(0)
	v_and_b32_e32 v145, 0xffff0000, v144
	v_lshlrev_b32_e32 v144, 16, v144
	v_pk_mul_f32 v[136:137], v[136:137], s[96:97] op_sel_hi:[1,0]
	v_pk_fma_f32 v[124:125], v[124:125], 0.5, v[136:137] op_sel_hi:[1,0,1]
	v_pk_mul_f32 v[144:145], v[144:145], s[96:97] op_sel_hi:[1,0]
	v_pk_fma_f32 v[122:123], v[122:123], 0.5, v[144:145] op_sel_hi:[1,0,1]
	v_cvt_pk_bf16_f32 v126, v126, v127
	v_cvt_pk_bf16_f32 v127, v128, v129
	v_cvt_pk_bf16_f32 v128, v122, v123
	v_cvt_pk_bf16_f32 v125, v124, v125
	s_nop 1
	ds_bpermute_b32 v122, v132, v126
	ds_bpermute_b32 v123, v132, v127
	ds_bpermute_b32 v124, v132, v128
	ds_bpermute_b32 v125, v132, v125
	s_waitcnt lgkmcnt(0)
	global_store_dwordx4 v[134:135], v[122:125], off
	s_mov_b64 s[12:13], 0x50000
	v_lshl_add_u64 v[130:131], v[138:139], 0, s[12:13]
	global_load_dwordx4 v[126:129], v[130:131], off
	s_waitcnt vmcnt(12)
	ds_bpermute_b32 v143, v133, v151
	ds_bpermute_b32 v142, v133, v150
	ds_bpermute_b32 v145, v133, v153
	ds_bpermute_b32 v144, v133, v152
	s_waitcnt lgkmcnt(3)
	v_lshlrev_b32_e32 v136, 16, v143
	v_and_b32_e32 v137, 0xffff0000, v143
	s_waitcnt lgkmcnt(2)
	v_and_b32_e32 v143, 0xffff0000, v142
	v_lshlrev_b32_e32 v142, 16, v142
	v_pk_mul_f32 v[136:137], v[136:137], s[96:97] op_sel_hi:[1,0]
	v_pk_fma_f32 v[120:121], v[120:121], 0.5, v[136:137] op_sel_hi:[1,0,1]
	v_pk_mul_f32 v[142:143], v[142:143], s[96:97] op_sel_hi:[1,0]
	v_pk_fma_f32 v[118:119], v[118:119], 0.5, v[142:143] op_sel_hi:[1,0,1]
	s_waitcnt lgkmcnt(1)
	v_lshlrev_b32_e32 v136, 16, v145
	v_and_b32_e32 v137, 0xffff0000, v145
	s_waitcnt lgkmcnt(0)
	v_and_b32_e32 v145, 0xffff0000, v144
	v_lshlrev_b32_e32 v144, 16, v144
	v_pk_mul_f32 v[136:137], v[136:137], s[96:97] op_sel_hi:[1,0]
	v_pk_fma_f32 v[116:117], v[116:117], 0.5, v[136:137] op_sel_hi:[1,0,1]
	v_pk_mul_f32 v[144:145], v[144:145], s[96:97] op_sel_hi:[1,0]
	v_pk_fma_f32 v[114:115], v[114:115], 0.5, v[144:145] op_sel_hi:[1,0,1]
	v_cvt_pk_bf16_f32 v118, v118, v119
	v_cvt_pk_bf16_f32 v119, v120, v121
	v_cvt_pk_bf16_f32 v120, v114, v115
	v_cvt_pk_bf16_f32 v117, v116, v117
	s_nop 1
	ds_bpermute_b32 v114, v132, v118
	ds_bpermute_b32 v115, v132, v119
	ds_bpermute_b32 v116, v132, v120
	ds_bpermute_b32 v117, v132, v117
	s_waitcnt lgkmcnt(0)
	global_store_dwordx4 v[134:135], v[114:117], off offset:256
	global_load_dwordx4 v[118:121], v[130:131], off offset:256
	s_waitcnt vmcnt(13)
	ds_bpermute_b32 v143, v133, v155
	ds_bpermute_b32 v142, v133, v154
	ds_bpermute_b32 v145, v133, v157
	ds_bpermute_b32 v144, v133, v156
	s_mov_b64 s[12:13], 0x8000
	v_lshl_add_u64 v[134:135], v[140:141], 0, s[12:13]
	s_waitcnt lgkmcnt(3)
; #define GAS __attribute__((address_space(1)))
; __device__ __forceinline__ v4u tr4(int a, v4u x) { return (v4u){bperm(a, x.x), bperm(a, x.y), bperm(a, x.z), bperm(a, x.w)}; }
; __device__ __forceinline__ v4u pack8(const f32x4& a, const f32x4& b) { return (v4u){pg8::cvt_pk_bf16(a[0], a[1]), pg8::cvt_pk_bf16(a[2], a[3]), pg8::cvt_pk_bf16(b[0], b[1]), pg8::cvt_pk_bf16(b[2], b[3])}; }
;     __device__ __forceinline__ bool operator()(AccT& acc, const Unit& u, int wr, int wc, int fr, int fq) const {
;     ...
;             for (int m = 0; m < 4; ++m) { const size_t off = (size_t)(row0 + ai * 128 + m * 16) * D + col0;
; #pragma unroll
;                 for (int bj = 0; bj < 2; ++bj) { const v4u r = tr4(t.push, *(const GAS v4u*)(src + off + bj * 128));
;                     const f32x4 y0 = (f32x4){bflo(r.x), bfhi(r.x), bflo(r.y), bfhi(r.y)} * ca + acc[ai][bj][m][0] * cb, y1 = (f32x4){bflo(r.z), bfhi(r.z), bflo(r.w), bfhi(r.w)} * ca + acc[ai][bj][m][1] * cb;
;                     *(GAS v4u*)(dst + off + bj * 128) = tr4(t.pull, pack8(y0, y1)); } }
	v_lshlrev_b32_e32 v136, 16, v143
	v_and_b32_e32 v137, 0xffff0000, v143
	s_waitcnt lgkmcnt(2)
	v_and_b32_e32 v143, 0xffff0000, v142
	v_lshlrev_b32_e32 v142, 16, v142
	v_pk_mul_f32 v[136:137], v[136:137], s[96:97] op_sel_hi:[1,0]
	v_pk_fma_f32 v[112:113], v[112:113], 0.5, v[136:137] op_sel_hi:[1,0,1]
	v_pk_mul_f32 v[142:143], v[142:143], s[96:97] op_sel_hi:[1,0]
	v_pk_fma_f32 v[110:111], v[110:111], 0.5, v[142:143] op_sel_hi:[1,0,1]
	s_waitcnt lgkmcnt(1)
	v_lshlrev_b32_e32 v136, 16, v145
	v_and_b32_e32 v137, 0xffff0000, v145
	s_waitcnt lgkmcnt(0)
	v_and_b32_e32 v145, 0xffff0000, v144
	v_lshlrev_b32_e32 v144, 16, v144
	v_pk_mul_f32 v[136:137], v[136:137], s[96:97] op_sel_hi:[1,0]
	v_pk_fma_f32 v[108:109], v[108:109], 0.5, v[136:137] op_sel_hi:[1,0,1]
	v_pk_mul_f32 v[144:145], v[144:145], s[96:97] op_sel_hi:[1,0]
	v_pk_fma_f32 v[106:107], v[106:107], 0.5, v[144:145] op_sel_hi:[1,0,1]
	v_cvt_pk_bf16_f32 v110, v110, v111
	v_cvt_pk_bf16_f32 v111, v112, v113
	v_cvt_pk_bf16_f32 v112, v106, v107
	v_cvt_pk_bf16_f32 v109, v108, v109
	s_nop 1
	ds_bpermute_b32 v106, v132, v110
	ds_bpermute_b32 v107, v132, v111
	ds_bpermute_b32 v108, v132, v112
	ds_bpermute_b32 v109, v132, v109
	s_waitcnt lgkmcnt(0)
	global_store_dwordx4 v[134:135], v[106:109], off
	s_mov_b64 s[12:13], 0x58000
	v_lshl_add_u64 v[130:131], v[138:139], 0, s[12:13]
	global_load_dwordx4 v[110:113], v[130:131], off
	s_waitcnt vmcnt(14)
	ds_bpermute_b32 v143, v133, v159
	ds_bpermute_b32 v142, v133, v158
	ds_bpermute_b32 v145, v133, v161
	ds_bpermute_b32 v144, v133, v160
	s_waitcnt lgkmcnt(3)
	v_lshlrev_b32_e32 v136, 16, v143
	v_and_b32_e32 v137, 0xffff0000, v143
	s_waitcnt lgkmcnt(2)
	v_and_b32_e32 v143, 0xffff0000, v142
	v_lshlrev_b32_e32 v142, 16, v142
	v_pk_mul_f32 v[136:137], v[136:137], s[96:97] op_sel_hi:[1,0]
	v_pk_fma_f32 v[104:105], v[104:105], 0.5, v[136:137] op_sel_hi:[1,0,1]
	v_pk_mul_f32 v[142:143], v[142:143], s[96:97] op_sel_hi:[1,0]
	v_pk_fma_f32 v[102:103], v[102:103], 0.5, v[142:143] op_sel_hi:[1,0,1]
	s_waitcnt lgkmcnt(1)
	v_lshlrev_b32_e32 v136, 16, v145
	v_and_b32_e32 v137, 0xffff0000, v145
	s_waitcnt lgkmcnt(0)
	v_and_b32_e32 v145, 0xffff0000, v144
	v_lshlrev_b32_e32 v144, 16, v144
	v_pk_mul_f32 v[136:137], v[136:137], s[96:97] op_sel_hi:[1,0]
	v_pk_fma_f32 v[100:101], v[100:101], 0.5, v[136:137] op_sel_hi:[1,0,1]
	v_pk_mul_f32 v[144:145], v[144:145], s[96:97] op_sel_hi:[1,0]
	v_pk_fma_f32 v[98:99], v[98:99], 0.5, v[144:145] op_sel_hi:[1,0,1]
	v_cvt_pk_bf16_f32 v102, v102, v103
	v_cvt_pk_bf16_f32 v103, v104, v105
	v_cvt_pk_bf16_f32 v104, v98, v99
	v_cvt_pk_bf16_f32 v101, v100, v101
	s_nop 1
	ds_bpermute_b32 v98, v132, v102
	ds_bpermute_b32 v99, v132, v103
	ds_bpermute_b32 v100, v132, v104
	ds_bpermute_b32 v101, v132, v101
	s_waitcnt lgkmcnt(0)
	global_store_dwordx4 v[134:135], v[98:101], off offset:256
	global_load_dwordx4 v[102:105], v[130:131], off offset:256
	s_waitcnt vmcnt(15)
	ds_bpermute_b32 v143, v133, v163
	ds_bpermute_b32 v142, v133, v162
	ds_bpermute_b32 v145, v133, v165
	ds_bpermute_b32 v144, v133, v164
	s_mov_b64 s[12:13], 0x10000
	v_lshl_add_u64 v[134:135], v[140:141], 0, s[12:13]
	s_waitcnt lgkmcnt(3)
	v_lshlrev_b32_e32 v136, 16, v143
	v_and_b32_e32 v137, 0xffff0000, v143
	s_waitcnt lgkmcnt(2)
	v_and_b32_e32 v143, 0xffff0000, v142
	v_lshlrev_b32_e32 v142, 16, v142
	v_pk_mul_f32 v[136:137], v[136:137], s[96:97] op_sel_hi:[1,0]
	v_pk_fma_f32 v[96:97], v[96:97], 0.5, v[136:137] op_sel_hi:[1,0,1]
	v_pk_mul_f32 v[142:143], v[142:143], s[96:97] op_sel_hi:[1,0]
	v_pk_fma_f32 v[94:95], v[94:95], 0.5, v[142:143] op_sel_hi:[1,0,1]
	s_waitcnt lgkmcnt(1)
	v_lshlrev_b32_e32 v136, 16, v145
	v_and_b32_e32 v137, 0xffff0000, v145
	s_waitcnt lgkmcnt(0)
	v_and_b32_e32 v145, 0xffff0000, v144
	v_lshlrev_b32_e32 v144, 16, v144
	v_pk_mul_f32 v[136:137], v[136:137], s[96:97] op_sel_hi:[1,0]
	v_pk_fma_f32 v[92:93], v[92:93], 0.5, v[136:137] op_sel_hi:[1,0,1]
	v_pk_mul_f32 v[144:145], v[144:145], s[96:97] op_sel_hi:[1,0]
	v_pk_fma_f32 v[90:91], v[90:91], 0.5, v[144:145] op_sel_hi:[1,0,1]
	v_cvt_pk_bf16_f32 v94, v94, v95
	v_cvt_pk_bf16_f32 v95, v96, v97
	v_cvt_pk_bf16_f32 v96, v90, v91
	v_cvt_pk_bf16_f32 v93, v92, v93
	s_nop 1
	ds_bpermute_b32 v90, v132, v94
	ds_bpermute_b32 v91, v132, v95
	ds_bpermute_b32 v92, v132, v96
	ds_bpermute_b32 v93, v132, v93
	s_waitcnt lgkmcnt(0)
	global_store_dwordx4 v[134:135], v[90:93], off
	s_waitcnt vmcnt(15)
	ds_bpermute_b32 v143, v133, v167
	ds_bpermute_b32 v142, v133, v166
	ds_bpermute_b32 v145, v133, v169
	ds_bpermute_b32 v144, v133, v168
	s_waitcnt lgkmcnt(3)
	v_lshlrev_b32_e32 v136, 16, v143
	v_and_b32_e32 v137, 0xffff0000, v143
	s_waitcnt lgkmcnt(2)
	v_and_b32_e32 v143, 0xffff0000, v142
	v_lshlrev_b32_e32 v142, 16, v142
	v_pk_mul_f32 v[136:137], v[136:137], s[96:97] op_sel_hi:[1,0]
	v_pk_fma_f32 v[88:89], v[88:89], 0.5, v[136:137] op_sel_hi:[1,0,1]
	v_pk_mul_f32 v[142:143], v[142:143], s[96:97] op_sel_hi:[1,0]
	v_pk_fma_f32 v[86:87], v[86:87], 0.5, v[142:143] op_sel_hi:[1,0,1]
	s_waitcnt lgkmcnt(1)
	v_lshlrev_b32_e32 v136, 16, v145
	v_and_b32_e32 v137, 0xffff0000, v145
	s_waitcnt lgkmcnt(0)
	v_and_b32_e32 v145, 0xffff0000, v144
	v_lshlrev_b32_e32 v144, 16, v144
	v_pk_mul_f32 v[136:137], v[136:137], s[96:97] op_sel_hi:[1,0]
	v_pk_fma_f32 v[84:85], v[84:85], 0.5, v[136:137] op_sel_hi:[1,0,1]
	v_pk_mul_f32 v[144:145], v[144:145], s[96:97] op_sel_hi:[1,0]
	v_pk_fma_f32 v[82:83], v[82:83], 0.5, v[144:145] op_sel_hi:[1,0,1]
	v_cvt_pk_bf16_f32 v86, v86, v87
	v_cvt_pk_bf16_f32 v87, v88, v89
	v_cvt_pk_bf16_f32 v88, v82, v83
	v_cvt_pk_bf16_f32 v85, v84, v85
	s_nop 1
	ds_bpermute_b32 v82, v132, v86
	ds_bpermute_b32 v83, v132, v87
	ds_bpermute_b32 v84, v132, v88
	ds_bpermute_b32 v85, v132, v85
	s_waitcnt lgkmcnt(0)
; #define GAS __attribute__((address_space(1)))
; __device__ __forceinline__ v4u tr4(int a, v4u x) { return (v4u){bperm(a, x.x), bperm(a, x.y), bperm(a, x.z), bperm(a, x.w)}; }
; __device__ __forceinline__ v4u pack8(const f32x4& a, const f32x4& b) { return (v4u){pg8::cvt_pk_bf16(a[0], a[1]), pg8::cvt_pk_bf16(a[2], a[3]), pg8::cvt_pk_bf16(b[0], b[1]), pg8::cvt_pk_bf16(b[2], b[3])}; }
;     __device__ __forceinline__ bool operator()(AccT& acc, const Unit& u, int wr, int wc, int fr, int fq) const {
;     ...
;             for (int m = 0; m < 4; ++m) { const size_t off = (size_t)(row0 + ai * 128 + m * 16) * D + col0;
; #pragma unroll
;                 for (int bj = 0; bj < 2; ++bj) { const v4u r = tr4(t.push, *(const GAS v4u*)(src + off + bj * 128));
;                     const f32x4 y0 = (f32x4){bflo(r.x), bfhi(r.x), bflo(r.y), bfhi(r.y)} * ca + acc[ai][bj][m][0] * cb, y1 = (f32x4){bflo(r.z), bfhi(r.z), bflo(r.w), bfhi(r.w)} * ca + acc[ai][bj][m][1] * cb;
;                     *(GAS v4u*)(dst + off + bj * 128) = tr4(t.pull, pack8(y0, y1)); } }
	global_store_dwordx4 v[134:135], v[82:85], off offset:256
	s_waitcnt vmcnt(15)
	ds_bpermute_b32 v143, v133, v171
	ds_bpermute_b32 v142, v133, v170
	ds_bpermute_b32 v145, v133, v173
	ds_bpermute_b32 v144, v133, v172
	s_mov_b64 s[12:13], 0x18000
	v_lshl_add_u64 v[134:135], v[140:141], 0, s[12:13]
	s_waitcnt lgkmcnt(3)
	v_lshlrev_b32_e32 v136, 16, v143
	v_and_b32_e32 v137, 0xffff0000, v143
	s_waitcnt lgkmcnt(2)
	v_and_b32_e32 v143, 0xffff0000, v142
	v_lshlrev_b32_e32 v142, 16, v142
	v_pk_mul_f32 v[136:137], v[136:137], s[96:97] op_sel_hi:[1,0]
	v_pk_fma_f32 v[80:81], v[80:81], 0.5, v[136:137] op_sel_hi:[1,0,1]
	v_pk_mul_f32 v[142:143], v[142:143], s[96:97] op_sel_hi:[1,0]
	v_pk_fma_f32 v[78:79], v[78:79], 0.5, v[142:143] op_sel_hi:[1,0,1]
	s_waitcnt lgkmcnt(1)
	v_lshlrev_b32_e32 v136, 16, v145
	v_and_b32_e32 v137, 0xffff0000, v145
	s_waitcnt lgkmcnt(0)
	v_and_b32_e32 v145, 0xffff0000, v144
	v_lshlrev_b32_e32 v144, 16, v144
	v_pk_mul_f32 v[136:137], v[136:137], s[96:97] op_sel_hi:[1,0]
	v_pk_fma_f32 v[76:77], v[76:77], 0.5, v[136:137] op_sel_hi:[1,0,1]
	v_pk_mul_f32 v[144:145], v[144:145], s[96:97] op_sel_hi:[1,0]
	v_pk_fma_f32 v[74:75], v[74:75], 0.5, v[144:145] op_sel_hi:[1,0,1]
	v_cvt_pk_bf16_f32 v78, v78, v79
	v_cvt_pk_bf16_f32 v79, v80, v81
	v_cvt_pk_bf16_f32 v80, v74, v75
	v_cvt_pk_bf16_f32 v77, v76, v77
	s_nop 1
	ds_bpermute_b32 v74, v132, v78
	ds_bpermute_b32 v75, v132, v79
	ds_bpermute_b32 v76, v132, v80
	ds_bpermute_b32 v77, v132, v77
	s_waitcnt lgkmcnt(0)
	global_store_dwordx4 v[134:135], v[74:77], off
	s_waitcnt vmcnt(15)
	ds_bpermute_b32 v143, v133, v175
	ds_bpermute_b32 v142, v133, v174
	ds_bpermute_b32 v145, v133, v177
	ds_bpermute_b32 v144, v133, v176
	s_waitcnt lgkmcnt(3)
	v_lshlrev_b32_e32 v136, 16, v143
	v_and_b32_e32 v137, 0xffff0000, v143
	s_waitcnt lgkmcnt(2)
	v_and_b32_e32 v143, 0xffff0000, v142
	v_lshlrev_b32_e32 v142, 16, v142
	v_pk_mul_f32 v[136:137], v[136:137], s[96:97] op_sel_hi:[1,0]
	v_pk_fma_f32 v[72:73], v[72:73], 0.5, v[136:137] op_sel_hi:[1,0,1]
	v_pk_mul_f32 v[142:143], v[142:143], s[96:97] op_sel_hi:[1,0]
	v_pk_fma_f32 v[70:71], v[70:71], 0.5, v[142:143] op_sel_hi:[1,0,1]
	s_waitcnt lgkmcnt(1)
	v_lshlrev_b32_e32 v136, 16, v145
	v_and_b32_e32 v137, 0xffff0000, v145
	s_waitcnt lgkmcnt(0)
	v_and_b32_e32 v145, 0xffff0000, v144
	v_lshlrev_b32_e32 v144, 16, v144
	v_pk_mul_f32 v[136:137], v[136:137], s[96:97] op_sel_hi:[1,0]
	v_pk_fma_f32 v[68:69], v[68:69], 0.5, v[136:137] op_sel_hi:[1,0,1]
	v_pk_mul_f32 v[144:145], v[144:145], s[96:97] op_sel_hi:[1,0]
	v_pk_fma_f32 v[66:67], v[66:67], 0.5, v[144:145] op_sel_hi:[1,0,1]
	v_cvt_pk_bf16_f32 v70, v70, v71
	v_cvt_pk_bf16_f32 v71, v72, v73
	v_cvt_pk_bf16_f32 v72, v66, v67
	v_cvt_pk_bf16_f32 v69, v68, v69
	s_nop 1
	ds_bpermute_b32 v66, v132, v70
	ds_bpermute_b32 v67, v132, v71
	ds_bpermute_b32 v68, v132, v72
	ds_bpermute_b32 v69, v132, v69
	s_waitcnt lgkmcnt(0)
	global_store_dwordx4 v[134:135], v[66:69], off offset:256
	s_waitcnt vmcnt(15)
	ds_bpermute_b32 v143, v133, v179
	ds_bpermute_b32 v142, v133, v178
	ds_bpermute_b32 v145, v133, v181
	ds_bpermute_b32 v144, v133, v180
	s_mov_b64 s[12:13], 0x40000
	v_lshl_add_u64 v[134:135], v[140:141], 0, s[12:13]
	s_waitcnt lgkmcnt(3)
	v_lshlrev_b32_e32 v136, 16, v143
	v_and_b32_e32 v137, 0xffff0000, v143
	s_waitcnt lgkmcnt(2)
	v_and_b32_e32 v143, 0xffff0000, v142
	v_lshlrev_b32_e32 v142, 16, v142
	v_pk_mul_f32 v[136:137], v[136:137], s[96:97] op_sel_hi:[1,0]
	v_pk_fma_f32 v[64:65], v[64:65], 0.5, v[136:137] op_sel_hi:[1,0,1]
	v_pk_mul_f32 v[142:143], v[142:143], s[96:97] op_sel_hi:[1,0]
	v_pk_fma_f32 v[62:63], v[62:63], 0.5, v[142:143] op_sel_hi:[1,0,1]
	s_waitcnt lgkmcnt(1)
	v_lshlrev_b32_e32 v136, 16, v145
	v_and_b32_e32 v137, 0xffff0000, v145
	s_waitcnt lgkmcnt(0)
	v_and_b32_e32 v145, 0xffff0000, v144
	v_lshlrev_b32_e32 v144, 16, v144
	v_pk_mul_f32 v[136:137], v[136:137], s[96:97] op_sel_hi:[1,0]
	v_pk_fma_f32 v[60:61], v[60:61], 0.5, v[136:137] op_sel_hi:[1,0,1]
	v_pk_mul_f32 v[144:145], v[144:145], s[96:97] op_sel_hi:[1,0]
	v_pk_fma_f32 v[58:59], v[58:59], 0.5, v[144:145] op_sel_hi:[1,0,1]
	v_cvt_pk_bf16_f32 v62, v62, v63
	v_cvt_pk_bf16_f32 v63, v64, v65
	v_cvt_pk_bf16_f32 v64, v58, v59
	v_cvt_pk_bf16_f32 v61, v60, v61
	s_nop 1
	ds_bpermute_b32 v58, v132, v62
	ds_bpermute_b32 v59, v132, v63
	ds_bpermute_b32 v60, v132, v64
	ds_bpermute_b32 v61, v132, v61
	s_waitcnt lgkmcnt(0)
	global_store_dwordx4 v[134:135], v[58:61], off
	s_waitcnt vmcnt(15)
	ds_bpermute_b32 v143, v133, v183
	ds_bpermute_b32 v142, v133, v182
	ds_bpermute_b32 v145, v133, v185
	ds_bpermute_b32 v144, v133, v184
	s_waitcnt lgkmcnt(3)
	v_lshlrev_b32_e32 v136, 16, v143
	v_and_b32_e32 v137, 0xffff0000, v143
	s_waitcnt lgkmcnt(2)
	v_and_b32_e32 v143, 0xffff0000, v142
	v_lshlrev_b32_e32 v142, 16, v142
	v_pk_mul_f32 v[136:137], v[136:137], s[96:97] op_sel_hi:[1,0]
	v_pk_fma_f32 v[56:57], v[56:57], 0.5, v[136:137] op_sel_hi:[1,0,1]
	v_pk_mul_f32 v[142:143], v[142:143], s[96:97] op_sel_hi:[1,0]
	v_pk_fma_f32 v[54:55], v[54:55], 0.5, v[142:143] op_sel_hi:[1,0,1]
	s_waitcnt lgkmcnt(1)
	v_lshlrev_b32_e32 v136, 16, v145
	v_and_b32_e32 v137, 0xffff0000, v145
	s_waitcnt lgkmcnt(0)
	v_and_b32_e32 v145, 0xffff0000, v144
	v_lshlrev_b32_e32 v144, 16, v144
	v_pk_mul_f32 v[136:137], v[136:137], s[96:97] op_sel_hi:[1,0]
	v_pk_fma_f32 v[52:53], v[52:53], 0.5, v[136:137] op_sel_hi:[1,0,1]
	v_pk_mul_f32 v[144:145], v[144:145], s[96:97] op_sel_hi:[1,0]
	v_pk_fma_f32 v[50:51], v[50:51], 0.5, v[144:145] op_sel_hi:[1,0,1]
	v_cvt_pk_bf16_f32 v54, v54, v55
	v_cvt_pk_bf16_f32 v55, v56, v57
	v_cvt_pk_bf16_f32 v56, v50, v51
	v_cvt_pk_bf16_f32 v53, v52, v53
	s_nop 1
	ds_bpermute_b32 v50, v132, v54
	ds_bpermute_b32 v51, v132, v55
	ds_bpermute_b32 v52, v132, v56
	ds_bpermute_b32 v53, v132, v53
	s_waitcnt lgkmcnt(0)
; #define GAS __attribute__((address_space(1)))
; __device__ __forceinline__ v4u tr4(int a, v4u x) { return (v4u){bperm(a, x.x), bperm(a, x.y), bperm(a, x.z), bperm(a, x.w)}; }
; __device__ __forceinline__ v4u pack8(const f32x4& a, const f32x4& b) { return (v4u){pg8::cvt_pk_bf16(a[0], a[1]), pg8::cvt_pk_bf16(a[2], a[3]), pg8::cvt_pk_bf16(b[0], b[1]), pg8::cvt_pk_bf16(b[2], b[3])}; }
;     __device__ __forceinline__ bool operator()(AccT& acc, const Unit& u, int wr, int wc, int fr, int fq) const {
;     ...
;             for (int m = 0; m < 4; ++m) { const size_t off = (size_t)(row0 + ai * 128 + m * 16) * D + col0;
; #pragma unroll
;                 for (int bj = 0; bj < 2; ++bj) { const v4u r = tr4(t.push, *(const GAS v4u*)(src + off + bj * 128));
;                     const f32x4 y0 = (f32x4){bflo(r.x), bfhi(r.x), bflo(r.y), bfhi(r.y)} * ca + acc[ai][bj][m][0] * cb, y1 = (f32x4){bflo(r.z), bfhi(r.z), bflo(r.w), bfhi(r.w)} * ca + acc[ai][bj][m][1] * cb;
;                     *(GAS v4u*)(dst + off + bj * 128) = tr4(t.pull, pack8(y0, y1)); } }
	global_store_dwordx4 v[134:135], v[50:53], off offset:256
	s_waitcnt vmcnt(15)
	ds_bpermute_b32 v143, v133, v187
	ds_bpermute_b32 v142, v133, v186
	ds_bpermute_b32 v145, v133, v189
	ds_bpermute_b32 v144, v133, v188
	s_mov_b64 s[12:13], 0x48000
	v_lshl_add_u64 v[134:135], v[140:141], 0, s[12:13]
	s_waitcnt lgkmcnt(3)
	v_lshlrev_b32_e32 v136, 16, v143
	v_and_b32_e32 v137, 0xffff0000, v143
	s_waitcnt lgkmcnt(2)
	v_and_b32_e32 v143, 0xffff0000, v142
	v_lshlrev_b32_e32 v142, 16, v142
	v_pk_mul_f32 v[136:137], v[136:137], s[96:97] op_sel_hi:[1,0]
	v_pk_fma_f32 v[48:49], v[48:49], 0.5, v[136:137] op_sel_hi:[1,0,1]
	v_pk_mul_f32 v[142:143], v[142:143], s[96:97] op_sel_hi:[1,0]
	v_pk_fma_f32 v[46:47], v[46:47], 0.5, v[142:143] op_sel_hi:[1,0,1]
	s_waitcnt lgkmcnt(1)
	v_lshlrev_b32_e32 v136, 16, v145
	v_and_b32_e32 v137, 0xffff0000, v145
	s_waitcnt lgkmcnt(0)
	v_and_b32_e32 v145, 0xffff0000, v144
	v_lshlrev_b32_e32 v144, 16, v144
	v_pk_mul_f32 v[136:137], v[136:137], s[96:97] op_sel_hi:[1,0]
	v_pk_fma_f32 v[44:45], v[44:45], 0.5, v[136:137] op_sel_hi:[1,0,1]
	v_pk_mul_f32 v[144:145], v[144:145], s[96:97] op_sel_hi:[1,0]
	v_pk_fma_f32 v[42:43], v[42:43], 0.5, v[144:145] op_sel_hi:[1,0,1]
	v_cvt_pk_bf16_f32 v46, v46, v47
	v_cvt_pk_bf16_f32 v47, v48, v49
	v_cvt_pk_bf16_f32 v48, v42, v43
	v_cvt_pk_bf16_f32 v45, v44, v45
	s_nop 1
	ds_bpermute_b32 v42, v132, v46
	ds_bpermute_b32 v43, v132, v47
	ds_bpermute_b32 v44, v132, v48
	ds_bpermute_b32 v45, v132, v45
	s_waitcnt lgkmcnt(0)
	global_store_dwordx4 v[134:135], v[42:45], off
	s_waitcnt vmcnt(15)
	ds_bpermute_b32 v143, v133, v191
	ds_bpermute_b32 v142, v133, v190
	ds_bpermute_b32 v145, v133, v193
	ds_bpermute_b32 v144, v133, v192
	s_waitcnt lgkmcnt(3)
	v_lshlrev_b32_e32 v136, 16, v143
	v_and_b32_e32 v137, 0xffff0000, v143
	s_waitcnt lgkmcnt(2)
	v_and_b32_e32 v143, 0xffff0000, v142
	v_lshlrev_b32_e32 v142, 16, v142
	v_pk_mul_f32 v[136:137], v[136:137], s[96:97] op_sel_hi:[1,0]
	v_pk_fma_f32 v[40:41], v[40:41], 0.5, v[136:137] op_sel_hi:[1,0,1]
	v_pk_mul_f32 v[142:143], v[142:143], s[96:97] op_sel_hi:[1,0]
	v_pk_fma_f32 v[38:39], v[38:39], 0.5, v[142:143] op_sel_hi:[1,0,1]
	s_waitcnt lgkmcnt(1)
	v_lshlrev_b32_e32 v136, 16, v145
	v_and_b32_e32 v137, 0xffff0000, v145
	s_waitcnt lgkmcnt(0)
	v_and_b32_e32 v145, 0xffff0000, v144
	v_lshlrev_b32_e32 v144, 16, v144
	v_pk_mul_f32 v[136:137], v[136:137], s[96:97] op_sel_hi:[1,0]
	v_pk_fma_f32 v[36:37], v[36:37], 0.5, v[136:137] op_sel_hi:[1,0,1]
	v_pk_mul_f32 v[144:145], v[144:145], s[96:97] op_sel_hi:[1,0]
	v_pk_fma_f32 v[34:35], v[34:35], 0.5, v[144:145] op_sel_hi:[1,0,1]
	v_cvt_pk_bf16_f32 v38, v38, v39
	v_cvt_pk_bf16_f32 v39, v40, v41
	v_cvt_pk_bf16_f32 v40, v34, v35
	v_cvt_pk_bf16_f32 v37, v36, v37
	s_nop 1
	ds_bpermute_b32 v34, v132, v38
	ds_bpermute_b32 v35, v132, v39
	ds_bpermute_b32 v36, v132, v40
	ds_bpermute_b32 v37, v132, v37
	s_waitcnt lgkmcnt(0)
	global_store_dwordx4 v[134:135], v[34:37], off offset:256
	s_waitcnt vmcnt(14)
	ds_bpermute_b32 v143, v133, v127
	ds_bpermute_b32 v142, v133, v126
	ds_bpermute_b32 v145, v133, v129
	ds_bpermute_b32 v144, v133, v128
	s_mov_b64 s[12:13], 0x50000
	v_lshl_add_u64 v[134:135], v[140:141], 0, s[12:13]
	s_waitcnt lgkmcnt(3)
	v_lshlrev_b32_e32 v136, 16, v143
	v_and_b32_e32 v137, 0xffff0000, v143
	s_waitcnt lgkmcnt(2)
	v_and_b32_e32 v143, 0xffff0000, v142
	v_lshlrev_b32_e32 v142, 16, v142
	v_pk_mul_f32 v[136:137], v[136:137], s[96:97] op_sel_hi:[1,0]
	v_pk_fma_f32 v[32:33], v[32:33], 0.5, v[136:137] op_sel_hi:[1,0,1]
	v_pk_mul_f32 v[142:143], v[142:143], s[96:97] op_sel_hi:[1,0]
	v_pk_fma_f32 v[30:31], v[30:31], 0.5, v[142:143] op_sel_hi:[1,0,1]
	s_waitcnt lgkmcnt(1)
	v_lshlrev_b32_e32 v136, 16, v145
	v_and_b32_e32 v137, 0xffff0000, v145
	s_waitcnt lgkmcnt(0)
	v_and_b32_e32 v145, 0xffff0000, v144
	v_lshlrev_b32_e32 v144, 16, v144
	v_pk_mul_f32 v[136:137], v[136:137], s[96:97] op_sel_hi:[1,0]
	v_pk_fma_f32 v[28:29], v[28:29], 0.5, v[136:137] op_sel_hi:[1,0,1]
	v_pk_mul_f32 v[144:145], v[144:145], s[96:97] op_sel_hi:[1,0]
	v_pk_fma_f32 v[26:27], v[26:27], 0.5, v[144:145] op_sel_hi:[1,0,1]
	v_cvt_pk_bf16_f32 v30, v30, v31
	v_cvt_pk_bf16_f32 v31, v32, v33
	v_cvt_pk_bf16_f32 v32, v26, v27
	v_cvt_pk_bf16_f32 v29, v28, v29
	s_nop 1
	ds_bpermute_b32 v26, v132, v30
	ds_bpermute_b32 v27, v132, v31
	ds_bpermute_b32 v28, v132, v32
	ds_bpermute_b32 v29, v132, v29
	s_waitcnt lgkmcnt(0)
	global_store_dwordx4 v[134:135], v[26:29], off
	s_waitcnt vmcnt(13)
; #define PG8_BAR __builtin_amdgcn_s_barrier()
; #define GAS __attribute__((address_space(1)))
; __device__ __forceinline__ v4u tr4(int a, v4u x) { return (v4u){bperm(a, x.x), bperm(a, x.y), bperm(a, x.z), bperm(a, x.w)}; }
; __device__ __forceinline__ v4u pack8(const f32x4& a, const f32x4& b) { return (v4u){pg8::cvt_pk_bf16(a[0], a[1]), pg8::cvt_pk_bf16(a[2], a[3]), pg8::cvt_pk_bf16(b[0], b[1]), pg8::cvt_pk_bf16(b[2], b[3])}; }
; template <class Epi, class Sched, bool ALIGN_EPI = false, bool SP2 = false>
; __device__ __forceinline__ void gemm_phase(PG8_LAS unsigned char* lds, const Gemm g, const Sched& S, const Epi& E, const int wave_id) {
;     ...
;         if (!has_next) break;
;         if (!keep_acc) {
; #pragma unroll
;         for (int a = 0; a < 2; ++a)
; #pragma unroll
;             for (int b = 0; b < 2; ++b)
; #pragma unroll
;                 for (int m = 0; m < 4; ++m)
; #pragma unroll
;                     for (int n = 0; n < 2; ++n) acc[a][b][m][n] = (f32x4){0.f, 0.f, 0.f, 0.f};
;         }
;         cur = nxt; cA = nA; cB = nB; ++ui;
;         if constexpr (ALIGN_EPI) { if (wr == 1) PG8_BAR; }
;     }
;     __device__ __forceinline__ bool operator()(AccT& acc, const Unit& u, int wr, int wc, int fr, int fq) const {
;     ...
;             for (int m = 0; m < 4; ++m) { const size_t off = (size_t)(row0 + ai * 128 + m * 16) * D + col0;
; #pragma unroll
;                 for (int bj = 0; bj < 2; ++bj) { const v4u r = tr4(t.push, *(const GAS v4u*)(src + off + bj * 128));
;                     const f32x4 y0 = (f32x4){bflo(r.x), bfhi(r.x), bflo(r.y), bfhi(r.y)} * ca + acc[ai][bj][m][0] * cb, y1 = (f32x4){bflo(r.z), bfhi(r.z), bflo(r.w), bfhi(r.w)} * ca + acc[ai][bj][m][1] * cb;
;                     *(GAS v4u*)(dst + off + bj * 128) = tr4(t.pull, pack8(y0, y1)); } }
	ds_bpermute_b32 v143, v133, v119
	ds_bpermute_b32 v142, v133, v118
	ds_bpermute_b32 v145, v133, v121
	ds_bpermute_b32 v144, v133, v120
	s_waitcnt lgkmcnt(3)
	v_lshlrev_b32_e32 v136, 16, v143
	v_and_b32_e32 v137, 0xffff0000, v143
	s_waitcnt lgkmcnt(2)
	v_and_b32_e32 v143, 0xffff0000, v142
	v_lshlrev_b32_e32 v142, 16, v142
	v_pk_mul_f32 v[136:137], v[136:137], s[96:97] op_sel_hi:[1,0]
	v_pk_fma_f32 v[24:25], v[24:25], 0.5, v[136:137] op_sel_hi:[1,0,1]
	v_pk_mul_f32 v[142:143], v[142:143], s[96:97] op_sel_hi:[1,0]
	v_pk_fma_f32 v[22:23], v[22:23], 0.5, v[142:143] op_sel_hi:[1,0,1]
	s_waitcnt lgkmcnt(1)
	v_lshlrev_b32_e32 v136, 16, v145
	v_and_b32_e32 v137, 0xffff0000, v145
	s_waitcnt lgkmcnt(0)
	v_and_b32_e32 v145, 0xffff0000, v144
	v_lshlrev_b32_e32 v144, 16, v144
	v_pk_mul_f32 v[136:137], v[136:137], s[96:97] op_sel_hi:[1,0]
	v_pk_fma_f32 v[20:21], v[20:21], 0.5, v[136:137] op_sel_hi:[1,0,1]
	v_pk_mul_f32 v[144:145], v[144:145], s[96:97] op_sel_hi:[1,0]
	v_pk_fma_f32 v[18:19], v[18:19], 0.5, v[144:145] op_sel_hi:[1,0,1]
	v_cvt_pk_bf16_f32 v22, v22, v23
	v_cvt_pk_bf16_f32 v23, v24, v25
	v_cvt_pk_bf16_f32 v24, v18, v19
	v_cvt_pk_bf16_f32 v21, v20, v21
	s_nop 1
	ds_bpermute_b32 v18, v132, v22
	ds_bpermute_b32 v19, v132, v23
	ds_bpermute_b32 v20, v132, v24
	ds_bpermute_b32 v21, v132, v21
	s_waitcnt lgkmcnt(0)
	global_store_dwordx4 v[134:135], v[18:21], off offset:256
	s_waitcnt vmcnt(12)
	ds_bpermute_b32 v143, v133, v111
	ds_bpermute_b32 v142, v133, v110
	ds_bpermute_b32 v145, v133, v113
	ds_bpermute_b32 v144, v133, v112
	s_mov_b64 s[12:13], 0x58000
	v_lshl_add_u64 v[134:135], v[140:141], 0, s[12:13]
	s_waitcnt lgkmcnt(3)
	v_lshlrev_b32_e32 v136, 16, v143
	v_and_b32_e32 v137, 0xffff0000, v143
	s_waitcnt lgkmcnt(2)
	v_and_b32_e32 v143, 0xffff0000, v142
	v_lshlrev_b32_e32 v142, 16, v142
	v_pk_mul_f32 v[136:137], v[136:137], s[96:97] op_sel_hi:[1,0]
	v_pk_fma_f32 v[16:17], v[16:17], 0.5, v[136:137] op_sel_hi:[1,0,1]
	v_pk_mul_f32 v[142:143], v[142:143], s[96:97] op_sel_hi:[1,0]
	v_pk_fma_f32 v[14:15], v[14:15], 0.5, v[142:143] op_sel_hi:[1,0,1]
	s_waitcnt lgkmcnt(1)
	v_lshlrev_b32_e32 v136, 16, v145
	v_and_b32_e32 v137, 0xffff0000, v145
	s_waitcnt lgkmcnt(0)
	v_and_b32_e32 v145, 0xffff0000, v144
	v_lshlrev_b32_e32 v144, 16, v144
	v_pk_mul_f32 v[136:137], v[136:137], s[96:97] op_sel_hi:[1,0]
	v_pk_fma_f32 v[12:13], v[12:13], 0.5, v[136:137] op_sel_hi:[1,0,1]
	v_pk_mul_f32 v[144:145], v[144:145], s[96:97] op_sel_hi:[1,0]
	v_pk_fma_f32 v[10:11], v[10:11], 0.5, v[144:145] op_sel_hi:[1,0,1]
	v_cvt_pk_bf16_f32 v14, v14, v15
	v_cvt_pk_bf16_f32 v15, v16, v17
	v_cvt_pk_bf16_f32 v16, v10, v11
	v_cvt_pk_bf16_f32 v13, v12, v13
	s_nop 1
	ds_bpermute_b32 v10, v132, v14
	ds_bpermute_b32 v11, v132, v15
	ds_bpermute_b32 v12, v132, v16
	ds_bpermute_b32 v13, v132, v13
	s_waitcnt lgkmcnt(0)
	global_store_dwordx4 v[134:135], v[10:13], off
	s_waitcnt vmcnt(11)
	ds_bpermute_b32 v143, v133, v103
	ds_bpermute_b32 v142, v133, v102
	ds_bpermute_b32 v145, v133, v105
	ds_bpermute_b32 v144, v133, v104
	s_waitcnt lgkmcnt(3)
	v_lshlrev_b32_e32 v136, 16, v143
	v_and_b32_e32 v137, 0xffff0000, v143
	s_waitcnt lgkmcnt(2)
	v_and_b32_e32 v143, 0xffff0000, v142
	v_lshlrev_b32_e32 v142, 16, v142
	v_pk_mul_f32 v[136:137], v[136:137], s[96:97] op_sel_hi:[1,0]
	v_pk_fma_f32 v[8:9], v[8:9], 0.5, v[136:137] op_sel_hi:[1,0,1]
	v_pk_mul_f32 v[142:143], v[142:143], s[96:97] op_sel_hi:[1,0]
	v_pk_fma_f32 v[6:7], v[6:7], 0.5, v[142:143] op_sel_hi:[1,0,1]
	s_waitcnt lgkmcnt(1)
	v_lshlrev_b32_e32 v136, 16, v145
	v_and_b32_e32 v137, 0xffff0000, v145
	s_waitcnt lgkmcnt(0)
	v_and_b32_e32 v145, 0xffff0000, v144
	v_lshlrev_b32_e32 v144, 16, v144
	v_pk_mul_f32 v[136:137], v[136:137], s[96:97] op_sel_hi:[1,0]
	v_pk_fma_f32 v[4:5], v[4:5], 0.5, v[136:137] op_sel_hi:[1,0,1]
	v_pk_mul_f32 v[144:145], v[144:145], s[96:97] op_sel_hi:[1,0]
	v_pk_fma_f32 v[2:3], v[2:3], 0.5, v[144:145] op_sel_hi:[1,0,1]
	v_cvt_pk_bf16_f32 v6, v6, v7
	v_cvt_pk_bf16_f32 v7, v8, v9
	v_cvt_pk_bf16_f32 v8, v2, v3
	v_cvt_pk_bf16_f32 v5, v4, v5
	s_nop 1
	ds_bpermute_b32 v2, v132, v6
	ds_bpermute_b32 v3, v132, v7
	ds_bpermute_b32 v4, v132, v8
	ds_bpermute_b32 v5, v132, v5
	s_waitcnt lgkmcnt(0)
	global_store_dwordx4 v[134:135], v[2:5], off offset:256
	s_mov_b64 s[12:13], -1
	s_cbranch_vccnz .LBB0_2018
	s_andn2_b64 vcc, exec, s[2:3]
	s_cbranch_vccnz .LBB0_2017
	s_barrier
	s_branch .LBB0_2017

; __global__ void __launch_bounds__(512, 2) mega_fwd(Args args) {
;     extern __shared__ __attribute__((aligned(16))) unsigned char lds[];
	.amdhsa_kernel _Z8mega_fwd4Args
		.amdhsa_group_segment_fixed_size 0
		.amdhsa_private_segment_fixed_size 0
		.amdhsa_kernarg_size 424
		.amdhsa_user_sgpr_count 2
		.amdhsa_user_sgpr_dispatch_ptr 0
		.amdhsa_user_sgpr_queue_ptr 0
		.amdhsa_user_sgpr_kernarg_segment_ptr 1
		.amdhsa_user_sgpr_dispatch_id 0
		.amdhsa_user_sgpr_kernarg_preload_length 0
		.amdhsa_user_sgpr_kernarg_preload_offset 0
		.amdhsa_user_sgpr_private_segment_size 0
		.amdhsa_uses_dynamic_stack 0
		.amdhsa_enable_private_segment 0
		.amdhsa_system_sgpr_workgroup_id_x 1
		.amdhsa_system_sgpr_workgroup_id_y 0
		.amdhsa_system_sgpr_workgroup_id_z 0
		.amdhsa_system_sgpr_workgroup_info 0
		.amdhsa_system_vgpr_workitem_id 0
		.amdhsa_next_free_vgpr 256
		.amdhsa_next_free_sgpr 102
		.amdhsa_accum_offset 256
		.amdhsa_reserve_vcc 1
		.amdhsa_float_round_mode_32 0
		.amdhsa_float_round_mode_16_64 0
		.amdhsa_float_denorm_mode_32 3
		.amdhsa_float_denorm_mode_16_64 3
		.amdhsa_dx10_clamp 1
		.amdhsa_ieee_mode 1
		.amdhsa_fp16_overflow 0
		.amdhsa_tg_split 0
		.amdhsa_exception_fp_ieee_invalid_op 0
		.amdhsa_exception_fp_denorm_src 0
		.amdhsa_exception_fp_ieee_div_zero 0
		.amdhsa_exception_fp_ieee_overflow 0
		.amdhsa_exception_fp_ieee_underflow 0
		.amdhsa_exception_fp_ieee_inexact 0
		.amdhsa_exception_int_div_zero 0
	.end_amdhsa_kernel

; __global__ void __launch_bounds__(512, 2) mega_fwd(Args args) {
;     extern __shared__ __attribute__((aligned(16))) unsigned char lds[];
amdhsa.kernels:
  - .agpr_count:     0
    .args:
      - .offset:         0
        .size:           168
        .value_kind:     by_value
      - .offset:         168
        .size:           4
        .value_kind:     hidden_block_count_x
      - .offset:         172
        .size:           4
        .value_kind:     hidden_block_count_y
      - .offset:         176
        .size:           4
        .value_kind:     hidden_block_count_z
      - .offset:         180
        .size:           2
        .value_kind:     hidden_group_size_x
      - .offset:         182
        .size:           2
        .value_kind:     hidden_group_size_y
      - .offset:         184
        .size:           2
        .value_kind:     hidden_group_size_z
      - .offset:         186
        .size:           2
        .value_kind:     hidden_remainder_x
      - .offset:         188
        .size:           2
        .value_kind:     hidden_remainder_y
      - .offset:         190
        .size:           2
        .value_kind:     hidden_remainder_z
      - .offset:         208
        .size:           8
        .value_kind:     hidden_global_offset_x
      - .offset:         216
        .size:           8
        .value_kind:     hidden_global_offset_y
      - .offset:         224
        .size:           8
        .value_kind:     hidden_global_offset_z
      - .offset:         232
        .size:           2
        .value_kind:     hidden_grid_dims
      - .offset:         288
        .size:           4
        .value_kind:     hidden_dynamic_lds_size
    .group_segment_fixed_size: 0
    .kernarg_segment_align: 8
    .kernarg_segment_size: 424
    .language:       OpenCL C
    .language_version:
      - 2
      - 0
    .max_flat_workgroup_size: 512
    .name:           _Z8mega_fwd4Args
    .private_segment_fixed_size: 0
    .sgpr_count:     108
    .sgpr_spill_count: 160
    .symbol:         _Z8mega_fwd4Args.kd
    .uniform_work_group_size: 1
    .uses_dynamic_stack: false
    .vgpr_count:     256
    .vgpr_spill_count: 0
    .wavefront_size: 64
